# baseline (speedup 1.0000x reference)
; #define PG8_STAGE(bufoff, gbase, voff) do { _Pragma("unroll") for (int _i = 0; _i < 2; ++_i) \
;         __builtin_amdgcn_global_load_lds((const unsigned*)((const char*)(gbase) + (voff)[_i]), (LAS unsigned*)(lds + (bufoff) + ldsw + _i * 8192), 16, 0, 0); } while (0)
; #define PG8_LDA(dst, b, h) do { _Pragma("unroll") for (int m = 0; m < 4; ++m) _Pragma("unroll") for (int k = 0; k < 2; ++k) dst[m][k] = *(const LAS bf16x8*)(lds + PG8_SA(b, h) + aoff + m * 2048 + k * 1024); } while (0)
; #define PG8_LDB(dst, b, h) do { _Pragma("unroll") for (int n = 0; n < 2; ++n) _Pragma("unroll") for (int k = 0; k < 2; ++k) dst[n][k] = *(const LAS bf16x8*)(lds + PG8_SB(b, h) + boff + n * 2048 + k * 1024); } while (0)
; #define PG8_MMA(ai, bj, At, Bt) do { __builtin_amdgcn_s_setprio(1); _Pragma("unroll") for (int m = 0; m < 4; ++m) _Pragma("unroll") for (int n = 0; n < 2; ++n) _Pragma("unroll") for (int k = 0; k < 2; ++k) \
;         acc[ai][bj][m][n] = __builtin_amdgcn_mfma_f32_16x16x32_bf16(Bt[n][k], At[m][k], acc[ai][bj][m][n], 0, 0, 0); __builtin_amdgcn_s_setprio(0); } while (0)
; #define PG8_WAIT_V(n) asm volatile("s_waitcnt vmcnt(" #n ")" ::: "memory")
; #define PG8_WAIT_L(n) asm volatile("s_waitcnt lgkmcnt(" #n ")" ::: "memory")
; #define PG8_BAR __builtin_amdgcn_s_barrier()
; template <class Epi>
; DEV void gemm_phase(LAS unsigned char* lds, const Gemm g, const StaticOrder& S, const Epi& E) {
;     ...
;         for (int t = 0; t < nt; t += 2) {
;             const bool last = (t == nt - 2);
;             const char* a1 = cA + (size_t)(t + 1) * kstep;
;             const char* a2 = last ? nA : cA + (size_t)(t + 2) * kstep; const char* b2 = last ? nB : cB + (size_t)(t + 2) * kstep;
;             const char* a3 = a2 + kstep; const char* b3 = b2 + kstep;
;             PG8_LDB(B0, 0, 0); PG8_SCHED; PG8_LDA(At, 0, 0); PG8_STAGE(PG8_SA(1, 1), a1 + hstep, voffA);
;             PG8_WAIT_L(8); PG8_BAR; PG8_WAIT_L(0); PG8_MMA(0, 0, At, B0); PG8_BAR; PG8_SCHED;
;             PG8_LDB(B1, 0, 1); PG8_STAGE(PG8_SB(0, 0), b2, voffB);
;             PG8_BAR; PG8_WAIT_L(0); PG8_MMA(0, 1, At, B1); PG8_BAR;
;             PG8_LDA(At, 0, 1); PG8_STAGE(PG8_SA(0, 0), a2, voffA);
;             PG8_BAR; PG8_WAIT_L(0); PG8_MMA(1, 0, At, B0); PG8_BAR; PG8_SCHED;
;             PG8_STAGE(PG8_SB(0, 1), b2 + hstep, voffB);
;             PG8_WAIT_V(6); PG8_BAR; PG8_MMA(1, 1, At, B1); PG8_BAR;
.LBB0_61:
	s_add_u32 s28, s26, 0xfff80080
	s_addc_u32 s29, s27, -1
	s_add_i32 s49, 0, 0x10000
	v_add_u32_e32 v140, s49, v178
	ds_read_b128 v[128:131], v140
	ds_read_b128 v[132:135], v140 offset:1024
	ds_read_b128 v[136:139], v140 offset:2048
	ds_read_b128 v[140:143], v140 offset:3072
	s_cmp_eq_u32 s48, 28
	s_cselect_b32 s31, s15, s29
	s_cselect_b32 s30, s19, s28
	s_cselect_b32 s29, s17, s47
	s_cselect_b32 s28, s25, s46
	s_add_i32 m0, s37, 0xc000
	ds_read_b128 v[154:157], v181
	ds_read_b128 v[174:177], v181 offset:1024
	ds_read_b128 v[182:185], v181 offset:2048
	ds_read_b128 v[186:189], v181 offset:3072
	ds_read_b128 v[190:193], v181 offset:4096
	ds_read_b128 v[194:197], v181 offset:5120
	ds_read_b128 v[214:217], v181 offset:6144
	ds_read_b128 v[218:221], v181 offset:7168
	global_load_lds_dwordx4 v150, s[26:27]
	s_add_i32 m0, s37, 0xe000
	s_nop 0
	global_load_lds_dwordx4 v152, s[26:27]
	s_waitcnt lgkmcnt(8)
	s_barrier
	s_waitcnt lgkmcnt(0)
	v_mfma_f32_16x16x32_bf16 v[124:127], v[128:131], v[154:157], v[124:127]
	v_mfma_f32_16x16x32_bf16 v[120:123], v[136:139], v[154:157], v[120:123]
	v_mfma_f32_16x16x32_bf16 v[108:111], v[128:131], v[182:185], v[108:111]
	v_mfma_f32_16x16x32_bf16 v[104:107], v[136:139], v[182:185], v[104:107]
	v_mfma_f32_16x16x32_bf16 v[92:95], v[128:131], v[190:193], v[92:95]
	v_mfma_f32_16x16x32_bf16 v[88:91], v[136:139], v[190:193], v[88:91]
	v_mfma_f32_16x16x32_bf16 v[76:79], v[128:131], v[214:217], v[76:79]
	v_mfma_f32_16x16x32_bf16 v[72:75], v[136:139], v[214:217], v[72:75]
	v_mfma_f32_16x16x32_bf16 v[124:127], v[132:135], v[174:177], v[124:127]
	v_mfma_f32_16x16x32_bf16 v[120:123], v[140:143], v[174:177], v[120:123]
	v_mfma_f32_16x16x32_bf16 v[108:111], v[132:135], v[186:189], v[108:111]
	v_mfma_f32_16x16x32_bf16 v[104:107], v[140:143], v[186:189], v[104:107]
	v_mfma_f32_16x16x32_bf16 v[92:95], v[132:135], v[194:197], v[92:95]
	v_mfma_f32_16x16x32_bf16 v[88:91], v[140:143], v[194:197], v[88:91]
	v_mfma_f32_16x16x32_bf16 v[76:79], v[132:135], v[218:221], v[76:79]
	v_mfma_f32_16x16x32_bf16 v[72:75], v[140:143], v[218:221], v[72:75]
	s_barrier
	s_add_i32 s52, 0, 0x14000
	v_add_u32_e32 v158, s52, v178
	s_add_i32 s49, s49, s36
	ds_read_b128 v[222:225], v158
	ds_read_b128 v[226:229], v158 offset:1024
	ds_read_b128 v[230:233], v158 offset:2048
	ds_read_b128 v[234:237], v158 offset:3072
	s_mov_b32 m0, s49
	s_nop 0
	global_load_lds_dwordx4 v160, s[28:29]
	s_add_i32 m0, s49, 0x2000
	s_nop 0
	global_load_lds_dwordx4 v148, s[28:29]
	s_barrier
	s_waitcnt lgkmcnt(0)
	v_mfma_f32_16x16x32_bf16 v[116:119], v[222:225], v[154:157], v[116:119]
	v_mfma_f32_16x16x32_bf16 v[112:115], v[230:233], v[154:157], v[112:115]
	v_mfma_f32_16x16x32_bf16 v[100:103], v[222:225], v[182:185], v[100:103]
	v_mfma_f32_16x16x32_bf16 v[96:99], v[230:233], v[182:185], v[96:99]
	v_mfma_f32_16x16x32_bf16 v[84:87], v[222:225], v[190:193], v[84:87]
	v_mfma_f32_16x16x32_bf16 v[80:83], v[230:233], v[190:193], v[80:83]
	v_mfma_f32_16x16x32_bf16 v[68:71], v[222:225], v[214:217], v[68:71]
	v_mfma_f32_16x16x32_bf16 v[64:67], v[230:233], v[214:217], v[64:67]
	v_mfma_f32_16x16x32_bf16 v[116:119], v[226:229], v[174:177], v[116:119]
	v_mfma_f32_16x16x32_bf16 v[112:115], v[234:237], v[174:177], v[112:115]
	v_mfma_f32_16x16x32_bf16 v[100:103], v[226:229], v[186:189], v[100:103]
	v_mfma_f32_16x16x32_bf16 v[96:99], v[234:237], v[186:189], v[96:99]
	v_mfma_f32_16x16x32_bf16 v[84:87], v[226:229], v[194:197], v[84:87]
	v_mfma_f32_16x16x32_bf16 v[80:83], v[234:237], v[194:197], v[80:83]
	v_mfma_f32_16x16x32_bf16 v[68:71], v[226:229], v[218:221], v[68:71]
	v_mfma_f32_16x16x32_bf16 v[64:67], v[234:237], v[218:221], v[64:67]
	s_mov_b32 m0, s37
	v_lshl_add_u64 v[240:241], s[30:31], 0, v[144:145]
	s_barrier
	ds_read_b128 v[154:157], v181 offset:16384
	ds_read_b128 v[174:177], v181 offset:17408
	ds_read_b128 v[182:185], v181 offset:18432
	ds_read_b128 v[186:189], v181 offset:19456
	ds_read_b128 v[190:193], v181 offset:20480
	ds_read_b128 v[194:197], v181 offset:21504
	ds_read_b128 v[214:217], v181 offset:22528
	ds_read_b128 v[218:221], v181 offset:23552
	global_load_lds_dwordx4 v144, s[30:31]
	v_lshl_add_u64 v[242:243], s[30:31], 0, v[146:147]
	s_mov_b32 m0, s38
	s_nop 0
	global_load_lds_dwordx4 v146, s[30:31]
	s_barrier
	s_waitcnt lgkmcnt(0)
	v_mfma_f32_16x16x32_bf16 v[60:63], v[128:131], v[154:157], v[60:63]
	v_mfma_f32_16x16x32_bf16 v[56:59], v[136:139], v[154:157], v[56:59]
	v_mfma_f32_16x16x32_bf16 v[44:47], v[128:131], v[182:185], v[44:47]
	v_mfma_f32_16x16x32_bf16 v[40:43], v[136:139], v[182:185], v[40:43]
	v_mfma_f32_16x16x32_bf16 v[28:31], v[128:131], v[190:193], v[28:31]
	v_mfma_f32_16x16x32_bf16 v[24:27], v[136:139], v[190:193], v[24:27]
	v_mfma_f32_16x16x32_bf16 v[12:15], v[128:131], v[214:217], v[12:15]
	v_mfma_f32_16x16x32_bf16 v[8:11], v[136:139], v[214:217], v[8:11]
	v_mfma_f32_16x16x32_bf16 v[60:63], v[132:135], v[174:177], v[60:63]
	v_mfma_f32_16x16x32_bf16 v[56:59], v[140:143], v[174:177], v[56:59]
	v_mfma_f32_16x16x32_bf16 v[44:47], v[132:135], v[186:189], v[44:47]
	v_mfma_f32_16x16x32_bf16 v[40:43], v[140:143], v[186:189], v[40:43]
	v_mfma_f32_16x16x32_bf16 v[28:31], v[132:135], v[194:197], v[28:31]
	v_mfma_f32_16x16x32_bf16 v[24:27], v[140:143], v[194:197], v[24:27]
	v_mfma_f32_16x16x32_bf16 v[12:15], v[132:135], v[218:221], v[12:15]
	v_mfma_f32_16x16x32_bf16 v[8:11], v[140:143], v[218:221], v[8:11]
	s_barrier
	s_add_u32 s50, s28, 0x80000
	s_addc_u32 s51, s29, 0
	s_add_i32 s49, s52, s36
	s_mov_b32 m0, s49
	s_nop 0
	global_load_lds_dwordx4 v160, s[50:51]
	s_add_i32 m0, s49, 0x2000
	s_nop 0
	global_load_lds_dwordx4 v148, s[50:51]
	s_waitcnt vmcnt(6)
	s_barrier
; #define PG8_STAGE(bufoff, gbase, voff) do { _Pragma("unroll") for (int _i = 0; _i < 2; ++_i) \
;         __builtin_amdgcn_global_load_lds((const unsigned*)((const char*)(gbase) + (voff)[_i]), (LAS unsigned*)(lds + (bufoff) + ldsw + _i * 8192), 16, 0, 0); } while (0)
; #define PG8_LDA(dst, b, h) do { _Pragma("unroll") for (int m = 0; m < 4; ++m) _Pragma("unroll") for (int k = 0; k < 2; ++k) dst[m][k] = *(const LAS bf16x8*)(lds + PG8_SA(b, h) + aoff + m * 2048 + k * 1024); } while (0)
; #define PG8_LDB(dst, b, h) do { _Pragma("unroll") for (int n = 0; n < 2; ++n) _Pragma("unroll") for (int k = 0; k < 2; ++k) dst[n][k] = *(const LAS bf16x8*)(lds + PG8_SB(b, h) + boff + n * 2048 + k * 1024); } while (0)
; #define PG8_MMA(ai, bj, At, Bt) do { __builtin_amdgcn_s_setprio(1); _Pragma("unroll") for (int m = 0; m < 4; ++m) _Pragma("unroll") for (int n = 0; n < 2; ++n) _Pragma("unroll") for (int k = 0; k < 2; ++k) \
;         acc[ai][bj][m][n] = __builtin_amdgcn_mfma_f32_16x16x32_bf16(Bt[n][k], At[m][k], acc[ai][bj][m][n], 0, 0, 0); __builtin_amdgcn_s_setprio(0); } while (0)
; #define PG8_WAIT_V(n) asm volatile("s_waitcnt vmcnt(" #n ")" ::: "memory")
; #define PG8_WAIT_L(n) asm volatile("s_waitcnt lgkmcnt(" #n ")" ::: "memory")
; #define PG8_BAR __builtin_amdgcn_s_barrier()
; #define PG8_SCHED __builtin_amdgcn_sched_barrier(0)
; template <class Epi>
; DEV void gemm_phase(LAS unsigned char* lds, const Gemm g, const StaticOrder& S, const Epi& E) {
;     ...
;             PG8_WAIT_V(6); PG8_BAR; PG8_MMA(1, 1, At, B1); PG8_BAR;
;             PG8_LDB(B0, 1, 0); PG8_SCHED; PG8_LDA(At, 1, 0); PG8_STAGE(PG8_SA(0, 1), a2 + hstep, voffA);
;             PG8_WAIT_L(8); PG8_BAR; PG8_WAIT_L(0); PG8_MMA(0, 0, At, B0); PG8_BAR; PG8_SCHED;
;             PG8_LDB(B1, 1, 1); PG8_STAGE(PG8_SB(1, 0), b3, voffB);
;             PG8_BAR; PG8_WAIT_L(0); PG8_MMA(0, 1, At, B1); PG8_BAR;
;             PG8_LDA(At, 1, 1); PG8_STAGE(PG8_SA(1, 0), a3, voffA);
;             PG8_BAR; PG8_WAIT_L(0); PG8_MMA(1, 0, At, B0); PG8_BAR; PG8_SCHED;
;             PG8_STAGE(PG8_SB(1, 1), b3 + hstep, voffB);
	v_mfma_f32_16x16x32_bf16 v[52:55], v[222:225], v[154:157], v[52:55]
	v_mfma_f32_16x16x32_bf16 v[48:51], v[230:233], v[154:157], v[48:51]
	v_mfma_f32_16x16x32_bf16 v[36:39], v[222:225], v[182:185], v[36:39]
	v_mfma_f32_16x16x32_bf16 v[32:35], v[230:233], v[182:185], v[32:35]
	v_mfma_f32_16x16x32_bf16 v[20:23], v[222:225], v[190:193], v[20:23]
	v_mfma_f32_16x16x32_bf16 v[16:19], v[230:233], v[190:193], v[16:19]
	v_mfma_f32_16x16x32_bf16 v[4:7], v[222:225], v[214:217], v[4:7]
	v_mfma_f32_16x16x32_bf16 v[0:3], v[230:233], v[214:217], v[0:3]
	v_mfma_f32_16x16x32_bf16 v[52:55], v[226:229], v[174:177], v[52:55]
	v_mfma_f32_16x16x32_bf16 v[48:51], v[234:237], v[174:177], v[48:51]
	v_mfma_f32_16x16x32_bf16 v[36:39], v[226:229], v[186:189], v[36:39]
	v_mfma_f32_16x16x32_bf16 v[32:35], v[234:237], v[186:189], v[32:35]
	v_mfma_f32_16x16x32_bf16 v[20:23], v[226:229], v[194:197], v[20:23]
	v_mfma_f32_16x16x32_bf16 v[16:19], v[234:237], v[194:197], v[16:19]
	v_mfma_f32_16x16x32_bf16 v[4:7], v[226:229], v[218:221], v[4:7]
	v_mfma_f32_16x16x32_bf16 v[0:3], v[234:237], v[218:221], v[0:3]
	s_add_i32 s49, 0, 0x18000
	v_add_u32_e32 v140, s49, v178
	s_barrier
	ds_read_b128 v[128:131], v140
	ds_read_b128 v[132:135], v140 offset:1024
	ds_read_b128 v[136:139], v140 offset:2048
	ds_read_b128 v[140:143], v140 offset:3072
	s_add_u32 s30, s30, 0x80000
	s_addc_u32 s31, s31, 0
	s_mov_b32 m0, s39
	ds_read_b128 v[154:157], v181 offset:32768
	ds_read_b128 v[174:177], v181 offset:33792
	ds_read_b128 v[182:185], v181 offset:34816
	ds_read_b128 v[186:189], v181 offset:35840
	ds_read_b128 v[190:193], v181 offset:36864
	ds_read_b128 v[194:197], v181 offset:37888
	ds_read_b128 v[214:217], v181 offset:38912
	ds_read_b128 v[218:221], v181 offset:39936
	global_load_lds_dwordx4 v144, s[30:31]
	s_mov_b32 m0, s40
	s_nop 0
	global_load_lds_dwordx4 v146, s[30:31]
	s_waitcnt lgkmcnt(8)
	s_barrier
	s_waitcnt lgkmcnt(0)
	v_mfma_f32_16x16x32_bf16 v[124:127], v[128:131], v[154:157], v[124:127]
	v_mfma_f32_16x16x32_bf16 v[120:123], v[136:139], v[154:157], v[120:123]
	v_mfma_f32_16x16x32_bf16 v[108:111], v[128:131], v[182:185], v[108:111]
	v_mfma_f32_16x16x32_bf16 v[104:107], v[136:139], v[182:185], v[104:107]
	v_mfma_f32_16x16x32_bf16 v[92:95], v[128:131], v[190:193], v[92:95]
	v_mfma_f32_16x16x32_bf16 v[88:91], v[136:139], v[190:193], v[88:91]
	v_mfma_f32_16x16x32_bf16 v[76:79], v[128:131], v[214:217], v[76:79]
	v_mfma_f32_16x16x32_bf16 v[72:75], v[136:139], v[214:217], v[72:75]
	v_mfma_f32_16x16x32_bf16 v[124:127], v[132:135], v[174:177], v[124:127]
	v_mfma_f32_16x16x32_bf16 v[120:123], v[140:143], v[174:177], v[120:123]
	v_mfma_f32_16x16x32_bf16 v[108:111], v[132:135], v[186:189], v[108:111]
	v_mfma_f32_16x16x32_bf16 v[104:107], v[140:143], v[186:189], v[104:107]
	v_mfma_f32_16x16x32_bf16 v[92:95], v[132:135], v[194:197], v[92:95]
	v_mfma_f32_16x16x32_bf16 v[88:91], v[140:143], v[194:197], v[88:91]
	v_mfma_f32_16x16x32_bf16 v[76:79], v[132:135], v[218:221], v[76:79]
	v_mfma_f32_16x16x32_bf16 v[72:75], v[140:143], v[218:221], v[72:75]
	s_barrier
	s_add_i32 s30, 0, 0x1c000
	s_add_i32 s31, s49, s36
	v_add_u32_e32 v234, s30, v178
	s_add_u32 s100, s28, 0x80
	s_addc_u32 s101, s29, 0
	s_mov_b32 m0, s31
	ds_read_b128 v[222:225], v234
	ds_read_b128 v[226:229], v234 offset:1024
	ds_read_b128 v[230:233], v234 offset:2048
	ds_read_b128 v[234:237], v234 offset:3072
	global_load_lds_dwordx4 v160, s[100:101]
	s_add_i32 m0, s31, 0x2000
	s_nop 0
	global_load_lds_dwordx4 v148, s[100:101]
	s_barrier
	s_waitcnt lgkmcnt(0)
	v_mfma_f32_16x16x32_bf16 v[116:119], v[222:225], v[154:157], v[116:119]
	v_mfma_f32_16x16x32_bf16 v[112:115], v[230:233], v[154:157], v[112:115]
	v_mfma_f32_16x16x32_bf16 v[100:103], v[222:225], v[182:185], v[100:103]
	v_mfma_f32_16x16x32_bf16 v[96:99], v[230:233], v[182:185], v[96:99]
	v_mfma_f32_16x16x32_bf16 v[84:87], v[222:225], v[190:193], v[84:87]
	v_mfma_f32_16x16x32_bf16 v[80:83], v[230:233], v[190:193], v[80:83]
	v_mfma_f32_16x16x32_bf16 v[68:71], v[222:225], v[214:217], v[68:71]
	v_mfma_f32_16x16x32_bf16 v[64:67], v[230:233], v[214:217], v[64:67]
	v_mfma_f32_16x16x32_bf16 v[116:119], v[226:229], v[174:177], v[116:119]
	v_mfma_f32_16x16x32_bf16 v[112:115], v[234:237], v[174:177], v[112:115]
	v_mfma_f32_16x16x32_bf16 v[100:103], v[226:229], v[186:189], v[100:103]
	v_mfma_f32_16x16x32_bf16 v[96:99], v[234:237], v[186:189], v[96:99]
	v_mfma_f32_16x16x32_bf16 v[84:87], v[226:229], v[194:197], v[84:87]
	v_mfma_f32_16x16x32_bf16 v[80:83], v[234:237], v[194:197], v[80:83]
	v_mfma_f32_16x16x32_bf16 v[68:71], v[226:229], v[218:221], v[68:71]
	v_mfma_f32_16x16x32_bf16 v[64:67], v[234:237], v[218:221], v[64:67]
	s_mov_b32 m0, s41
	v_lshl_add_u64 v[158:159], v[240:241], 0, s[2:3]
	s_barrier
	ds_read_b128 v[154:157], v181 offset:49152
	ds_read_b128 v[174:177], v181 offset:50176
	ds_read_b128 v[182:185], v181 offset:51200
	ds_read_b128 v[186:189], v181 offset:52224
	ds_read_b128 v[190:193], v181 offset:53248
	ds_read_b128 v[194:197], v181 offset:54272
	ds_read_b128 v[214:217], v181 offset:55296
	ds_read_b128 v[218:221], v181 offset:56320
	global_load_lds_dwordx4 v[158:159], off
	v_lshl_add_u64 v[158:159], v[242:243], 0, s[2:3]
	s_mov_b32 m0, s42
	s_nop 0
	global_load_lds_dwordx4 v[158:159], off
	s_barrier
; DEV bf16x8 pack8(f32x4 a, f32x4 b) { u32x4 w; w.x = cvt_pk_bf16(a[0], a[1]); w.y = cvt_pk_bf16(a[2], a[3]); w.z = cvt_pk_bf16(b[0], b[1]); w.w = cvt_pk_bf16(b[2], b[3]); return __builtin_bit_cast(bf16x8, w); }
; #define PG8_STAGE(bufoff, gbase, voff) do { _Pragma("unroll") for (int _i = 0; _i < 2; ++_i) \
;         __builtin_amdgcn_global_load_lds((const unsigned*)((const char*)(gbase) + (voff)[_i]), (LAS unsigned*)(lds + (bufoff) + ldsw + _i * 8192), 16, 0, 0); } while (0)
; #define PG8_BAR __builtin_amdgcn_s_barrier()
; template <class Epi>
; DEV void gemm_phase(LAS unsigned char* lds, const Gemm g, const StaticOrder& S, const Epi& E) {
;     ...
;             PG8_STAGE(PG8_SB(1, 1), b3 + hstep, voffB);
;             PG8_WAIT_V(6); PG8_BAR; PG8_MMA(1, 1, At, B1); PG8_BAR;
;         }
;     DEV void operator()(AccRef acc, const pg8::Unit& u, int wr, int wc, int fr, int fq) const {
;         const int row0 = u.pm * 256 + wr * 64 + fr, col0 = u.pn * 256 + wc * 32 + 8 * fq;
; #pragma unroll
;         for (int am = 0; am < 4; ++am) { const int ai = am >> 1, m0 = (am & 1) * 2;
;             f32x4 bv[4][2][2];
; #pragma unroll
;             for (int m = m0; m < m0 + 2; ++m)
; #pragma unroll
;                 for (int bj = 0; bj < 2; ++bj)
; #pragma unroll
;                     for (int n = 0; n < 2; ++n) bv[m][bj][n] = *(const f32x4*)(base + (size_t)(row0 + ai * 128 + m * 16) * 2048 + col0 + bj * 128 + n * 4);
; #pragma unroll
;             for (int m = m0; m < m0 + 2; ++m) { const size_t off = (size_t)(row0 + ai * 128 + m * 16) * 2048 + col0; float sq = 0.f;
; #pragma unroll
;                 for (int bj = 0; bj < 2; ++bj) { const f32x4 o0 = bv[m][bj][0] + scale * acc[ai][bj][m][0], o1 = bv[m][bj][1] + scale * acc[ai][bj][m][1];
;                     *(f32x4*)(out + off + bj * 128) = o0; *(f32x4*)(out + off + bj * 128 + 4) = o1;
;                     if (xb) { *(u32x4*)(xb + off + bj * 128) = __builtin_bit_cast(u32x4, pack8(o0, o1));
;                         sq += (o0[0] * o0[0] + o0[1] * o0[1] + o0[2] * o0[2] + o0[3] * o0[3]) + (o1[0] * o1[0] + o1[1] * o1[1] + o1[2] * o1[2] + o1[3] * o1[3]); } }
;                 if (ssout) { sq += __shfl_xor(sq, 16); sq += __shfl_xor(sq, 32);
;                     if (fq == 0) { if (red) red[(ai * 128 + wr * 64 + m * 16 + fr) * 4 + wc] = sq; else atomicAdd(ssout + (size_t)(row0 + ai * 128 + m * 16) * 8 + u.pn, sq); } } }
	s_waitcnt lgkmcnt(0)
	v_mfma_f32_16x16x32_bf16 v[60:63], v[128:131], v[154:157], v[60:63]
	v_mfma_f32_16x16x32_bf16 v[56:59], v[136:139], v[154:157], v[56:59]
	v_mfma_f32_16x16x32_bf16 v[44:47], v[128:131], v[182:185], v[44:47]
	v_mfma_f32_16x16x32_bf16 v[40:43], v[136:139], v[182:185], v[40:43]
	v_mfma_f32_16x16x32_bf16 v[28:31], v[128:131], v[190:193], v[28:31]
	v_mfma_f32_16x16x32_bf16 v[24:27], v[136:139], v[190:193], v[24:27]
	v_mfma_f32_16x16x32_bf16 v[12:15], v[128:131], v[214:217], v[12:15]
	v_mfma_f32_16x16x32_bf16 v[8:11], v[136:139], v[214:217], v[8:11]
	v_mfma_f32_16x16x32_bf16 v[60:63], v[132:135], v[174:177], v[60:63]
	v_mfma_f32_16x16x32_bf16 v[56:59], v[140:143], v[174:177], v[56:59]
	v_mfma_f32_16x16x32_bf16 v[44:47], v[132:135], v[186:189], v[44:47]
	v_mfma_f32_16x16x32_bf16 v[40:43], v[140:143], v[186:189], v[40:43]
	v_mfma_f32_16x16x32_bf16 v[28:31], v[132:135], v[194:197], v[28:31]
	v_mfma_f32_16x16x32_bf16 v[24:27], v[140:143], v[194:197], v[24:27]
	v_mfma_f32_16x16x32_bf16 v[12:15], v[132:135], v[218:221], v[12:15]
	v_mfma_f32_16x16x32_bf16 v[8:11], v[140:143], v[218:221], v[8:11]
	s_barrier
	s_add_u32 s28, s28, 0x80080
	s_addc_u32 s29, s29, 0
	s_add_i32 s30, s30, s36
	s_mov_b32 m0, s30
	s_nop 0
	global_load_lds_dwordx4 v160, s[28:29]
	s_add_i32 m0, s30, 0x2000
	s_nop 0
	global_load_lds_dwordx4 v148, s[28:29]
	s_waitcnt vmcnt(6)
	s_barrier
	v_mfma_f32_16x16x32_bf16 v[52:55], v[222:225], v[154:157], v[52:55]
	v_mfma_f32_16x16x32_bf16 v[48:51], v[230:233], v[154:157], v[48:51]
	v_mfma_f32_16x16x32_bf16 v[36:39], v[222:225], v[182:185], v[36:39]
	v_mfma_f32_16x16x32_bf16 v[32:35], v[230:233], v[182:185], v[32:35]
	v_mfma_f32_16x16x32_bf16 v[20:23], v[222:225], v[190:193], v[20:23]
	v_mfma_f32_16x16x32_bf16 v[16:19], v[230:233], v[190:193], v[16:19]
	v_mfma_f32_16x16x32_bf16 v[4:7], v[222:225], v[214:217], v[4:7]
	v_mfma_f32_16x16x32_bf16 v[0:3], v[230:233], v[214:217], v[0:3]
	v_mfma_f32_16x16x32_bf16 v[52:55], v[226:229], v[174:177], v[52:55]
	v_mfma_f32_16x16x32_bf16 v[48:51], v[234:237], v[174:177], v[48:51]
	v_mfma_f32_16x16x32_bf16 v[36:39], v[226:229], v[186:189], v[36:39]
	v_mfma_f32_16x16x32_bf16 v[32:35], v[234:237], v[186:189], v[32:35]
	v_mfma_f32_16x16x32_bf16 v[20:23], v[226:229], v[194:197], v[20:23]
	v_mfma_f32_16x16x32_bf16 v[16:19], v[234:237], v[194:197], v[16:19]
	v_mfma_f32_16x16x32_bf16 v[4:7], v[226:229], v[218:221], v[4:7]
	v_mfma_f32_16x16x32_bf16 v[0:3], v[234:237], v[218:221], v[0:3]
	s_add_i32 s48, s48, 2
	s_add_u32 s26, s26, 0x100
	s_addc_u32 s27, s27, 0
	s_add_u32 s46, s46, 0x100
	s_addc_u32 s47, s47, 0
	s_cmp_gt_u32 s48, 29
	s_barrier
	s_cbranch_scc0 .LBB0_61
	v_lshl_add_u32 v156, s24, 8, v167
	v_lshl_or_b32 v154, s14, 8, v179
	v_readlane_b32 s24, v254, 16
	v_ashrrev_i32_e32 v155, 31, v154
	v_readlane_b32 s25, v254, 17
	v_ashrrev_i32_e32 v157, 31, v156
	v_lshlrev_b64 v[128:129], 13, v[156:157]
	v_lshl_add_u64 v[158:159], v[154:155], 2, s[24:25]
	v_lshl_add_u64 v[214:215], v[158:159], 0, v[128:129]
	global_load_dwordx4 v[182:185], v[214:215], off offset:16
	global_load_dwordx4 v[186:189], v[214:215], off
	global_load_dwordx4 v[190:193], v[214:215], off offset:528
	global_load_dwordx4 v[194:197], v[214:215], off offset:512
	v_or_b32_e32 v174, 16, v156
	v_ashrrev_i32_e32 v175, 31, v174
	v_lshlrev_b64 v[128:129], 13, v[174:175]
	v_lshl_add_u64 v[176:177], v[158:159], 0, v[128:129]
	global_load_dwordx4 v[136:139], v[176:177], off offset:16
	global_load_dwordx4 v[140:143], v[176:177], off
	global_load_dwordx4 v[128:131], v[176:177], off offset:528
	global_load_dwordx4 v[132:135], v[176:177], off offset:512
	v_lshlrev_b64 v[216:217], 11, v[156:157]
	v_readlane_b32 s24, v250, 9
	v_lshl_add_u64 v[216:217], v[216:217], 0, v[154:155]
	v_readlane_b32 s25, v250, 10
	v_cmp_lt_i32_e32 vcc, v208, v206
	s_ashr_i32 s15, s14, 31
	s_waitcnt vmcnt(0)
	v_pk_add_f32 v[120:121], v[120:121], v[182:183]
	v_pk_add_f32 v[126:127], v[126:127], v[188:189]
	v_pk_add_f32 v[124:125], v[124:125], v[186:187]
	v_pk_add_f32 v[122:123], v[122:123], v[184:185]
	global_store_dwordx4 v[214:215], v[124:127], off
	global_store_dwordx4 v[214:215], v[120:123], off offset:16
	v_cvt_pk_bf16_f32 v184, v120, v121
	v_cvt_pk_bf16_f32 v182, v124, v125
	v_mul_f32_e32 v121, v121, v121
	v_cvt_pk_bf16_f32 v183, v126, v127
	v_cvt_pk_bf16_f32 v185, v122, v123
	v_lshl_add_u64 v[186:187], v[216:217], 1, s[24:25]
	v_fmac_f32_e32 v121, v120, v120
	v_pk_add_f32 v[118:119], v[118:119], v[196:197]
	v_pk_add_f32 v[116:117], v[116:117], v[194:195]
	v_pk_add_f32 v[112:113], v[112:113], v[190:191]
	global_store_dwordx4 v[186:187], v[182:185], off
	v_mul_f32_e32 v125, v125, v125
	v_fmac_f32_e32 v121, v122, v122
	v_pk_add_f32 v[114:115], v[114:115], v[192:193]
	global_store_dwordx4 v[214:215], v[116:119], off offset:512
	global_store_dwordx4 v[214:215], v[112:115], off offset:528
	v_cvt_pk_bf16_f32 v120, v116, v117
	v_cvt_pk_bf16_f32 v122, v112, v113
	v_mul_f32_e32 v117, v117, v117
	v_mul_f32_e32 v113, v113, v113
	v_fmac_f32_e32 v125, v124, v124
	v_fmac_f32_e32 v117, v116, v116
	v_fmac_f32_e32 v113, v112, v112
	v_fmac_f32_e32 v125, v126, v126
	v_fmac_f32_e32 v117, v118, v118
	v_fmac_f32_e32 v113, v114, v114
	v_fmac_f32_e32 v125, v127, v127
	v_fmac_f32_e32 v121, v123, v123
	v_fmac_f32_e32 v117, v119, v119
	v_fmac_f32_e32 v113, v115, v115
	v_add_f32_e32 v124, v125, v121
	v_add_f32_e32 v112, v117, v113
	v_cndmask_b32_e32 v113, v204, v208, vcc
	v_cvt_pk_bf16_f32 v121, v118, v119
	v_add_f32_e32 v112, v124, v112
	v_lshlrev_b32_e32 v118, 2, v113
	ds_bpermute_b32 v113, v118, v112
	v_cmp_lt_i32_e32 vcc, v207, v206
	v_cvt_pk_bf16_f32 v123, v114, v115
	global_store_dwordx4 v[186:187], v[120:123], off offset:256
	s_waitcnt lgkmcnt(0)
	v_add_f32_e32 v112, v112, v113
	v_cndmask_b32_e32 v113, v204, v207, vcc
	v_lshlrev_b32_e32 v119, 2, v113
	ds_bpermute_b32 v113, v119, v112
	s_and_saveexec_b64 s[24:25], s[6:7]
	s_cbranch_execz .LBB0_67
	s_waitcnt lgkmcnt(0)
	v_add_f32_e32 v112, v112, v113
	s_mov_b64 s[26:27], -1
	s_and_b64 vcc, exec, s[12:13]
	s_cbranch_vccz .LBB0_65
	v_readlane_b32 s26, v250, 37
	v_lshlrev_b64 v[114:115], 5, v[156:157]
	v_readlane_b32 s27, v250, 38
	s_nop 1
	v_lshl_add_u64 v[114:115], s[26:27], 0, v[114:115]
	v_lshl_add_u64 v[114:115], s[14:15], 2, v[114:115]
	global_atomic_add_f32 v[114:115], v112, off
	s_mov_b64 s[26:27], 0

; #define PG8_STAGE(bufoff, gbase, voff) do { _Pragma("unroll") for (int _i = 0; _i < 2; ++_i) \
;         __builtin_amdgcn_global_load_lds((const unsigned*)((const char*)(gbase) + (voff)[_i]), (LAS unsigned*)(lds + (bufoff) + ldsw + _i * 8192), 16, 0, 0); } while (0)
; #define PG8_LDA(dst, b, h) do { _Pragma("unroll") for (int m = 0; m < 4; ++m) _Pragma("unroll") for (int k = 0; k < 2; ++k) dst[m][k] = *(const LAS bf16x8*)(lds + PG8_SA(b, h) + aoff + m * 2048 + k * 1024); } while (0)
; #define PG8_LDB(dst, b, h) do { _Pragma("unroll") for (int n = 0; n < 2; ++n) _Pragma("unroll") for (int k = 0; k < 2; ++k) dst[n][k] = *(const LAS bf16x8*)(lds + PG8_SB(b, h) + boff + n * 2048 + k * 1024); } while (0)
; #define PG8_MMA(ai, bj, At, Bt) do { __builtin_amdgcn_s_setprio(1); _Pragma("unroll") for (int m = 0; m < 4; ++m) _Pragma("unroll") for (int n = 0; n < 2; ++n) _Pragma("unroll") for (int k = 0; k < 2; ++k) \
;         acc[ai][bj][m][n] = __builtin_amdgcn_mfma_f32_16x16x32_bf16(Bt[n][k], At[m][k], acc[ai][bj][m][n], 0, 0, 0); __builtin_amdgcn_s_setprio(0); } while (0)
; #define PG8_WAIT_V(n) asm volatile("s_waitcnt vmcnt(" #n ")" ::: "memory")
; #define PG8_WAIT_L(n) asm volatile("s_waitcnt lgkmcnt(" #n ")" ::: "memory")
; #define PG8_BAR __builtin_amdgcn_s_barrier()
; template <class Epi>
; DEV void gemm_phase(LAS unsigned char* lds, const Gemm g, const StaticOrder& S, const Epi& E) {
;     ...
;         for (int t = 0; t < nt; t += 2) {
;             const bool last = (t == nt - 2);
;             const char* a1 = cA + (size_t)(t + 1) * kstep;
;             const char* a2 = last ? nA : cA + (size_t)(t + 2) * kstep; const char* b2 = last ? nB : cB + (size_t)(t + 2) * kstep;
;             const char* a3 = a2 + kstep; const char* b3 = b2 + kstep;
;             PG8_LDB(B0, 0, 0); PG8_SCHED; PG8_LDA(At, 0, 0); PG8_STAGE(PG8_SA(1, 1), a1 + hstep, voffA);
;             PG8_WAIT_L(8); PG8_BAR; PG8_WAIT_L(0); PG8_MMA(0, 0, At, B0); PG8_BAR; PG8_SCHED;
;             PG8_LDB(B1, 0, 1); PG8_STAGE(PG8_SB(0, 0), b2, voffB);
;             PG8_BAR; PG8_WAIT_L(0); PG8_MMA(0, 1, At, B1); PG8_BAR;
;             PG8_LDA(At, 0, 1); PG8_STAGE(PG8_SA(0, 0), a2, voffA);
;             PG8_BAR; PG8_WAIT_L(0); PG8_MMA(1, 0, At, B0); PG8_BAR; PG8_SCHED;
;             PG8_STAGE(PG8_SB(0, 1), b2 + hstep, voffB);
;             PG8_WAIT_V(6); PG8_BAR; PG8_MMA(1, 1, At, B1); PG8_BAR;
.LBB0_152:
	s_add_u32 s20, s18, 0xfff80080
	s_addc_u32 s21, s19, -1
	s_add_i32 s41, 0, 0x10000
	v_add_u32_e32 v140, s41, v176
	ds_read_b128 v[128:131], v140
	ds_read_b128 v[132:135], v140 offset:1024
	ds_read_b128 v[136:139], v140 offset:2048
	ds_read_b128 v[140:143], v140 offset:3072
	s_cmp_eq_u32 s40, 28
	s_cselect_b32 s23, s5, s21
	s_cselect_b32 s22, s11, s20
	s_cselect_b32 s21, s9, s39
	s_cselect_b32 s20, s37, s38
	s_add_i32 m0, s17, 0xc000
	ds_read_b128 v[180:183], v178
	ds_read_b128 v[184:187], v178 offset:1024
	ds_read_b128 v[188:191], v178 offset:2048
	ds_read_b128 v[192:195], v178 offset:3072
	ds_read_b128 v[214:217], v178 offset:4096
	ds_read_b128 v[218:221], v178 offset:5120
	ds_read_b128 v[222:225], v178 offset:6144
	ds_read_b128 v[226:229], v178 offset:7168
	global_load_lds_dwordx4 v154, s[18:19]
	s_add_i32 m0, s17, 0xe000
	s_nop 0
	global_load_lds_dwordx4 v156, s[18:19]
	s_waitcnt lgkmcnt(8)
	s_barrier
	s_waitcnt lgkmcnt(0)
	v_mfma_f32_16x16x32_bf16 v[124:127], v[128:131], v[180:183], v[124:127]
	v_mfma_f32_16x16x32_bf16 v[120:123], v[136:139], v[180:183], v[120:123]
	v_mfma_f32_16x16x32_bf16 v[108:111], v[128:131], v[188:191], v[108:111]
	v_mfma_f32_16x16x32_bf16 v[104:107], v[136:139], v[188:191], v[104:107]
	v_mfma_f32_16x16x32_bf16 v[92:95], v[128:131], v[214:217], v[92:95]
	v_mfma_f32_16x16x32_bf16 v[88:91], v[136:139], v[214:217], v[88:91]
	v_mfma_f32_16x16x32_bf16 v[76:79], v[128:131], v[222:225], v[76:79]
	v_mfma_f32_16x16x32_bf16 v[72:75], v[136:139], v[222:225], v[72:75]
	v_mfma_f32_16x16x32_bf16 v[124:127], v[132:135], v[184:187], v[124:127]
	v_mfma_f32_16x16x32_bf16 v[120:123], v[140:143], v[184:187], v[120:123]
	v_mfma_f32_16x16x32_bf16 v[108:111], v[132:135], v[192:195], v[108:111]
	v_mfma_f32_16x16x32_bf16 v[104:107], v[140:143], v[192:195], v[104:107]
	v_mfma_f32_16x16x32_bf16 v[92:95], v[132:135], v[218:221], v[92:95]
	v_mfma_f32_16x16x32_bf16 v[88:91], v[140:143], v[218:221], v[88:91]
	v_mfma_f32_16x16x32_bf16 v[76:79], v[132:135], v[226:229], v[76:79]
	v_mfma_f32_16x16x32_bf16 v[72:75], v[140:143], v[226:229], v[72:75]
	s_barrier
	s_add_i32 s44, 0, 0x14000
	v_add_u32_e32 v158, s44, v176
	s_add_i32 s41, s41, s26
	ds_read_b128 v[230:233], v158
	ds_read_b128 v[234:237], v158 offset:1024
	ds_read_b128 v[238:241], v158 offset:2048
	ds_read_b128 v[242:245], v158 offset:3072
	s_mov_b32 m0, s41
	s_nop 0
	global_load_lds_dwordx4 v160, s[20:21]
	s_add_i32 m0, s41, 0x2000
	s_nop 0
	global_load_lds_dwordx4 v144, s[20:21]
	s_barrier
	s_waitcnt lgkmcnt(0)
	v_mfma_f32_16x16x32_bf16 v[116:119], v[230:233], v[180:183], v[116:119]
	v_mfma_f32_16x16x32_bf16 v[112:115], v[238:241], v[180:183], v[112:115]
	v_mfma_f32_16x16x32_bf16 v[100:103], v[230:233], v[188:191], v[100:103]
	v_mfma_f32_16x16x32_bf16 v[96:99], v[238:241], v[188:191], v[96:99]
	v_mfma_f32_16x16x32_bf16 v[84:87], v[230:233], v[214:217], v[84:87]
	v_mfma_f32_16x16x32_bf16 v[80:83], v[238:241], v[214:217], v[80:83]
	v_mfma_f32_16x16x32_bf16 v[68:71], v[230:233], v[222:225], v[68:71]
	v_mfma_f32_16x16x32_bf16 v[64:67], v[238:241], v[222:225], v[64:67]
	v_mfma_f32_16x16x32_bf16 v[116:119], v[234:237], v[184:187], v[116:119]
	v_mfma_f32_16x16x32_bf16 v[112:115], v[242:245], v[184:187], v[112:115]
	v_mfma_f32_16x16x32_bf16 v[100:103], v[234:237], v[192:195], v[100:103]
	v_mfma_f32_16x16x32_bf16 v[96:99], v[242:245], v[192:195], v[96:99]
	v_mfma_f32_16x16x32_bf16 v[84:87], v[234:237], v[218:221], v[84:87]
	v_mfma_f32_16x16x32_bf16 v[80:83], v[242:245], v[218:221], v[80:83]
	v_mfma_f32_16x16x32_bf16 v[68:71], v[234:237], v[226:229], v[68:71]
	v_mfma_f32_16x16x32_bf16 v[64:67], v[242:245], v[226:229], v[64:67]
	s_mov_b32 m0, s17
	v_lshl_add_u64 v[196:197], s[22:23], 0, v[160:161]
	s_barrier
	ds_read_b128 v[180:183], v178 offset:16384
	ds_read_b128 v[184:187], v178 offset:17408
	ds_read_b128 v[188:191], v178 offset:18432
	ds_read_b128 v[192:195], v178 offset:19456
	ds_read_b128 v[214:217], v178 offset:20480
	ds_read_b128 v[218:221], v178 offset:21504
	ds_read_b128 v[222:225], v178 offset:22528
	ds_read_b128 v[226:229], v178 offset:23552
	global_load_lds_dwordx4 v160, s[22:23]
	v_lshl_add_u64 v[246:247], s[22:23], 0, v[144:145]
	s_mov_b32 m0, s27
	s_nop 0
	global_load_lds_dwordx4 v144, s[22:23]
	s_barrier
	s_waitcnt lgkmcnt(0)
	v_mfma_f32_16x16x32_bf16 v[60:63], v[128:131], v[180:183], v[60:63]
	v_mfma_f32_16x16x32_bf16 v[56:59], v[136:139], v[180:183], v[56:59]
	v_mfma_f32_16x16x32_bf16 v[44:47], v[128:131], v[188:191], v[44:47]
	v_mfma_f32_16x16x32_bf16 v[40:43], v[136:139], v[188:191], v[40:43]
	v_mfma_f32_16x16x32_bf16 v[28:31], v[128:131], v[214:217], v[28:31]
	v_mfma_f32_16x16x32_bf16 v[24:27], v[136:139], v[214:217], v[24:27]
	v_mfma_f32_16x16x32_bf16 v[12:15], v[128:131], v[222:225], v[12:15]
	v_mfma_f32_16x16x32_bf16 v[8:11], v[136:139], v[222:225], v[8:11]
	v_mfma_f32_16x16x32_bf16 v[60:63], v[132:135], v[184:187], v[60:63]
	v_mfma_f32_16x16x32_bf16 v[56:59], v[140:143], v[184:187], v[56:59]
	v_mfma_f32_16x16x32_bf16 v[44:47], v[132:135], v[192:195], v[44:47]
	v_mfma_f32_16x16x32_bf16 v[40:43], v[140:143], v[192:195], v[40:43]
	v_mfma_f32_16x16x32_bf16 v[28:31], v[132:135], v[218:221], v[28:31]
	v_mfma_f32_16x16x32_bf16 v[24:27], v[140:143], v[218:221], v[24:27]
	v_mfma_f32_16x16x32_bf16 v[12:15], v[132:135], v[226:229], v[12:15]
	v_mfma_f32_16x16x32_bf16 v[8:11], v[140:143], v[226:229], v[8:11]
	s_barrier
	s_add_u32 s42, s20, 0x80000
	s_addc_u32 s43, s21, 0
	s_add_i32 s41, s44, s26
	s_mov_b32 m0, s41
	s_nop 0
	global_load_lds_dwordx4 v160, s[42:43]
	s_add_i32 m0, s41, 0x2000
	s_nop 0
	global_load_lds_dwordx4 v144, s[42:43]
	s_waitcnt vmcnt(6)
	s_barrier
; #define PG8_STAGE(bufoff, gbase, voff) do { _Pragma("unroll") for (int _i = 0; _i < 2; ++_i) \
;         __builtin_amdgcn_global_load_lds((const unsigned*)((const char*)(gbase) + (voff)[_i]), (LAS unsigned*)(lds + (bufoff) + ldsw + _i * 8192), 16, 0, 0); } while (0)
; #define PG8_LDA(dst, b, h) do { _Pragma("unroll") for (int m = 0; m < 4; ++m) _Pragma("unroll") for (int k = 0; k < 2; ++k) dst[m][k] = *(const LAS bf16x8*)(lds + PG8_SA(b, h) + aoff + m * 2048 + k * 1024); } while (0)
; #define PG8_LDB(dst, b, h) do { _Pragma("unroll") for (int n = 0; n < 2; ++n) _Pragma("unroll") for (int k = 0; k < 2; ++k) dst[n][k] = *(const LAS bf16x8*)(lds + PG8_SB(b, h) + boff + n * 2048 + k * 1024); } while (0)
; #define PG8_MMA(ai, bj, At, Bt) do { __builtin_amdgcn_s_setprio(1); _Pragma("unroll") for (int m = 0; m < 4; ++m) _Pragma("unroll") for (int n = 0; n < 2; ++n) _Pragma("unroll") for (int k = 0; k < 2; ++k) \
;         acc[ai][bj][m][n] = __builtin_amdgcn_mfma_f32_16x16x32_bf16(Bt[n][k], At[m][k], acc[ai][bj][m][n], 0, 0, 0); __builtin_amdgcn_s_setprio(0); } while (0)
; #define PG8_WAIT_V(n) asm volatile("s_waitcnt vmcnt(" #n ")" ::: "memory")
; #define PG8_WAIT_L(n) asm volatile("s_waitcnt lgkmcnt(" #n ")" ::: "memory")
; #define PG8_BAR __builtin_amdgcn_s_barrier()
; #define PG8_SCHED __builtin_amdgcn_sched_barrier(0)
; template <class Epi>
; DEV void gemm_phase(LAS unsigned char* lds, const Gemm g, const StaticOrder& S, const Epi& E) {
;     ...
;             PG8_WAIT_V(6); PG8_BAR; PG8_MMA(1, 1, At, B1); PG8_BAR;
;             PG8_LDB(B0, 1, 0); PG8_SCHED; PG8_LDA(At, 1, 0); PG8_STAGE(PG8_SA(0, 1), a2 + hstep, voffA);
;             PG8_WAIT_L(8); PG8_BAR; PG8_WAIT_L(0); PG8_MMA(0, 0, At, B0); PG8_BAR; PG8_SCHED;
;             PG8_LDB(B1, 1, 1); PG8_STAGE(PG8_SB(1, 0), b3, voffB);
;             PG8_BAR; PG8_WAIT_L(0); PG8_MMA(0, 1, At, B1); PG8_BAR;
;             PG8_LDA(At, 1, 1); PG8_STAGE(PG8_SA(1, 0), a3, voffA);
;             PG8_BAR; PG8_WAIT_L(0); PG8_MMA(1, 0, At, B0); PG8_BAR; PG8_SCHED;
	v_mfma_f32_16x16x32_bf16 v[52:55], v[230:233], v[180:183], v[52:55]
	v_mfma_f32_16x16x32_bf16 v[48:51], v[238:241], v[180:183], v[48:51]
	v_mfma_f32_16x16x32_bf16 v[36:39], v[230:233], v[188:191], v[36:39]
	v_mfma_f32_16x16x32_bf16 v[32:35], v[238:241], v[188:191], v[32:35]
	v_mfma_f32_16x16x32_bf16 v[20:23], v[230:233], v[214:217], v[20:23]
	v_mfma_f32_16x16x32_bf16 v[16:19], v[238:241], v[214:217], v[16:19]
	v_mfma_f32_16x16x32_bf16 v[4:7], v[230:233], v[222:225], v[4:7]
	v_mfma_f32_16x16x32_bf16 v[0:3], v[238:241], v[222:225], v[0:3]
	v_mfma_f32_16x16x32_bf16 v[52:55], v[234:237], v[184:187], v[52:55]
	v_mfma_f32_16x16x32_bf16 v[48:51], v[242:245], v[184:187], v[48:51]
	v_mfma_f32_16x16x32_bf16 v[36:39], v[234:237], v[192:195], v[36:39]
	v_mfma_f32_16x16x32_bf16 v[32:35], v[242:245], v[192:195], v[32:35]
	v_mfma_f32_16x16x32_bf16 v[20:23], v[234:237], v[218:221], v[20:23]
	v_mfma_f32_16x16x32_bf16 v[16:19], v[242:245], v[218:221], v[16:19]
	v_mfma_f32_16x16x32_bf16 v[4:7], v[234:237], v[226:229], v[4:7]
	v_mfma_f32_16x16x32_bf16 v[0:3], v[242:245], v[226:229], v[0:3]
	s_add_i32 s41, 0, 0x18000
	v_add_u32_e32 v140, s41, v176
	s_barrier
	ds_read_b128 v[128:131], v140
	ds_read_b128 v[132:135], v140 offset:1024
	ds_read_b128 v[136:139], v140 offset:2048
	ds_read_b128 v[140:143], v140 offset:3072
	s_add_u32 s22, s22, 0x80000
	s_addc_u32 s23, s23, 0
	s_mov_b32 m0, s28
	ds_read_b128 v[180:183], v178 offset:32768
	ds_read_b128 v[184:187], v178 offset:33792
	ds_read_b128 v[188:191], v178 offset:34816
	ds_read_b128 v[192:195], v178 offset:35840
	ds_read_b128 v[214:217], v178 offset:36864
	ds_read_b128 v[218:221], v178 offset:37888
	ds_read_b128 v[222:225], v178 offset:38912
	ds_read_b128 v[226:229], v178 offset:39936
	global_load_lds_dwordx4 v160, s[22:23]
	s_mov_b32 m0, s29
	s_nop 0
	global_load_lds_dwordx4 v144, s[22:23]
	s_waitcnt lgkmcnt(8)
	s_barrier
	s_waitcnt lgkmcnt(0)
	v_mfma_f32_16x16x32_bf16 v[124:127], v[128:131], v[180:183], v[124:127]
	v_mfma_f32_16x16x32_bf16 v[120:123], v[136:139], v[180:183], v[120:123]
	v_mfma_f32_16x16x32_bf16 v[108:111], v[128:131], v[188:191], v[108:111]
	v_mfma_f32_16x16x32_bf16 v[104:107], v[136:139], v[188:191], v[104:107]
	v_mfma_f32_16x16x32_bf16 v[92:95], v[128:131], v[214:217], v[92:95]
	v_mfma_f32_16x16x32_bf16 v[88:91], v[136:139], v[214:217], v[88:91]
	v_mfma_f32_16x16x32_bf16 v[76:79], v[128:131], v[222:225], v[76:79]
	v_mfma_f32_16x16x32_bf16 v[72:75], v[136:139], v[222:225], v[72:75]
	v_mfma_f32_16x16x32_bf16 v[124:127], v[132:135], v[184:187], v[124:127]
	v_mfma_f32_16x16x32_bf16 v[120:123], v[140:143], v[184:187], v[120:123]
	v_mfma_f32_16x16x32_bf16 v[108:111], v[132:135], v[192:195], v[108:111]
	v_mfma_f32_16x16x32_bf16 v[104:107], v[140:143], v[192:195], v[104:107]
	v_mfma_f32_16x16x32_bf16 v[92:95], v[132:135], v[218:221], v[92:95]
	v_mfma_f32_16x16x32_bf16 v[88:91], v[140:143], v[218:221], v[88:91]
	v_mfma_f32_16x16x32_bf16 v[76:79], v[132:135], v[226:229], v[76:79]
	v_mfma_f32_16x16x32_bf16 v[72:75], v[140:143], v[226:229], v[72:75]
	s_barrier
	s_add_i32 s22, 0, 0x1c000
	s_add_i32 s23, s41, s26
	v_add_u32_e32 v179, s22, v176
	s_add_u32 s100, s20, 0x80
	s_addc_u32 s101, s21, 0
	s_mov_b32 m0, s23
	ds_read_b128 v[230:233], v179
	ds_read_b128 v[234:237], v179 offset:1024
	ds_read_b128 v[238:241], v179 offset:2048
	ds_read_b128 v[242:245], v179 offset:3072
	global_load_lds_dwordx4 v160, s[100:101]
	s_add_i32 m0, s23, 0x2000
	s_nop 0
	global_load_lds_dwordx4 v144, s[100:101]
	s_barrier
	s_waitcnt lgkmcnt(0)
	v_mfma_f32_16x16x32_bf16 v[116:119], v[230:233], v[180:183], v[116:119]
	v_mfma_f32_16x16x32_bf16 v[112:115], v[238:241], v[180:183], v[112:115]
	v_mfma_f32_16x16x32_bf16 v[100:103], v[230:233], v[188:191], v[100:103]
	v_mfma_f32_16x16x32_bf16 v[96:99], v[238:241], v[188:191], v[96:99]
	v_mfma_f32_16x16x32_bf16 v[84:87], v[230:233], v[214:217], v[84:87]
	v_mfma_f32_16x16x32_bf16 v[80:83], v[238:241], v[214:217], v[80:83]
	v_mfma_f32_16x16x32_bf16 v[68:71], v[230:233], v[222:225], v[68:71]
	v_mfma_f32_16x16x32_bf16 v[64:67], v[238:241], v[222:225], v[64:67]
	v_mfma_f32_16x16x32_bf16 v[116:119], v[234:237], v[184:187], v[116:119]
	v_mfma_f32_16x16x32_bf16 v[112:115], v[242:245], v[184:187], v[112:115]
	v_mfma_f32_16x16x32_bf16 v[100:103], v[234:237], v[192:195], v[100:103]
	v_mfma_f32_16x16x32_bf16 v[96:99], v[242:245], v[192:195], v[96:99]
	v_mfma_f32_16x16x32_bf16 v[84:87], v[234:237], v[218:221], v[84:87]
	v_mfma_f32_16x16x32_bf16 v[80:83], v[242:245], v[218:221], v[80:83]
	v_mfma_f32_16x16x32_bf16 v[68:71], v[234:237], v[226:229], v[68:71]
	v_mfma_f32_16x16x32_bf16 v[64:67], v[242:245], v[226:229], v[64:67]
	s_mov_b32 m0, s30
	v_lshl_add_u64 v[158:159], v[196:197], 0, s[2:3]
	s_barrier
; #define PG8_STAGE(bufoff, gbase, voff) do { _Pragma("unroll") for (int _i = 0; _i < 2; ++_i) \
;         __builtin_amdgcn_global_load_lds((const unsigned*)((const char*)(gbase) + (voff)[_i]), (LAS unsigned*)(lds + (bufoff) + ldsw + _i * 8192), 16, 0, 0); } while (0)
; #define PG8_MMA(ai, bj, At, Bt) do { __builtin_amdgcn_s_setprio(1); _Pragma("unroll") for (int m = 0; m < 4; ++m) _Pragma("unroll") for (int n = 0; n < 2; ++n) _Pragma("unroll") for (int k = 0; k < 2; ++k) \
;         acc[ai][bj][m][n] = __builtin_amdgcn_mfma_f32_16x16x32_bf16(Bt[n][k], At[m][k], acc[ai][bj][m][n], 0, 0, 0); __builtin_amdgcn_s_setprio(0); } while (0)
; #define PG8_WAIT_V(n) asm volatile("s_waitcnt vmcnt(" #n ")" ::: "memory")
; #define PG8_WAIT_L(n) asm volatile("s_waitcnt lgkmcnt(" #n ")" ::: "memory")
; #define PG8_BAR __builtin_amdgcn_s_barrier()
; #define PG8_SCHED __builtin_amdgcn_sched_barrier(0)
;     DEV void operator()(AccRef acc, const pg8::Unit& u, int wr, int wc, int fr, int fq) const { store_bf16_tile<0, false>(acc, O, ld, u.pm * 256 + wr * 64 + fr, u.pn * 256 + wc * 32 + 4 * fq, ss); }
; template <class Epi>
; DEV void gemm_phase(LAS unsigned char* lds, const Gemm g, const StaticOrder& S, const Epi& E) {
;     ...
;             PG8_BAR; PG8_WAIT_L(0); PG8_MMA(1, 0, At, B0); PG8_BAR; PG8_SCHED;
;             PG8_STAGE(PG8_SB(1, 1), b3 + hstep, voffB);
;             PG8_WAIT_V(6); PG8_BAR; PG8_MMA(1, 1, At, B1); PG8_BAR;
;         }
;     DEV void operator()(AccRef acc, const pg8::Unit& u, int wr, int wc, int fr, int fq) const {
;         const int row0 = u.pm * 256 + wr * 64 + fr, col0 = u.pn * 256 + wc * 32 + 4 * fq;
;         const bool rope = (u.pn < 9) && ((wc & 1) == 0);
; #pragma unroll
;         for (int ai = 0; ai < 2; ++ai)
; #pragma unroll
;             for (int m = 0; m < 4; ++m) { const int row = row0 + ai * 128 + m * 16; u16* rowp = O + (size_t)row * 2560 + col0; const float rs = rowscale(ss, row);
;                 f32x4 cs = (f32x4){1.f, 1.f, 1.f, 1.f}, sn = (f32x4){0.f, 0.f, 0.f, 0.f};
;                 if (rope) { cs = *(const f32x4*)(cosT + row * 8 + 4 * (fq & 1)); sn = *(const f32x4*)(sinT + row * 8 + 4 * (fq & 1)); }
	ds_read_b128 v[180:183], v178 offset:49152
	ds_read_b128 v[184:187], v178 offset:50176
	ds_read_b128 v[188:191], v178 offset:51200
	ds_read_b128 v[192:195], v178 offset:52224
	ds_read_b128 v[214:217], v178 offset:53248
	ds_read_b128 v[218:221], v178 offset:54272
	ds_read_b128 v[222:225], v178 offset:55296
	ds_read_b128 v[226:229], v178 offset:56320
	global_load_lds_dwordx4 v[158:159], off
	v_lshl_add_u64 v[158:159], v[246:247], 0, s[2:3]
	s_mov_b32 m0, s31
	s_nop 0
	global_load_lds_dwordx4 v[158:159], off
	s_barrier
	s_waitcnt lgkmcnt(0)
	v_mfma_f32_16x16x32_bf16 v[60:63], v[128:131], v[180:183], v[60:63]
	v_mfma_f32_16x16x32_bf16 v[56:59], v[136:139], v[180:183], v[56:59]
	v_mfma_f32_16x16x32_bf16 v[44:47], v[128:131], v[188:191], v[44:47]
	v_mfma_f32_16x16x32_bf16 v[40:43], v[136:139], v[188:191], v[40:43]
	v_mfma_f32_16x16x32_bf16 v[28:31], v[128:131], v[214:217], v[28:31]
	v_mfma_f32_16x16x32_bf16 v[24:27], v[136:139], v[214:217], v[24:27]
	v_mfma_f32_16x16x32_bf16 v[12:15], v[128:131], v[222:225], v[12:15]
	v_mfma_f32_16x16x32_bf16 v[8:11], v[136:139], v[222:225], v[8:11]
	v_mfma_f32_16x16x32_bf16 v[60:63], v[132:135], v[184:187], v[60:63]
	v_mfma_f32_16x16x32_bf16 v[56:59], v[140:143], v[184:187], v[56:59]
	v_mfma_f32_16x16x32_bf16 v[44:47], v[132:135], v[192:195], v[44:47]
	v_mfma_f32_16x16x32_bf16 v[40:43], v[140:143], v[192:195], v[40:43]
	v_mfma_f32_16x16x32_bf16 v[28:31], v[132:135], v[218:221], v[28:31]
	v_mfma_f32_16x16x32_bf16 v[24:27], v[140:143], v[218:221], v[24:27]
	v_mfma_f32_16x16x32_bf16 v[12:15], v[132:135], v[226:229], v[12:15]
	v_mfma_f32_16x16x32_bf16 v[8:11], v[140:143], v[226:229], v[8:11]
	s_barrier
	s_add_u32 s20, s20, 0x80080
	s_addc_u32 s21, s21, 0
	s_add_i32 s22, s22, s26
	s_mov_b32 m0, s22
	s_nop 0
	global_load_lds_dwordx4 v160, s[20:21]
	s_add_i32 m0, s22, 0x2000
	s_nop 0
	global_load_lds_dwordx4 v144, s[20:21]
	s_waitcnt vmcnt(6)
	s_barrier
	v_mfma_f32_16x16x32_bf16 v[52:55], v[230:233], v[180:183], v[52:55]
	v_mfma_f32_16x16x32_bf16 v[48:51], v[238:241], v[180:183], v[48:51]
	v_mfma_f32_16x16x32_bf16 v[36:39], v[230:233], v[188:191], v[36:39]
	v_mfma_f32_16x16x32_bf16 v[32:35], v[238:241], v[188:191], v[32:35]
	v_mfma_f32_16x16x32_bf16 v[20:23], v[230:233], v[214:217], v[20:23]
	v_mfma_f32_16x16x32_bf16 v[16:19], v[238:241], v[214:217], v[16:19]
	v_mfma_f32_16x16x32_bf16 v[4:7], v[230:233], v[222:225], v[4:7]
	v_mfma_f32_16x16x32_bf16 v[0:3], v[238:241], v[222:225], v[0:3]
	v_mfma_f32_16x16x32_bf16 v[52:55], v[234:237], v[184:187], v[52:55]
	v_mfma_f32_16x16x32_bf16 v[48:51], v[242:245], v[184:187], v[48:51]
	v_mfma_f32_16x16x32_bf16 v[36:39], v[234:237], v[192:195], v[36:39]
	v_mfma_f32_16x16x32_bf16 v[32:35], v[242:245], v[192:195], v[32:35]
	v_mfma_f32_16x16x32_bf16 v[20:23], v[234:237], v[218:221], v[20:23]
	v_mfma_f32_16x16x32_bf16 v[16:19], v[242:245], v[218:221], v[16:19]
	v_mfma_f32_16x16x32_bf16 v[4:7], v[234:237], v[226:229], v[4:7]
	v_mfma_f32_16x16x32_bf16 v[0:3], v[242:245], v[226:229], v[0:3]
	s_add_i32 s40, s40, 2
	s_add_u32 s18, s18, 0x100
	s_addc_u32 s19, s19, 0
	s_add_u32 s38, s38, 0x100
	s_addc_u32 s39, s39, 0
	s_cmp_gt_u32 s40, 29
	s_barrier
	s_cbranch_scc0 .LBB0_152
	v_lshl_add_u32 v174, s4, 8, v167
	v_ashrrev_i32_e32 v175, 31, v174
	v_readlane_b32 s20, v250, 47
	v_lshlrev_b64 v[128:129], 5, v[174:175]
	v_readlane_b32 s21, v250, 48
	s_cmp_lt_i32 s16, 9
	s_cselect_b64 s[4:5], -1, 0
	v_lshl_add_u64 v[128:129], s[20:21], 0, v[128:129]
	global_load_dwordx4 v[136:139], v[128:129], off offset:16
	global_load_dwordx4 v[140:143], v[128:129], off
	s_and_b64 s[18:19], s[6:7], s[4:5]
	v_cndmask_b32_e64 v128, 0, 1, s[18:19]
	v_cmp_ne_u32_e64 s[4:5], 1, v128
	s_andn2_b64 vcc, exec, s[18:19]
	s_cbranch_vccnz .LBB0_155
	v_lshlrev_b32_e32 v128, 3, v174
	v_ashrrev_i32_e32 v129, 31, v128
	v_lshlrev_b64 v[128:129], 2, v[128:129]
	v_lshl_add_u64 v[130:131], v[152:153], 0, v[128:129]
	v_lshl_add_u64 v[132:133], v[150:151], 0, v[128:129]
	global_load_dwordx4 v[128:131], v[130:131], off
	s_nop 0
	global_load_dwordx4 v[132:135], v[132:133], off
	s_branch .LBB0_156

; #define PG8_STAGE(bufoff, gbase, voff) do { _Pragma("unroll") for (int _i = 0; _i < 2; ++_i) \
;         __builtin_amdgcn_global_load_lds((const unsigned*)((const char*)(gbase) + (voff)[_i]), (LAS unsigned*)(lds + (bufoff) + ldsw + _i * 8192), 16, 0, 0); } while (0)
; #define PG8_LDA(dst, b, h) do { _Pragma("unroll") for (int m = 0; m < 4; ++m) _Pragma("unroll") for (int k = 0; k < 2; ++k) dst[m][k] = *(const LAS bf16x8*)(lds + PG8_SA(b, h) + aoff + m * 2048 + k * 1024); } while (0)
; #define PG8_LDB(dst, b, h) do { _Pragma("unroll") for (int n = 0; n < 2; ++n) _Pragma("unroll") for (int k = 0; k < 2; ++k) dst[n][k] = *(const LAS bf16x8*)(lds + PG8_SB(b, h) + boff + n * 2048 + k * 1024); } while (0)
; #define PG8_MMA(ai, bj, At, Bt) do { __builtin_amdgcn_s_setprio(1); _Pragma("unroll") for (int m = 0; m < 4; ++m) _Pragma("unroll") for (int n = 0; n < 2; ++n) _Pragma("unroll") for (int k = 0; k < 2; ++k) \
;         acc[ai][bj][m][n] = __builtin_amdgcn_mfma_f32_16x16x32_bf16(Bt[n][k], At[m][k], acc[ai][bj][m][n], 0, 0, 0); __builtin_amdgcn_s_setprio(0); } while (0)
; #define PG8_WAIT_V(n) asm volatile("s_waitcnt vmcnt(" #n ")" ::: "memory")
; #define PG8_WAIT_L(n) asm volatile("s_waitcnt lgkmcnt(" #n ")" ::: "memory")
; #define PG8_BAR __builtin_amdgcn_s_barrier()
; template <class Epi>
; DEV void gemm_phase(LAS unsigned char* lds, const Gemm g, const StaticOrder& S, const Epi& E) {
;     ...
;         for (int t = 0; t < nt; t += 2) {
;             const bool last = (t == nt - 2);
;             const char* a1 = cA + (size_t)(t + 1) * kstep;
;             const char* a2 = last ? nA : cA + (size_t)(t + 2) * kstep; const char* b2 = last ? nB : cB + (size_t)(t + 2) * kstep;
;             const char* a3 = a2 + kstep; const char* b3 = b2 + kstep;
;             PG8_LDB(B0, 0, 0); PG8_SCHED; PG8_LDA(At, 0, 0); PG8_STAGE(PG8_SA(1, 1), a1 + hstep, voffA);
;             PG8_WAIT_L(8); PG8_BAR; PG8_WAIT_L(0); PG8_MMA(0, 0, At, B0); PG8_BAR; PG8_SCHED;
;             PG8_LDB(B1, 0, 1); PG8_STAGE(PG8_SB(0, 0), b2, voffB);
;             PG8_BAR; PG8_WAIT_L(0); PG8_MMA(0, 1, At, B1); PG8_BAR;
;             PG8_LDA(At, 0, 1); PG8_STAGE(PG8_SA(0, 0), a2, voffA);
;             PG8_BAR; PG8_WAIT_L(0); PG8_MMA(1, 0, At, B0); PG8_BAR; PG8_SCHED;
;             PG8_STAGE(PG8_SB(0, 1), b2 + hstep, voffB);
;             PG8_WAIT_V(6); PG8_BAR; PG8_MMA(1, 1, At, B1); PG8_BAR;
.LBB0_260:
	s_add_u32 s34, s30, 0xfffe0080
	s_addc_u32 s35, s31, -1
	s_add_i32 s55, 0, 0x10000
	v_add_u32_e32 v140, s55, v178
	ds_read_b128 v[128:131], v140
	ds_read_b128 v[132:135], v140 offset:1024
	ds_read_b128 v[136:139], v140 offset:2048
	ds_read_b128 v[140:143], v140 offset:3072
	s_cmp_eq_u32 s54, 4
	s_cselect_b32 s37, s19, s35
	s_cselect_b32 s36, s23, s34
	s_cselect_b32 s35, s21, s53
	s_cselect_b32 s34, s29, s52
	s_add_i32 m0, s43, 0xc000
	ds_read_b128 v[154:157], v181
	ds_read_b128 v[174:177], v181 offset:1024
	ds_read_b128 v[182:185], v181 offset:2048
	ds_read_b128 v[186:189], v181 offset:3072
	ds_read_b128 v[190:193], v181 offset:4096
	ds_read_b128 v[194:197], v181 offset:5120
	ds_read_b128 v[214:217], v181 offset:6144
	ds_read_b128 v[218:221], v181 offset:7168
	global_load_lds_dwordx4 v150, s[30:31]
	s_add_i32 m0, s43, 0xe000
	s_nop 0
	global_load_lds_dwordx4 v152, s[30:31]
	s_waitcnt lgkmcnt(8)
	s_barrier
	s_waitcnt lgkmcnt(0)
	v_mfma_f32_16x16x32_bf16 v[124:127], v[128:131], v[154:157], v[124:127]
	v_mfma_f32_16x16x32_bf16 v[120:123], v[136:139], v[154:157], v[120:123]
	v_mfma_f32_16x16x32_bf16 v[108:111], v[128:131], v[182:185], v[108:111]
	v_mfma_f32_16x16x32_bf16 v[104:107], v[136:139], v[182:185], v[104:107]
	v_mfma_f32_16x16x32_bf16 v[92:95], v[128:131], v[190:193], v[92:95]
	v_mfma_f32_16x16x32_bf16 v[88:91], v[136:139], v[190:193], v[88:91]
	v_mfma_f32_16x16x32_bf16 v[76:79], v[128:131], v[214:217], v[76:79]
	v_mfma_f32_16x16x32_bf16 v[72:75], v[136:139], v[214:217], v[72:75]
	v_mfma_f32_16x16x32_bf16 v[124:127], v[132:135], v[174:177], v[124:127]
	v_mfma_f32_16x16x32_bf16 v[120:123], v[140:143], v[174:177], v[120:123]
	v_mfma_f32_16x16x32_bf16 v[108:111], v[132:135], v[186:189], v[108:111]
	v_mfma_f32_16x16x32_bf16 v[104:107], v[140:143], v[186:189], v[104:107]
	v_mfma_f32_16x16x32_bf16 v[92:95], v[132:135], v[194:197], v[92:95]
	v_mfma_f32_16x16x32_bf16 v[88:91], v[140:143], v[194:197], v[88:91]
	v_mfma_f32_16x16x32_bf16 v[76:79], v[132:135], v[218:221], v[76:79]
	v_mfma_f32_16x16x32_bf16 v[72:75], v[140:143], v[218:221], v[72:75]
	s_barrier
	s_add_i32 s58, 0, 0x14000
	v_add_u32_e32 v158, s58, v178
	s_add_i32 s55, s55, s42
	ds_read_b128 v[222:225], v158
	ds_read_b128 v[226:229], v158 offset:1024
	ds_read_b128 v[230:233], v158 offset:2048
	ds_read_b128 v[234:237], v158 offset:3072
	s_mov_b32 m0, s55
	s_nop 0
	global_load_lds_dwordx4 v160, s[34:35]
	s_add_i32 m0, s55, 0x2000
	s_nop 0
	global_load_lds_dwordx4 v148, s[34:35]
	s_barrier
	s_waitcnt lgkmcnt(0)
	v_mfma_f32_16x16x32_bf16 v[116:119], v[222:225], v[154:157], v[116:119]
	v_mfma_f32_16x16x32_bf16 v[112:115], v[230:233], v[154:157], v[112:115]
	v_mfma_f32_16x16x32_bf16 v[100:103], v[222:225], v[182:185], v[100:103]
	v_mfma_f32_16x16x32_bf16 v[96:99], v[230:233], v[182:185], v[96:99]
	v_mfma_f32_16x16x32_bf16 v[84:87], v[222:225], v[190:193], v[84:87]
	v_mfma_f32_16x16x32_bf16 v[80:83], v[230:233], v[190:193], v[80:83]
	v_mfma_f32_16x16x32_bf16 v[68:71], v[222:225], v[214:217], v[68:71]
	v_mfma_f32_16x16x32_bf16 v[64:67], v[230:233], v[214:217], v[64:67]
	v_mfma_f32_16x16x32_bf16 v[116:119], v[226:229], v[174:177], v[116:119]
	v_mfma_f32_16x16x32_bf16 v[112:115], v[234:237], v[174:177], v[112:115]
	v_mfma_f32_16x16x32_bf16 v[100:103], v[226:229], v[186:189], v[100:103]
	v_mfma_f32_16x16x32_bf16 v[96:99], v[234:237], v[186:189], v[96:99]
	v_mfma_f32_16x16x32_bf16 v[84:87], v[226:229], v[194:197], v[84:87]
	v_mfma_f32_16x16x32_bf16 v[80:83], v[234:237], v[194:197], v[80:83]
	v_mfma_f32_16x16x32_bf16 v[68:71], v[226:229], v[218:221], v[68:71]
	v_mfma_f32_16x16x32_bf16 v[64:67], v[234:237], v[218:221], v[64:67]
	s_mov_b32 m0, s43
	v_lshl_add_u64 v[240:241], s[36:37], 0, v[144:145]
	s_barrier
	ds_read_b128 v[154:157], v181 offset:16384
	ds_read_b128 v[174:177], v181 offset:17408
	ds_read_b128 v[182:185], v181 offset:18432
	ds_read_b128 v[186:189], v181 offset:19456
	ds_read_b128 v[190:193], v181 offset:20480
	ds_read_b128 v[194:197], v181 offset:21504
	ds_read_b128 v[214:217], v181 offset:22528
	ds_read_b128 v[218:221], v181 offset:23552
	global_load_lds_dwordx4 v144, s[36:37]
	v_lshl_add_u64 v[242:243], s[36:37], 0, v[146:147]
	s_mov_b32 m0, s44
	s_nop 0
	global_load_lds_dwordx4 v146, s[36:37]
	s_barrier
	s_waitcnt lgkmcnt(0)
	v_mfma_f32_16x16x32_bf16 v[60:63], v[128:131], v[154:157], v[60:63]
	v_mfma_f32_16x16x32_bf16 v[56:59], v[136:139], v[154:157], v[56:59]
	v_mfma_f32_16x16x32_bf16 v[44:47], v[128:131], v[182:185], v[44:47]
	v_mfma_f32_16x16x32_bf16 v[40:43], v[136:139], v[182:185], v[40:43]
	v_mfma_f32_16x16x32_bf16 v[28:31], v[128:131], v[190:193], v[28:31]
	v_mfma_f32_16x16x32_bf16 v[24:27], v[136:139], v[190:193], v[24:27]
	v_mfma_f32_16x16x32_bf16 v[12:15], v[128:131], v[214:217], v[12:15]
	v_mfma_f32_16x16x32_bf16 v[8:11], v[136:139], v[214:217], v[8:11]
	v_mfma_f32_16x16x32_bf16 v[60:63], v[132:135], v[174:177], v[60:63]
	v_mfma_f32_16x16x32_bf16 v[56:59], v[140:143], v[174:177], v[56:59]
	v_mfma_f32_16x16x32_bf16 v[44:47], v[132:135], v[186:189], v[44:47]
	v_mfma_f32_16x16x32_bf16 v[40:43], v[140:143], v[186:189], v[40:43]
	v_mfma_f32_16x16x32_bf16 v[28:31], v[132:135], v[194:197], v[28:31]
	v_mfma_f32_16x16x32_bf16 v[24:27], v[140:143], v[194:197], v[24:27]
	v_mfma_f32_16x16x32_bf16 v[12:15], v[132:135], v[218:221], v[12:15]
	v_mfma_f32_16x16x32_bf16 v[8:11], v[140:143], v[218:221], v[8:11]
	s_barrier
	s_add_u32 s56, s34, 0x20000
	s_addc_u32 s57, s35, 0
	s_add_i32 s55, s58, s42
	s_mov_b32 m0, s55
	s_nop 0
	global_load_lds_dwordx4 v160, s[56:57]
	s_add_i32 m0, s55, 0x2000
	s_nop 0
	global_load_lds_dwordx4 v148, s[56:57]
	s_waitcnt vmcnt(6)
	s_barrier
; #define PG8_STAGE(bufoff, gbase, voff) do { _Pragma("unroll") for (int _i = 0; _i < 2; ++_i) \
;         __builtin_amdgcn_global_load_lds((const unsigned*)((const char*)(gbase) + (voff)[_i]), (LAS unsigned*)(lds + (bufoff) + ldsw + _i * 8192), 16, 0, 0); } while (0)
; #define PG8_LDA(dst, b, h) do { _Pragma("unroll") for (int m = 0; m < 4; ++m) _Pragma("unroll") for (int k = 0; k < 2; ++k) dst[m][k] = *(const LAS bf16x8*)(lds + PG8_SA(b, h) + aoff + m * 2048 + k * 1024); } while (0)
; #define PG8_LDB(dst, b, h) do { _Pragma("unroll") for (int n = 0; n < 2; ++n) _Pragma("unroll") for (int k = 0; k < 2; ++k) dst[n][k] = *(const LAS bf16x8*)(lds + PG8_SB(b, h) + boff + n * 2048 + k * 1024); } while (0)
; #define PG8_MMA(ai, bj, At, Bt) do { __builtin_amdgcn_s_setprio(1); _Pragma("unroll") for (int m = 0; m < 4; ++m) _Pragma("unroll") for (int n = 0; n < 2; ++n) _Pragma("unroll") for (int k = 0; k < 2; ++k) \
;         acc[ai][bj][m][n] = __builtin_amdgcn_mfma_f32_16x16x32_bf16(Bt[n][k], At[m][k], acc[ai][bj][m][n], 0, 0, 0); __builtin_amdgcn_s_setprio(0); } while (0)
; #define PG8_WAIT_V(n) asm volatile("s_waitcnt vmcnt(" #n ")" ::: "memory")
; #define PG8_WAIT_L(n) asm volatile("s_waitcnt lgkmcnt(" #n ")" ::: "memory")
; #define PG8_BAR __builtin_amdgcn_s_barrier()
; #define PG8_SCHED __builtin_amdgcn_sched_barrier(0)
; template <class Epi>
; DEV void gemm_phase(LAS unsigned char* lds, const Gemm g, const StaticOrder& S, const Epi& E) {
;     ...
;             PG8_WAIT_V(6); PG8_BAR; PG8_MMA(1, 1, At, B1); PG8_BAR;
;             PG8_LDB(B0, 1, 0); PG8_SCHED; PG8_LDA(At, 1, 0); PG8_STAGE(PG8_SA(0, 1), a2 + hstep, voffA);
;             PG8_WAIT_L(8); PG8_BAR; PG8_WAIT_L(0); PG8_MMA(0, 0, At, B0); PG8_BAR; PG8_SCHED;
;             PG8_LDB(B1, 1, 1); PG8_STAGE(PG8_SB(1, 0), b3, voffB);
;             PG8_BAR; PG8_WAIT_L(0); PG8_MMA(0, 1, At, B1); PG8_BAR;
;             PG8_LDA(At, 1, 1); PG8_STAGE(PG8_SA(1, 0), a3, voffA);
;             PG8_BAR; PG8_WAIT_L(0); PG8_MMA(1, 0, At, B0); PG8_BAR; PG8_SCHED;
;             PG8_STAGE(PG8_SB(1, 1), b3 + hstep, voffB);
	v_mfma_f32_16x16x32_bf16 v[52:55], v[222:225], v[154:157], v[52:55]
	v_mfma_f32_16x16x32_bf16 v[48:51], v[230:233], v[154:157], v[48:51]
	v_mfma_f32_16x16x32_bf16 v[36:39], v[222:225], v[182:185], v[36:39]
	v_mfma_f32_16x16x32_bf16 v[32:35], v[230:233], v[182:185], v[32:35]
	v_mfma_f32_16x16x32_bf16 v[20:23], v[222:225], v[190:193], v[20:23]
	v_mfma_f32_16x16x32_bf16 v[16:19], v[230:233], v[190:193], v[16:19]
	v_mfma_f32_16x16x32_bf16 v[4:7], v[222:225], v[214:217], v[4:7]
	v_mfma_f32_16x16x32_bf16 v[0:3], v[230:233], v[214:217], v[0:3]
	v_mfma_f32_16x16x32_bf16 v[52:55], v[226:229], v[174:177], v[52:55]
	v_mfma_f32_16x16x32_bf16 v[48:51], v[234:237], v[174:177], v[48:51]
	v_mfma_f32_16x16x32_bf16 v[36:39], v[226:229], v[186:189], v[36:39]
	v_mfma_f32_16x16x32_bf16 v[32:35], v[234:237], v[186:189], v[32:35]
	v_mfma_f32_16x16x32_bf16 v[20:23], v[226:229], v[194:197], v[20:23]
	v_mfma_f32_16x16x32_bf16 v[16:19], v[234:237], v[194:197], v[16:19]
	v_mfma_f32_16x16x32_bf16 v[4:7], v[226:229], v[218:221], v[4:7]
	v_mfma_f32_16x16x32_bf16 v[0:3], v[234:237], v[218:221], v[0:3]
	s_add_i32 s55, 0, 0x18000
	v_add_u32_e32 v140, s55, v178
	s_barrier
	ds_read_b128 v[128:131], v140
	ds_read_b128 v[132:135], v140 offset:1024
	ds_read_b128 v[136:139], v140 offset:2048
	ds_read_b128 v[140:143], v140 offset:3072
	s_add_u32 s36, s36, 0x20000
	s_addc_u32 s37, s37, 0
	s_mov_b32 m0, s45
	ds_read_b128 v[154:157], v181 offset:32768
	ds_read_b128 v[174:177], v181 offset:33792
	ds_read_b128 v[182:185], v181 offset:34816
	ds_read_b128 v[186:189], v181 offset:35840
	ds_read_b128 v[190:193], v181 offset:36864
	ds_read_b128 v[194:197], v181 offset:37888
	ds_read_b128 v[214:217], v181 offset:38912
	ds_read_b128 v[218:221], v181 offset:39936
	global_load_lds_dwordx4 v144, s[36:37]
	s_mov_b32 m0, s46
	s_nop 0
	global_load_lds_dwordx4 v146, s[36:37]
	s_waitcnt lgkmcnt(8)
	s_barrier
	s_waitcnt lgkmcnt(0)
	v_mfma_f32_16x16x32_bf16 v[124:127], v[128:131], v[154:157], v[124:127]
	v_mfma_f32_16x16x32_bf16 v[120:123], v[136:139], v[154:157], v[120:123]
	v_mfma_f32_16x16x32_bf16 v[108:111], v[128:131], v[182:185], v[108:111]
	v_mfma_f32_16x16x32_bf16 v[104:107], v[136:139], v[182:185], v[104:107]
	v_mfma_f32_16x16x32_bf16 v[92:95], v[128:131], v[190:193], v[92:95]
	v_mfma_f32_16x16x32_bf16 v[88:91], v[136:139], v[190:193], v[88:91]
	v_mfma_f32_16x16x32_bf16 v[76:79], v[128:131], v[214:217], v[76:79]
	v_mfma_f32_16x16x32_bf16 v[72:75], v[136:139], v[214:217], v[72:75]
	v_mfma_f32_16x16x32_bf16 v[124:127], v[132:135], v[174:177], v[124:127]
	v_mfma_f32_16x16x32_bf16 v[120:123], v[140:143], v[174:177], v[120:123]
	v_mfma_f32_16x16x32_bf16 v[108:111], v[132:135], v[186:189], v[108:111]
	v_mfma_f32_16x16x32_bf16 v[104:107], v[140:143], v[186:189], v[104:107]
	v_mfma_f32_16x16x32_bf16 v[92:95], v[132:135], v[194:197], v[92:95]
	v_mfma_f32_16x16x32_bf16 v[88:91], v[140:143], v[194:197], v[88:91]
	v_mfma_f32_16x16x32_bf16 v[76:79], v[132:135], v[218:221], v[76:79]
	v_mfma_f32_16x16x32_bf16 v[72:75], v[140:143], v[218:221], v[72:75]
	s_barrier
	s_add_i32 s36, 0, 0x1c000
	s_add_i32 s37, s55, s42
	v_add_u32_e32 v234, s36, v178
	s_add_u32 s100, s34, 0x80
	s_addc_u32 s101, s35, 0
	s_mov_b32 m0, s37
	ds_read_b128 v[222:225], v234
	ds_read_b128 v[226:229], v234 offset:1024
	ds_read_b128 v[230:233], v234 offset:2048
	ds_read_b128 v[234:237], v234 offset:3072
	global_load_lds_dwordx4 v160, s[100:101]
	s_add_i32 m0, s37, 0x2000
	s_nop 0
	global_load_lds_dwordx4 v148, s[100:101]
	s_barrier
	s_waitcnt lgkmcnt(0)
	v_mfma_f32_16x16x32_bf16 v[116:119], v[222:225], v[154:157], v[116:119]
	v_mfma_f32_16x16x32_bf16 v[112:115], v[230:233], v[154:157], v[112:115]
	v_mfma_f32_16x16x32_bf16 v[100:103], v[222:225], v[182:185], v[100:103]
	v_mfma_f32_16x16x32_bf16 v[96:99], v[230:233], v[182:185], v[96:99]
	v_mfma_f32_16x16x32_bf16 v[84:87], v[222:225], v[190:193], v[84:87]
	v_mfma_f32_16x16x32_bf16 v[80:83], v[230:233], v[190:193], v[80:83]
	v_mfma_f32_16x16x32_bf16 v[68:71], v[222:225], v[214:217], v[68:71]
	v_mfma_f32_16x16x32_bf16 v[64:67], v[230:233], v[214:217], v[64:67]
	v_mfma_f32_16x16x32_bf16 v[116:119], v[226:229], v[174:177], v[116:119]
	v_mfma_f32_16x16x32_bf16 v[112:115], v[234:237], v[174:177], v[112:115]
	v_mfma_f32_16x16x32_bf16 v[100:103], v[226:229], v[186:189], v[100:103]
	v_mfma_f32_16x16x32_bf16 v[96:99], v[234:237], v[186:189], v[96:99]
	v_mfma_f32_16x16x32_bf16 v[84:87], v[226:229], v[194:197], v[84:87]
	v_mfma_f32_16x16x32_bf16 v[80:83], v[234:237], v[194:197], v[80:83]
	v_mfma_f32_16x16x32_bf16 v[68:71], v[226:229], v[218:221], v[68:71]
	v_mfma_f32_16x16x32_bf16 v[64:67], v[234:237], v[218:221], v[64:67]
	s_mov_b32 m0, s47
	v_lshl_add_u64 v[158:159], v[240:241], 0, s[2:3]
	s_barrier
	ds_read_b128 v[154:157], v181 offset:49152
	ds_read_b128 v[174:177], v181 offset:50176
	ds_read_b128 v[182:185], v181 offset:51200
	ds_read_b128 v[186:189], v181 offset:52224
	ds_read_b128 v[190:193], v181 offset:53248
	ds_read_b128 v[194:197], v181 offset:54272
	ds_read_b128 v[214:217], v181 offset:55296
	ds_read_b128 v[218:221], v181 offset:56320
	global_load_lds_dwordx4 v[158:159], off
	v_lshl_add_u64 v[158:159], v[242:243], 0, s[2:3]
	s_mov_b32 m0, s48
	s_nop 0
	global_load_lds_dwordx4 v[158:159], off
	s_barrier
; DEV bf16x8 pack8(f32x4 a, f32x4 b) { u32x4 w; w.x = cvt_pk_bf16(a[0], a[1]); w.y = cvt_pk_bf16(a[2], a[3]); w.z = cvt_pk_bf16(b[0], b[1]); w.w = cvt_pk_bf16(b[2], b[3]); return __builtin_bit_cast(bf16x8, w); }
; #define PG8_STAGE(bufoff, gbase, voff) do { _Pragma("unroll") for (int _i = 0; _i < 2; ++_i) \
;         __builtin_amdgcn_global_load_lds((const unsigned*)((const char*)(gbase) + (voff)[_i]), (LAS unsigned*)(lds + (bufoff) + ldsw + _i * 8192), 16, 0, 0); } while (0)
; #define PG8_BAR __builtin_amdgcn_s_barrier()
; template <class Epi>
; DEV void gemm_phase(LAS unsigned char* lds, const Gemm g, const StaticOrder& S, const Epi& E) {
;     ...
;             PG8_STAGE(PG8_SB(1, 1), b3 + hstep, voffB);
;             PG8_WAIT_V(6); PG8_BAR; PG8_MMA(1, 1, At, B1); PG8_BAR;
;         }
;     DEV void operator()(AccRef acc, const pg8::Unit& u, int wr, int wc, int fr, int fq) const {
;         const int row0 = u.pm * 256 + wr * 64 + fr, col0 = u.pn * 256 + wc * 32 + 8 * fq;
; #pragma unroll
;         for (int am = 0; am < 4; ++am) { const int ai = am >> 1, m0 = (am & 1) * 2;
;             f32x4 bv[4][2][2];
; #pragma unroll
;             for (int m = m0; m < m0 + 2; ++m)
; #pragma unroll
;                 for (int bj = 0; bj < 2; ++bj)
; #pragma unroll
;                     for (int n = 0; n < 2; ++n) bv[m][bj][n] = *(const f32x4*)(base + (size_t)(row0 + ai * 128 + m * 16) * 2048 + col0 + bj * 128 + n * 4);
; #pragma unroll
;             for (int m = m0; m < m0 + 2; ++m) { const size_t off = (size_t)(row0 + ai * 128 + m * 16) * 2048 + col0; float sq = 0.f;
; #pragma unroll
;                 for (int bj = 0; bj < 2; ++bj) { const f32x4 o0 = bv[m][bj][0] + scale * acc[ai][bj][m][0], o1 = bv[m][bj][1] + scale * acc[ai][bj][m][1];
;                     *(f32x4*)(out + off + bj * 128) = o0; *(f32x4*)(out + off + bj * 128 + 4) = o1;
;                     if (xb) { *(u32x4*)(xb + off + bj * 128) = __builtin_bit_cast(u32x4, pack8(o0, o1));
;                         sq += (o0[0] * o0[0] + o0[1] * o0[1] + o0[2] * o0[2] + o0[3] * o0[3]) + (o1[0] * o1[0] + o1[1] * o1[1] + o1[2] * o1[2] + o1[3] * o1[3]); } }
;                 if (ssout) { sq += __shfl_xor(sq, 16); sq += __shfl_xor(sq, 32);
;                     if (fq == 0) { if (red) red[(ai * 128 + wr * 64 + m * 16 + fr) * 4 + wc] = sq; else atomicAdd(ssout + (size_t)(row0 + ai * 128 + m * 16) * 8 + u.pn, sq); } } }
	s_waitcnt lgkmcnt(0)
	v_mfma_f32_16x16x32_bf16 v[60:63], v[128:131], v[154:157], v[60:63]
	v_mfma_f32_16x16x32_bf16 v[56:59], v[136:139], v[154:157], v[56:59]
	v_mfma_f32_16x16x32_bf16 v[44:47], v[128:131], v[182:185], v[44:47]
	v_mfma_f32_16x16x32_bf16 v[40:43], v[136:139], v[182:185], v[40:43]
	v_mfma_f32_16x16x32_bf16 v[28:31], v[128:131], v[190:193], v[28:31]
	v_mfma_f32_16x16x32_bf16 v[24:27], v[136:139], v[190:193], v[24:27]
	v_mfma_f32_16x16x32_bf16 v[12:15], v[128:131], v[214:217], v[12:15]
	v_mfma_f32_16x16x32_bf16 v[8:11], v[136:139], v[214:217], v[8:11]
	v_mfma_f32_16x16x32_bf16 v[60:63], v[132:135], v[174:177], v[60:63]
	v_mfma_f32_16x16x32_bf16 v[56:59], v[140:143], v[174:177], v[56:59]
	v_mfma_f32_16x16x32_bf16 v[44:47], v[132:135], v[186:189], v[44:47]
	v_mfma_f32_16x16x32_bf16 v[40:43], v[140:143], v[186:189], v[40:43]
	v_mfma_f32_16x16x32_bf16 v[28:31], v[132:135], v[194:197], v[28:31]
	v_mfma_f32_16x16x32_bf16 v[24:27], v[140:143], v[194:197], v[24:27]
	v_mfma_f32_16x16x32_bf16 v[12:15], v[132:135], v[218:221], v[12:15]
	v_mfma_f32_16x16x32_bf16 v[8:11], v[140:143], v[218:221], v[8:11]
	s_barrier
	s_add_u32 s34, s34, 0x20080
	s_addc_u32 s35, s35, 0
	s_add_i32 s36, s36, s42
	s_mov_b32 m0, s36
	s_nop 0
	global_load_lds_dwordx4 v160, s[34:35]
	s_add_i32 m0, s36, 0x2000
	s_nop 0
	global_load_lds_dwordx4 v148, s[34:35]
	s_waitcnt vmcnt(6)
	s_barrier
	v_mfma_f32_16x16x32_bf16 v[52:55], v[222:225], v[154:157], v[52:55]
	v_mfma_f32_16x16x32_bf16 v[48:51], v[230:233], v[154:157], v[48:51]
	v_mfma_f32_16x16x32_bf16 v[36:39], v[222:225], v[182:185], v[36:39]
	v_mfma_f32_16x16x32_bf16 v[32:35], v[230:233], v[182:185], v[32:35]
	v_mfma_f32_16x16x32_bf16 v[20:23], v[222:225], v[190:193], v[20:23]
	v_mfma_f32_16x16x32_bf16 v[16:19], v[230:233], v[190:193], v[16:19]
	v_mfma_f32_16x16x32_bf16 v[4:7], v[222:225], v[214:217], v[4:7]
	v_mfma_f32_16x16x32_bf16 v[0:3], v[230:233], v[214:217], v[0:3]
	v_mfma_f32_16x16x32_bf16 v[52:55], v[226:229], v[174:177], v[52:55]
	v_mfma_f32_16x16x32_bf16 v[48:51], v[234:237], v[174:177], v[48:51]
	v_mfma_f32_16x16x32_bf16 v[36:39], v[226:229], v[186:189], v[36:39]
	v_mfma_f32_16x16x32_bf16 v[32:35], v[234:237], v[186:189], v[32:35]
	v_mfma_f32_16x16x32_bf16 v[20:23], v[226:229], v[194:197], v[20:23]
	v_mfma_f32_16x16x32_bf16 v[16:19], v[234:237], v[194:197], v[16:19]
	v_mfma_f32_16x16x32_bf16 v[4:7], v[226:229], v[218:221], v[4:7]
	v_mfma_f32_16x16x32_bf16 v[0:3], v[234:237], v[218:221], v[0:3]
	s_add_i32 s54, s54, 2
	s_add_u32 s30, s30, 0x100
	s_addc_u32 s31, s31, 0
	s_add_u32 s52, s52, 0x100
	s_addc_u32 s53, s53, 0
	s_cmp_gt_u32 s54, 5
	s_barrier
	s_cbranch_scc0 .LBB0_260
	v_lshl_add_u32 v156, s28, 8, v167
	v_lshl_or_b32 v154, s18, 8, v179
	v_readlane_b32 s28, v254, 16
	v_ashrrev_i32_e32 v155, 31, v154
	v_readlane_b32 s29, v254, 17
	v_ashrrev_i32_e32 v157, 31, v156
	v_lshlrev_b64 v[128:129], 13, v[156:157]
	v_lshl_add_u64 v[158:159], v[154:155], 2, s[28:29]
	v_lshl_add_u64 v[214:215], v[158:159], 0, v[128:129]
	global_load_dwordx4 v[182:185], v[214:215], off offset:16
	global_load_dwordx4 v[186:189], v[214:215], off
	global_load_dwordx4 v[190:193], v[214:215], off offset:528
	global_load_dwordx4 v[194:197], v[214:215], off offset:512
	v_or_b32_e32 v174, 16, v156
	v_ashrrev_i32_e32 v175, 31, v174
	v_lshlrev_b64 v[128:129], 13, v[174:175]
	v_lshl_add_u64 v[176:177], v[158:159], 0, v[128:129]
	global_load_dwordx4 v[136:139], v[176:177], off offset:16
	global_load_dwordx4 v[140:143], v[176:177], off
	global_load_dwordx4 v[128:131], v[176:177], off offset:528
	global_load_dwordx4 v[132:135], v[176:177], off offset:512
	v_lshlrev_b64 v[216:217], 11, v[156:157]
	v_readlane_b32 s28, v250, 9
	v_lshl_add_u64 v[216:217], v[216:217], 0, v[154:155]
	v_readlane_b32 s29, v250, 10
	v_cmp_lt_i32_e32 vcc, v208, v206
	s_ashr_i32 s19, s18, 31
	s_waitcnt vmcnt(0)
	v_pk_add_f32 v[120:121], v[120:121], v[182:183]
	v_pk_add_f32 v[126:127], v[126:127], v[188:189]
	v_pk_add_f32 v[124:125], v[124:125], v[186:187]
	v_pk_add_f32 v[122:123], v[122:123], v[184:185]
	global_store_dwordx4 v[214:215], v[124:127], off
	global_store_dwordx4 v[214:215], v[120:123], off offset:16
	v_cvt_pk_bf16_f32 v184, v120, v121
	v_cvt_pk_bf16_f32 v182, v124, v125
	v_mul_f32_e32 v121, v121, v121
	v_cvt_pk_bf16_f32 v183, v126, v127
	v_cvt_pk_bf16_f32 v185, v122, v123
	v_lshl_add_u64 v[186:187], v[216:217], 1, s[28:29]
	v_fmac_f32_e32 v121, v120, v120
	v_pk_add_f32 v[118:119], v[118:119], v[196:197]
	v_pk_add_f32 v[116:117], v[116:117], v[194:195]
	v_pk_add_f32 v[112:113], v[112:113], v[190:191]
	global_store_dwordx4 v[186:187], v[182:185], off
	v_mul_f32_e32 v125, v125, v125
	v_fmac_f32_e32 v121, v122, v122
	v_pk_add_f32 v[114:115], v[114:115], v[192:193]
	global_store_dwordx4 v[214:215], v[116:119], off offset:512
	global_store_dwordx4 v[214:215], v[112:115], off offset:528
	v_cvt_pk_bf16_f32 v120, v116, v117
	v_cvt_pk_bf16_f32 v122, v112, v113
	v_mul_f32_e32 v117, v117, v117
	v_mul_f32_e32 v113, v113, v113
	v_fmac_f32_e32 v125, v124, v124
	v_fmac_f32_e32 v117, v116, v116
	v_fmac_f32_e32 v113, v112, v112
	v_fmac_f32_e32 v125, v126, v126
	v_fmac_f32_e32 v117, v118, v118
	v_fmac_f32_e32 v113, v114, v114
	v_fmac_f32_e32 v125, v127, v127
	v_fmac_f32_e32 v121, v123, v123
	v_fmac_f32_e32 v117, v119, v119
	v_fmac_f32_e32 v113, v115, v115
	v_add_f32_e32 v124, v125, v121
	v_add_f32_e32 v112, v117, v113
	v_cndmask_b32_e32 v113, v204, v208, vcc
	v_cvt_pk_bf16_f32 v121, v118, v119
	v_add_f32_e32 v112, v124, v112
	v_lshlrev_b32_e32 v118, 2, v113
	ds_bpermute_b32 v113, v118, v112
	v_cmp_lt_i32_e32 vcc, v207, v206
	v_cvt_pk_bf16_f32 v123, v114, v115
	global_store_dwordx4 v[186:187], v[120:123], off offset:256
	s_waitcnt lgkmcnt(0)
	v_add_f32_e32 v112, v112, v113
	v_cndmask_b32_e32 v113, v204, v207, vcc
	v_lshlrev_b32_e32 v119, 2, v113
	ds_bpermute_b32 v113, v119, v112
	s_and_saveexec_b64 s[28:29], s[6:7]
	s_cbranch_execz .LBB0_266
	s_waitcnt lgkmcnt(0)
	v_add_f32_e32 v112, v112, v113
	s_mov_b64 s[30:31], -1
	s_and_b64 vcc, exec, s[16:17]
	s_cbranch_vccz .LBB0_264
	v_lshlrev_b64 v[114:115], 5, v[156:157]
	v_lshl_add_u64 v[114:115], s[12:13], 0, v[114:115]
	v_lshl_add_u64 v[114:115], s[18:19], 2, v[114:115]
	global_atomic_add_f32 v[114:115], v112, off
	s_mov_b64 s[30:31], 0

; #define PG8_STAGE(bufoff, gbase, voff) do { _Pragma("unroll") for (int _i = 0; _i < 2; ++_i) \
;         __builtin_amdgcn_global_load_lds((const unsigned*)((const char*)(gbase) + (voff)[_i]), (LAS unsigned*)(lds + (bufoff) + ldsw + _i * 8192), 16, 0, 0); } while (0)
; #define PG8_LDA(dst, b, h) do { _Pragma("unroll") for (int m = 0; m < 4; ++m) _Pragma("unroll") for (int k = 0; k < 2; ++k) dst[m][k] = *(const LAS bf16x8*)(lds + PG8_SA(b, h) + aoff + m * 2048 + k * 1024); } while (0)
; #define PG8_LDB(dst, b, h) do { _Pragma("unroll") for (int n = 0; n < 2; ++n) _Pragma("unroll") for (int k = 0; k < 2; ++k) dst[n][k] = *(const LAS bf16x8*)(lds + PG8_SB(b, h) + boff + n * 2048 + k * 1024); } while (0)
; #define PG8_MMA(ai, bj, At, Bt) do { __builtin_amdgcn_s_setprio(1); _Pragma("unroll") for (int m = 0; m < 4; ++m) _Pragma("unroll") for (int n = 0; n < 2; ++n) _Pragma("unroll") for (int k = 0; k < 2; ++k) \
;         acc[ai][bj][m][n] = __builtin_amdgcn_mfma_f32_16x16x32_bf16(Bt[n][k], At[m][k], acc[ai][bj][m][n], 0, 0, 0); __builtin_amdgcn_s_setprio(0); } while (0)
; #define PG8_WAIT_V(n) asm volatile("s_waitcnt vmcnt(" #n ")" ::: "memory")
; #define PG8_WAIT_L(n) asm volatile("s_waitcnt lgkmcnt(" #n ")" ::: "memory")
; #define PG8_BAR __builtin_amdgcn_s_barrier()
; template <class Epi>
; DEV void gemm_phase(LAS unsigned char* lds, const Gemm g, const StaticOrder& S, const Epi& E) {
;     ...
;         for (int t = 0; t < nt; t += 2) {
;             const bool last = (t == nt - 2);
;             const char* a1 = cA + (size_t)(t + 1) * kstep;
;             const char* a2 = last ? nA : cA + (size_t)(t + 2) * kstep; const char* b2 = last ? nB : cB + (size_t)(t + 2) * kstep;
;             const char* a3 = a2 + kstep; const char* b3 = b2 + kstep;
;             PG8_LDB(B0, 0, 0); PG8_SCHED; PG8_LDA(At, 0, 0); PG8_STAGE(PG8_SA(1, 1), a1 + hstep, voffA);
;             PG8_WAIT_L(8); PG8_BAR; PG8_WAIT_L(0); PG8_MMA(0, 0, At, B0); PG8_BAR; PG8_SCHED;
;             PG8_LDB(B1, 0, 1); PG8_STAGE(PG8_SB(0, 0), b2, voffB);
;             PG8_BAR; PG8_WAIT_L(0); PG8_MMA(0, 1, At, B1); PG8_BAR;
;             PG8_LDA(At, 0, 1); PG8_STAGE(PG8_SA(0, 0), a2, voffA);
;             PG8_BAR; PG8_WAIT_L(0); PG8_MMA(1, 0, At, B0); PG8_BAR; PG8_SCHED;
;             PG8_STAGE(PG8_SB(0, 1), b2 + hstep, voffB);
;             PG8_WAIT_V(6); PG8_BAR; PG8_MMA(1, 1, At, B1); PG8_BAR;
.LBB0_344:
	s_add_u32 s20, s18, 0xfff80080
	s_addc_u32 s21, s19, -1
	s_add_i32 s45, 0, 0x10000
	v_add_u32_e32 v146, s45, v149
	ds_read_b128 v[128:131], v146
	ds_read_b128 v[132:135], v146 offset:1024
	ds_read_b128 v[142:145], v146 offset:2048
	ds_read_b128 v[150:153], v146 offset:3072
	s_cmp_eq_u32 s44, 28
	s_cselect_b32 s23, s1, s21
	s_cselect_b32 s22, s13, s20
	s_cselect_b32 s21, s11, s43
	s_cselect_b32 s20, s41, s42
	s_add_i32 m0, s30, 0xc000
	ds_read_b128 v[174:177], v159
	ds_read_b128 v[178:181], v159 offset:1024
	ds_read_b128 v[182:185], v159 offset:2048
	ds_read_b128 v[186:189], v159 offset:3072
	ds_read_b128 v[190:193], v159 offset:4096
	ds_read_b128 v[194:197], v159 offset:5120
	ds_read_b128 v[214:217], v159 offset:6144
	ds_read_b128 v[218:221], v159 offset:7168
	global_load_lds_dwordx4 v138, s[18:19]
	s_add_i32 m0, s30, 0xe000
	s_nop 0
	global_load_lds_dwordx4 v140, s[18:19]
	s_waitcnt lgkmcnt(8)
	s_barrier
	s_waitcnt lgkmcnt(0)
	v_mfma_f32_16x16x32_bf16 v[124:127], v[128:131], v[174:177], v[124:127]
	v_mfma_f32_16x16x32_bf16 v[120:123], v[142:145], v[174:177], v[120:123]
	v_mfma_f32_16x16x32_bf16 v[116:119], v[128:131], v[182:185], v[116:119]
	v_mfma_f32_16x16x32_bf16 v[108:111], v[142:145], v[182:185], v[108:111]
	v_mfma_f32_16x16x32_bf16 v[100:103], v[128:131], v[190:193], v[100:103]
	v_mfma_f32_16x16x32_bf16 v[92:95], v[142:145], v[190:193], v[92:95]
	v_mfma_f32_16x16x32_bf16 v[84:87], v[128:131], v[214:217], v[84:87]
	v_mfma_f32_16x16x32_bf16 v[76:79], v[142:145], v[214:217], v[76:79]
	v_mfma_f32_16x16x32_bf16 v[124:127], v[132:135], v[178:181], v[124:127]
	v_mfma_f32_16x16x32_bf16 v[120:123], v[150:153], v[178:181], v[120:123]
	v_mfma_f32_16x16x32_bf16 v[116:119], v[132:135], v[186:189], v[116:119]
	v_mfma_f32_16x16x32_bf16 v[108:111], v[150:153], v[186:189], v[108:111]
	v_mfma_f32_16x16x32_bf16 v[100:103], v[132:135], v[194:197], v[100:103]
	v_mfma_f32_16x16x32_bf16 v[92:95], v[150:153], v[194:197], v[92:95]
	v_mfma_f32_16x16x32_bf16 v[84:87], v[132:135], v[218:221], v[84:87]
	v_mfma_f32_16x16x32_bf16 v[76:79], v[150:153], v[218:221], v[76:79]
	s_barrier
	s_add_i32 s48, 0, 0x14000
	s_add_i32 s45, s45, s29
	v_add_u32_e32 v146, s48, v149
	s_mov_b32 m0, s45
	ds_read_b128 v[222:225], v146
	ds_read_b128 v[226:229], v146 offset:1024
	ds_read_b128 v[230:233], v146 offset:2048
	ds_read_b128 v[234:237], v146 offset:3072
	global_load_lds_dwordx4 v160, s[20:21]
	s_add_i32 m0, s45, 0x2000
	s_nop 0
	global_load_lds_dwordx4 v136, s[20:21]
	s_barrier
	s_waitcnt lgkmcnt(0)
	v_mfma_f32_16x16x32_bf16 v[112:115], v[222:225], v[174:177], v[112:115]
	v_mfma_f32_16x16x32_bf16 v[104:107], v[230:233], v[174:177], v[104:107]
	v_mfma_f32_16x16x32_bf16 v[96:99], v[222:225], v[182:185], v[96:99]
	v_mfma_f32_16x16x32_bf16 v[88:91], v[230:233], v[182:185], v[88:91]
	v_mfma_f32_16x16x32_bf16 v[80:83], v[222:225], v[190:193], v[80:83]
	v_mfma_f32_16x16x32_bf16 v[72:75], v[230:233], v[190:193], v[72:75]
	v_mfma_f32_16x16x32_bf16 v[68:71], v[222:225], v[214:217], v[68:71]
	v_mfma_f32_16x16x32_bf16 v[64:67], v[230:233], v[214:217], v[64:67]
	v_mfma_f32_16x16x32_bf16 v[112:115], v[226:229], v[178:181], v[112:115]
	v_mfma_f32_16x16x32_bf16 v[104:107], v[234:237], v[178:181], v[104:107]
	v_mfma_f32_16x16x32_bf16 v[96:99], v[226:229], v[186:189], v[96:99]
	v_mfma_f32_16x16x32_bf16 v[88:91], v[234:237], v[186:189], v[88:91]
	v_mfma_f32_16x16x32_bf16 v[80:83], v[226:229], v[194:197], v[80:83]
	v_mfma_f32_16x16x32_bf16 v[72:75], v[234:237], v[194:197], v[72:75]
	v_mfma_f32_16x16x32_bf16 v[68:71], v[226:229], v[218:221], v[68:71]
	v_mfma_f32_16x16x32_bf16 v[64:67], v[234:237], v[218:221], v[64:67]
	s_mov_b32 m0, s30
	v_lshl_add_u64 v[240:241], s[22:23], 0, v[160:161]
	s_barrier
	ds_read_b128 v[174:177], v159 offset:16384
	ds_read_b128 v[178:181], v159 offset:17408
	ds_read_b128 v[182:185], v159 offset:18432
	ds_read_b128 v[186:189], v159 offset:19456
	ds_read_b128 v[190:193], v159 offset:20480
	ds_read_b128 v[194:197], v159 offset:21504
	ds_read_b128 v[214:217], v159 offset:22528
	ds_read_b128 v[218:221], v159 offset:23552
	global_load_lds_dwordx4 v160, s[22:23]
	v_lshl_add_u64 v[242:243], s[22:23], 0, v[136:137]
	s_mov_b32 m0, s31
	s_nop 0
	global_load_lds_dwordx4 v136, s[22:23]
	s_barrier
	s_waitcnt lgkmcnt(0)
	v_mfma_f32_16x16x32_bf16 v[60:63], v[128:131], v[174:177], v[60:63]
	v_mfma_f32_16x16x32_bf16 v[56:59], v[142:145], v[174:177], v[56:59]
	v_mfma_f32_16x16x32_bf16 v[52:55], v[128:131], v[182:185], v[52:55]
	v_mfma_f32_16x16x32_bf16 v[44:47], v[142:145], v[182:185], v[44:47]
	v_mfma_f32_16x16x32_bf16 v[36:39], v[128:131], v[190:193], v[36:39]
	v_mfma_f32_16x16x32_bf16 v[28:31], v[142:145], v[190:193], v[28:31]
	v_mfma_f32_16x16x32_bf16 v[20:23], v[128:131], v[214:217], v[20:23]
	v_mfma_f32_16x16x32_bf16 v[12:15], v[142:145], v[214:217], v[12:15]
	v_mfma_f32_16x16x32_bf16 v[60:63], v[132:135], v[178:181], v[60:63]
	v_mfma_f32_16x16x32_bf16 v[56:59], v[150:153], v[178:181], v[56:59]
	v_mfma_f32_16x16x32_bf16 v[52:55], v[132:135], v[186:189], v[52:55]
	v_mfma_f32_16x16x32_bf16 v[44:47], v[150:153], v[186:189], v[44:47]
	v_mfma_f32_16x16x32_bf16 v[36:39], v[132:135], v[194:197], v[36:39]
	v_mfma_f32_16x16x32_bf16 v[28:31], v[150:153], v[194:197], v[28:31]
	v_mfma_f32_16x16x32_bf16 v[20:23], v[132:135], v[218:221], v[20:23]
	v_mfma_f32_16x16x32_bf16 v[12:15], v[150:153], v[218:221], v[12:15]
	s_barrier
	s_add_u32 s46, s20, 0x80000
	s_addc_u32 s47, s21, 0
	s_add_i32 s45, s48, s29
	s_mov_b32 m0, s45
	s_nop 0
	global_load_lds_dwordx4 v160, s[46:47]
	s_add_i32 m0, s45, 0x2000
	s_nop 0
	global_load_lds_dwordx4 v136, s[46:47]
	s_waitcnt vmcnt(6)
	s_barrier
; #define PG8_STAGE(bufoff, gbase, voff) do { _Pragma("unroll") for (int _i = 0; _i < 2; ++_i) \
;         __builtin_amdgcn_global_load_lds((const unsigned*)((const char*)(gbase) + (voff)[_i]), (LAS unsigned*)(lds + (bufoff) + ldsw + _i * 8192), 16, 0, 0); } while (0)
; #define PG8_LDA(dst, b, h) do { _Pragma("unroll") for (int m = 0; m < 4; ++m) _Pragma("unroll") for (int k = 0; k < 2; ++k) dst[m][k] = *(const LAS bf16x8*)(lds + PG8_SA(b, h) + aoff + m * 2048 + k * 1024); } while (0)
; #define PG8_LDB(dst, b, h) do { _Pragma("unroll") for (int n = 0; n < 2; ++n) _Pragma("unroll") for (int k = 0; k < 2; ++k) dst[n][k] = *(const LAS bf16x8*)(lds + PG8_SB(b, h) + boff + n * 2048 + k * 1024); } while (0)
; #define PG8_MMA(ai, bj, At, Bt) do { __builtin_amdgcn_s_setprio(1); _Pragma("unroll") for (int m = 0; m < 4; ++m) _Pragma("unroll") for (int n = 0; n < 2; ++n) _Pragma("unroll") for (int k = 0; k < 2; ++k) \
;         acc[ai][bj][m][n] = __builtin_amdgcn_mfma_f32_16x16x32_bf16(Bt[n][k], At[m][k], acc[ai][bj][m][n], 0, 0, 0); __builtin_amdgcn_s_setprio(0); } while (0)
; #define PG8_WAIT_V(n) asm volatile("s_waitcnt vmcnt(" #n ")" ::: "memory")
; #define PG8_WAIT_L(n) asm volatile("s_waitcnt lgkmcnt(" #n ")" ::: "memory")
; #define PG8_BAR __builtin_amdgcn_s_barrier()
; #define PG8_SCHED __builtin_amdgcn_sched_barrier(0)
; template <class Epi>
; DEV void gemm_phase(LAS unsigned char* lds, const Gemm g, const StaticOrder& S, const Epi& E) {
;     ...
;             PG8_WAIT_V(6); PG8_BAR; PG8_MMA(1, 1, At, B1); PG8_BAR;
;             PG8_LDB(B0, 1, 0); PG8_SCHED; PG8_LDA(At, 1, 0); PG8_STAGE(PG8_SA(0, 1), a2 + hstep, voffA);
;             PG8_WAIT_L(8); PG8_BAR; PG8_WAIT_L(0); PG8_MMA(0, 0, At, B0); PG8_BAR; PG8_SCHED;
;             PG8_LDB(B1, 1, 1); PG8_STAGE(PG8_SB(1, 0), b3, voffB);
;             PG8_BAR; PG8_WAIT_L(0); PG8_MMA(0, 1, At, B1); PG8_BAR;
;             PG8_LDA(At, 1, 1); PG8_STAGE(PG8_SA(1, 0), a3, voffA);
;             PG8_BAR; PG8_WAIT_L(0); PG8_MMA(1, 0, At, B0); PG8_BAR; PG8_SCHED;
;             PG8_STAGE(PG8_SB(1, 1), b3 + hstep, voffB);
	v_mfma_f32_16x16x32_bf16 v[48:51], v[222:225], v[174:177], v[48:51]
	v_mfma_f32_16x16x32_bf16 v[40:43], v[230:233], v[174:177], v[40:43]
	v_mfma_f32_16x16x32_bf16 v[32:35], v[222:225], v[182:185], v[32:35]
	v_mfma_f32_16x16x32_bf16 v[24:27], v[230:233], v[182:185], v[24:27]
	v_mfma_f32_16x16x32_bf16 v[16:19], v[222:225], v[190:193], v[16:19]
	v_mfma_f32_16x16x32_bf16 v[8:11], v[230:233], v[190:193], v[8:11]
	v_mfma_f32_16x16x32_bf16 v[4:7], v[222:225], v[214:217], v[4:7]
	v_mfma_f32_16x16x32_bf16 v[0:3], v[230:233], v[214:217], v[0:3]
	v_mfma_f32_16x16x32_bf16 v[48:51], v[226:229], v[178:181], v[48:51]
	v_mfma_f32_16x16x32_bf16 v[40:43], v[234:237], v[178:181], v[40:43]
	v_mfma_f32_16x16x32_bf16 v[32:35], v[226:229], v[186:189], v[32:35]
	v_mfma_f32_16x16x32_bf16 v[24:27], v[234:237], v[186:189], v[24:27]
	v_mfma_f32_16x16x32_bf16 v[16:19], v[226:229], v[194:197], v[16:19]
	v_mfma_f32_16x16x32_bf16 v[8:11], v[234:237], v[194:197], v[8:11]
	v_mfma_f32_16x16x32_bf16 v[4:7], v[226:229], v[218:221], v[4:7]
	v_mfma_f32_16x16x32_bf16 v[0:3], v[234:237], v[218:221], v[0:3]
	s_add_i32 s45, 0, 0x18000
	v_add_u32_e32 v146, s45, v149
	s_barrier
	ds_read_b128 v[128:131], v146
	ds_read_b128 v[132:135], v146 offset:1024
	ds_read_b128 v[142:145], v146 offset:2048
	ds_read_b128 v[150:153], v146 offset:3072
	s_add_u32 s22, s22, 0x80000
	s_addc_u32 s23, s23, 0
	s_mov_b32 m0, s34
	ds_read_b128 v[174:177], v159 offset:32768
	ds_read_b128 v[178:181], v159 offset:33792
	ds_read_b128 v[182:185], v159 offset:34816
	ds_read_b128 v[186:189], v159 offset:35840
	ds_read_b128 v[190:193], v159 offset:36864
	ds_read_b128 v[194:197], v159 offset:37888
	ds_read_b128 v[214:217], v159 offset:38912
	ds_read_b128 v[218:221], v159 offset:39936
	global_load_lds_dwordx4 v160, s[22:23]
	s_mov_b32 m0, s35
	s_nop 0
	global_load_lds_dwordx4 v136, s[22:23]
	s_waitcnt lgkmcnt(8)
	s_barrier
	s_waitcnt lgkmcnt(0)
	v_mfma_f32_16x16x32_bf16 v[124:127], v[128:131], v[174:177], v[124:127]
	v_mfma_f32_16x16x32_bf16 v[120:123], v[142:145], v[174:177], v[120:123]
	v_mfma_f32_16x16x32_bf16 v[116:119], v[128:131], v[182:185], v[116:119]
	v_mfma_f32_16x16x32_bf16 v[108:111], v[142:145], v[182:185], v[108:111]
	v_mfma_f32_16x16x32_bf16 v[100:103], v[128:131], v[190:193], v[100:103]
	v_mfma_f32_16x16x32_bf16 v[92:95], v[142:145], v[190:193], v[92:95]
	v_mfma_f32_16x16x32_bf16 v[84:87], v[128:131], v[214:217], v[84:87]
	v_mfma_f32_16x16x32_bf16 v[76:79], v[142:145], v[214:217], v[76:79]
	v_mfma_f32_16x16x32_bf16 v[124:127], v[132:135], v[178:181], v[124:127]
	v_mfma_f32_16x16x32_bf16 v[120:123], v[150:153], v[178:181], v[120:123]
	v_mfma_f32_16x16x32_bf16 v[116:119], v[132:135], v[186:189], v[116:119]
	v_mfma_f32_16x16x32_bf16 v[108:111], v[150:153], v[186:189], v[108:111]
	v_mfma_f32_16x16x32_bf16 v[100:103], v[132:135], v[194:197], v[100:103]
	v_mfma_f32_16x16x32_bf16 v[92:95], v[150:153], v[194:197], v[92:95]
	v_mfma_f32_16x16x32_bf16 v[84:87], v[132:135], v[218:221], v[84:87]
	v_mfma_f32_16x16x32_bf16 v[76:79], v[150:153], v[218:221], v[76:79]
	s_barrier
	s_add_i32 s22, 0, 0x1c000
	s_add_i32 s23, s45, s29
	v_add_u32_e32 v146, s22, v149
	s_add_u32 s100, s20, 0x80
	s_addc_u32 s101, s21, 0
	s_mov_b32 m0, s23
	ds_read_b128 v[222:225], v146
	ds_read_b128 v[226:229], v146 offset:1024
	ds_read_b128 v[230:233], v146 offset:2048
	ds_read_b128 v[234:237], v146 offset:3072
	global_load_lds_dwordx4 v160, s[100:101]
	s_add_i32 m0, s23, 0x2000
	s_nop 0
	global_load_lds_dwordx4 v136, s[100:101]
	s_barrier
	s_waitcnt lgkmcnt(0)
	v_mfma_f32_16x16x32_bf16 v[112:115], v[222:225], v[174:177], v[112:115]
	v_mfma_f32_16x16x32_bf16 v[104:107], v[230:233], v[174:177], v[104:107]
	v_mfma_f32_16x16x32_bf16 v[96:99], v[222:225], v[182:185], v[96:99]
	v_mfma_f32_16x16x32_bf16 v[88:91], v[230:233], v[182:185], v[88:91]
	v_mfma_f32_16x16x32_bf16 v[80:83], v[222:225], v[190:193], v[80:83]
	v_mfma_f32_16x16x32_bf16 v[72:75], v[230:233], v[190:193], v[72:75]
	v_mfma_f32_16x16x32_bf16 v[68:71], v[222:225], v[214:217], v[68:71]
	v_mfma_f32_16x16x32_bf16 v[64:67], v[230:233], v[214:217], v[64:67]
	v_mfma_f32_16x16x32_bf16 v[112:115], v[226:229], v[178:181], v[112:115]
	v_mfma_f32_16x16x32_bf16 v[104:107], v[234:237], v[178:181], v[104:107]
	v_mfma_f32_16x16x32_bf16 v[96:99], v[226:229], v[186:189], v[96:99]
	v_mfma_f32_16x16x32_bf16 v[88:91], v[234:237], v[186:189], v[88:91]
	v_mfma_f32_16x16x32_bf16 v[80:83], v[226:229], v[194:197], v[80:83]
	v_mfma_f32_16x16x32_bf16 v[72:75], v[234:237], v[194:197], v[72:75]
	v_mfma_f32_16x16x32_bf16 v[68:71], v[226:229], v[218:221], v[68:71]
	v_mfma_f32_16x16x32_bf16 v[64:67], v[234:237], v[218:221], v[64:67]
	s_mov_b32 m0, s37
	v_lshl_add_u64 v[154:155], v[240:241], 0, s[2:3]
	s_barrier
	ds_read_b128 v[174:177], v159 offset:49152
	ds_read_b128 v[178:181], v159 offset:50176
	ds_read_b128 v[182:185], v159 offset:51200
	ds_read_b128 v[186:189], v159 offset:52224
	ds_read_b128 v[190:193], v159 offset:53248
	ds_read_b128 v[194:197], v159 offset:54272
	ds_read_b128 v[214:217], v159 offset:55296
	ds_read_b128 v[218:221], v159 offset:56320
	global_load_lds_dwordx4 v[154:155], off
	v_lshl_add_u64 v[154:155], v[242:243], 0, s[2:3]
	s_mov_b32 m0, s38
	s_nop 0
	global_load_lds_dwordx4 v[154:155], off
	s_barrier
; DEV bf16x8 pack8(f32x4 a, f32x4 b) { u32x4 w; w.x = cvt_pk_bf16(a[0], a[1]); w.y = cvt_pk_bf16(a[2], a[3]); w.z = cvt_pk_bf16(b[0], b[1]); w.w = cvt_pk_bf16(b[2], b[3]); return __builtin_bit_cast(bf16x8, w); }
; DEV u32x2 pack4(f32x4 a) { u32x2 w; w.x = cvt_pk_bf16(a[0], a[1]); w.y = cvt_pk_bf16(a[2], a[3]); return w; }
; DEV f32x4 gelu4(f32x4 v) { f32x2 a = gelu_pk((f32x2){v[0], v[1]}), b = gelu_pk((f32x2){v[2], v[3]}); return (f32x4){a.x, a.y, b.x, b.y}; }
; DEV float rowscale(const float* ss, int row) { const f32x4 a = *(const f32x4*)(ss + (size_t)row * 8), b = *(const f32x4*)(ss + (size_t)row * 8 + 4);
;     return rsqrtf(((a[0] + a[1]) + (a[2] + a[3]) + (b[0] + b[1]) + (b[2] + b[3])) * (1.0f / 2048.0f) + EPS); }
; template <int ACT, bool PERM>
; DEV void store_bf16_tile(AccRef acc, u16* O, int ld, int row0, int col0, const float* ss) {
;     float rsv[2][4];
; #pragma unroll
;     for (int ai = 0; ai < 2; ++ai)
; #pragma unroll
;         for (int m = 0; m < 4; ++m) rsv[ai][m] = ss ? rowscale(ss, row0 + ai * 128 + m * 16) : 1.0f;
; #pragma unroll
;     for (int ai = 0; ai < 2; ++ai)
; #pragma unroll
;         for (int m = 0; m < 4; ++m) { u16* rowp = O + (size_t)(row0 + ai * 128 + m * 16) * ld + col0; const float rs = rsv[ai][m];
; #pragma unroll
;             for (int bj = 0; bj < 2; ++bj) { f32x4 v0 = acc[ai][bj][m][0] * rs, v1 = acc[ai][bj][m][1] * rs; if (ACT == 1) { v0 = gelu4(v0); v1 = gelu4(v1); }
;                 if (PERM) *(u32x4*)(rowp + bj * 128) = __builtin_bit_cast(u32x4, pack8(v0, v1));
;                 else { *(u32x2*)(rowp + bj * 128) = pack4(v0); *(u32x2*)(rowp + bj * 128 + 16) = pack4(v1); } } }
	s_waitcnt lgkmcnt(0)
	v_mfma_f32_16x16x32_bf16 v[60:63], v[128:131], v[174:177], v[60:63]
	v_mfma_f32_16x16x32_bf16 v[56:59], v[142:145], v[174:177], v[56:59]
	v_mfma_f32_16x16x32_bf16 v[52:55], v[128:131], v[182:185], v[52:55]
	v_mfma_f32_16x16x32_bf16 v[44:47], v[142:145], v[182:185], v[44:47]
	v_mfma_f32_16x16x32_bf16 v[36:39], v[128:131], v[190:193], v[36:39]
	v_mfma_f32_16x16x32_bf16 v[28:31], v[142:145], v[190:193], v[28:31]
	v_mfma_f32_16x16x32_bf16 v[20:23], v[128:131], v[214:217], v[20:23]
	v_mfma_f32_16x16x32_bf16 v[12:15], v[142:145], v[214:217], v[12:15]
	v_mfma_f32_16x16x32_bf16 v[60:63], v[132:135], v[178:181], v[60:63]
	v_mfma_f32_16x16x32_bf16 v[56:59], v[150:153], v[178:181], v[56:59]
	v_mfma_f32_16x16x32_bf16 v[52:55], v[132:135], v[186:189], v[52:55]
	v_mfma_f32_16x16x32_bf16 v[44:47], v[150:153], v[186:189], v[44:47]
	v_mfma_f32_16x16x32_bf16 v[36:39], v[132:135], v[194:197], v[36:39]
	v_mfma_f32_16x16x32_bf16 v[28:31], v[150:153], v[194:197], v[28:31]
	v_mfma_f32_16x16x32_bf16 v[20:23], v[132:135], v[218:221], v[20:23]
	v_mfma_f32_16x16x32_bf16 v[12:15], v[150:153], v[218:221], v[12:15]
	s_barrier
	s_add_u32 s20, s20, 0x80080
	s_addc_u32 s21, s21, 0
	s_add_i32 s22, s22, s29
	s_mov_b32 m0, s22
	s_nop 0
	global_load_lds_dwordx4 v160, s[20:21]
	s_add_i32 m0, s22, 0x2000
	s_nop 0
	global_load_lds_dwordx4 v136, s[20:21]
	s_waitcnt vmcnt(6)
	s_barrier
	v_mfma_f32_16x16x32_bf16 v[48:51], v[222:225], v[174:177], v[48:51]
	v_mfma_f32_16x16x32_bf16 v[40:43], v[230:233], v[174:177], v[40:43]
	v_mfma_f32_16x16x32_bf16 v[32:35], v[222:225], v[182:185], v[32:35]
	v_mfma_f32_16x16x32_bf16 v[24:27], v[230:233], v[182:185], v[24:27]
	v_mfma_f32_16x16x32_bf16 v[16:19], v[222:225], v[190:193], v[16:19]
	v_mfma_f32_16x16x32_bf16 v[8:11], v[230:233], v[190:193], v[8:11]
	v_mfma_f32_16x16x32_bf16 v[4:7], v[222:225], v[214:217], v[4:7]
	v_mfma_f32_16x16x32_bf16 v[0:3], v[230:233], v[214:217], v[0:3]
	v_mfma_f32_16x16x32_bf16 v[48:51], v[226:229], v[178:181], v[48:51]
	v_mfma_f32_16x16x32_bf16 v[40:43], v[234:237], v[178:181], v[40:43]
	v_mfma_f32_16x16x32_bf16 v[32:35], v[226:229], v[186:189], v[32:35]
	v_mfma_f32_16x16x32_bf16 v[24:27], v[234:237], v[186:189], v[24:27]
	v_mfma_f32_16x16x32_bf16 v[16:19], v[226:229], v[194:197], v[16:19]
	v_mfma_f32_16x16x32_bf16 v[8:11], v[234:237], v[194:197], v[8:11]
	v_mfma_f32_16x16x32_bf16 v[4:7], v[226:229], v[218:221], v[4:7]
	v_mfma_f32_16x16x32_bf16 v[0:3], v[234:237], v[218:221], v[0:3]
	s_add_i32 s44, s44, 2
	s_add_u32 s18, s18, 0x100
	s_addc_u32 s19, s19, 0
	s_add_u32 s42, s42, 0x100
	s_addc_u32 s43, s43, 0
	s_cmp_gt_u32 s44, 29
	s_barrier
	s_cbranch_scc0 .LBB0_344
	v_lshl_add_u32 v142, s0, 8, v147
	v_ashrrev_i32_e32 v143, 31, v142
	v_lshlrev_b64 v[128:129], 5, v[142:143]
	v_lshl_add_u64 v[132:133], s[4:5], 0, v[128:129]
	global_load_dwordx4 v[128:131], v[132:133], off offset:16
	s_nop 0
	global_load_dwordx4 v[132:135], v[132:133], off
	s_mov_b32 s0, 0x3727c5ac
	s_mov_b32 s18, 0x3a000000
	s_mov_b32 s11, 0x800000
	s_mov_b64 s[20:21], s[16:17]
	s_waitcnt vmcnt(0)
	v_mov_b32_e32 v144, v133
	v_mov_b32_e32 v145, v134
	v_mov_b32_e32 v133, v135
	v_pk_add_f32 v[150:151], v[144:145], v[132:133]
	v_or_b32_e32 v144, 16, v142
	v_mov_b32_e32 v132, v130
	v_mov_b32_e32 v133, v128
	v_mov_b32_e32 v128, v131
	v_ashrrev_i32_e32 v145, 31, v144
	v_pk_add_f32 v[152:153], v[132:133], v[128:129]
	v_lshlrev_b64 v[128:129], 5, v[144:145]
	v_lshl_add_u64 v[132:133], s[4:5], 0, v[128:129]
	global_load_dwordx4 v[128:131], v[132:133], off offset:16
	s_nop 0
	global_load_dwordx4 v[132:135], v[132:133], off
	s_waitcnt vmcnt(0)
	v_mov_b32_e32 v154, v133
	v_mov_b32_e32 v155, v134
	v_mov_b32_e32 v133, v135
	v_pk_add_f32 v[132:133], v[154:155], v[132:133]
	v_mov_b32_e32 v134, v130
	v_mov_b32_e32 v135, v128
	v_mov_b32_e32 v128, v131
	v_pk_add_f32 v[128:129], v[134:135], v[128:129]
	v_mov_b32_e32 v130, v132
	v_mov_b32_e32 v131, v150
	v_mov_b32_e32 v150, v133
	v_pk_add_f32 v[130:131], v[130:131], v[150:151]
	v_mov_b32_e32 v132, v129
	v_mov_b32_e32 v133, v153
	v_pk_add_f32 v[130:131], v[130:131], v[132:133]
	v_mov_b32_e32 v129, v152
	v_pk_add_f32 v[128:129], v[128:129], v[130:131]
	v_mov_b64_e32 v[150:151], s[0:1]
	v_pk_fma_f32 v[128:129], v[128:129], s[18:19], v[150:151] op_sel_hi:[1,0,0]
	v_or_b32_e32 v152, 32, v142
	v_mul_f32_e32 v130, 0x4b800000, v129
	v_cmp_gt_f32_e64 s[0:1], s11, v129
	v_cmp_gt_f32_e32 vcc, s11, v128
	v_ashrrev_i32_e32 v153, 31, v152
	v_cndmask_b32_e64 v129, v129, v130, s[0:1]
	v_rsq_f32_e32 v129, v129
	s_nop 0
	v_mul_f32_e32 v130, 0x45800000, v129
	v_cndmask_b32_e64 v148, v129, v130, s[0:1]
	v_mul_f32_e32 v129, 0x4b800000, v128
	v_cndmask_b32_e32 v128, v128, v129, vcc
	v_rsq_f32_e32 v128, v128
	v_pk_mul_f32 v[106:107], v[106:107], v[148:149] op_sel_hi:[1,0]
	v_pk_mul_f32 v[104:105], v[104:105], v[148:149] op_sel_hi:[1,0]
	v_pk_mul_f32 v[114:115], v[114:115], v[148:149] op_sel_hi:[1,0]
	v_mul_f32_e32 v129, 0x45800000, v128
	v_cndmask_b32_e32 v146, v128, v129, vcc
	v_lshlrev_b64 v[128:129], 5, v[152:153]
	v_lshl_add_u64 v[132:133], s[4:5], 0, v[128:129]
	global_load_dwordx4 v[128:131], v[132:133], off offset:16
	s_nop 0
	global_load_dwordx4 v[132:135], v[132:133], off
	v_cvt_pk_bf16_f32 v104, v104, v105
	v_cvt_pk_bf16_f32 v105, v106, v107
	v_pk_mul_f32 v[90:91], v[90:91], v[146:147] op_sel_hi:[1,0]
	v_pk_mul_f32 v[88:89], v[88:89], v[146:147] op_sel_hi:[1,0]
	v_pk_mul_f32 v[112:113], v[112:113], v[148:149] op_sel_hi:[1,0]
	v_cvt_pk_bf16_f32 v88, v88, v89
	v_cvt_pk_bf16_f32 v89, v90, v91
	v_pk_mul_f32 v[98:99], v[98:99], v[146:147] op_sel_hi:[1,0]
	v_pk_mul_f32 v[96:97], v[96:97], v[146:147] op_sel_hi:[1,0]
	v_cvt_pk_bf16_f32 v112, v112, v113
	v_cvt_pk_bf16_f32 v113, v114, v115
	v_cvt_pk_bf16_f32 v96, v96, v97
	v_cvt_pk_bf16_f32 v97, v98, v99
	v_pk_mul_f32 v[126:127], v[126:127], v[148:149] op_sel_hi:[1,0]
	v_pk_mul_f32 v[124:125], v[124:125], v[148:149] op_sel_hi:[1,0]
	v_pk_mul_f32 v[122:123], v[122:123], v[148:149] op_sel_hi:[1,0]
	v_pk_mul_f32 v[120:121], v[120:121], v[148:149] op_sel_hi:[1,0]
	v_pk_mul_f32 v[106:107], v[118:119], v[146:147] op_sel_hi:[1,0]
	v_pk_mul_f32 v[110:111], v[110:111], v[146:147] op_sel_hi:[1,0]
	v_pk_mul_f32 v[108:109], v[108:109], v[146:147] op_sel_hi:[1,0]
	v_cvt_pk_bf16_f32 v124, v124, v125
	v_cvt_pk_bf16_f32 v125, v126, v127
	v_cvt_pk_bf16_f32 v120, v120, v121
	v_cvt_pk_bf16_f32 v121, v122, v123
	s_waitcnt vmcnt(0)
; DEV bf16x8 pack8(f32x4 a, f32x4 b) { u32x4 w; w.x = cvt_pk_bf16(a[0], a[1]); w.y = cvt_pk_bf16(a[2], a[3]); w.z = cvt_pk_bf16(b[0], b[1]); w.w = cvt_pk_bf16(b[2], b[3]); return __builtin_bit_cast(bf16x8, w); }
; DEV u32x2 pack4(f32x4 a) { u32x2 w; w.x = cvt_pk_bf16(a[0], a[1]); w.y = cvt_pk_bf16(a[2], a[3]); return w; }
; DEV f32x4 gelu4(f32x4 v) { f32x2 a = gelu_pk((f32x2){v[0], v[1]}), b = gelu_pk((f32x2){v[2], v[3]}); return (f32x4){a.x, a.y, b.x, b.y}; }
; DEV float rowscale(const float* ss, int row) { const f32x4 a = *(const f32x4*)(ss + (size_t)row * 8), b = *(const f32x4*)(ss + (size_t)row * 8 + 4);
;     return rsqrtf(((a[0] + a[1]) + (a[2] + a[3]) + (b[0] + b[1]) + (b[2] + b[3])) * (1.0f / 2048.0f) + EPS); }
; template <int ACT, bool PERM>
; DEV void store_bf16_tile(AccRef acc, u16* O, int ld, int row0, int col0, const float* ss) {
;     float rsv[2][4];
; #pragma unroll
;     for (int ai = 0; ai < 2; ++ai)
; #pragma unroll
;         for (int m = 0; m < 4; ++m) rsv[ai][m] = ss ? rowscale(ss, row0 + ai * 128 + m * 16) : 1.0f;
; #pragma unroll
;     for (int ai = 0; ai < 2; ++ai)
; #pragma unroll
;         for (int m = 0; m < 4; ++m) { u16* rowp = O + (size_t)(row0 + ai * 128 + m * 16) * ld + col0; const float rs = rsv[ai][m];
; #pragma unroll
;             for (int bj = 0; bj < 2; ++bj) { f32x4 v0 = acc[ai][bj][m][0] * rs, v1 = acc[ai][bj][m][1] * rs; if (ACT == 1) { v0 = gelu4(v0); v1 = gelu4(v1); }
;                 if (PERM) *(u32x4*)(rowp + bj * 128) = __builtin_bit_cast(u32x4, pack8(v0, v1));
;                 else { *(u32x2*)(rowp + bj * 128) = pack4(v0); *(u32x2*)(rowp + bj * 128 + 16) = pack4(v1); } } }
	v_mov_b32_e32 v154, v133
	v_mov_b32_e32 v155, v134
	v_mov_b32_e32 v133, v135
	v_pk_add_f32 v[174:175], v[154:155], v[132:133]
	v_or_b32_e32 v154, 48, v142
	v_mov_b32_e32 v132, v130
	v_mov_b32_e32 v133, v128
	v_mov_b32_e32 v128, v131
	v_ashrrev_i32_e32 v155, 31, v154
	v_pk_add_f32 v[176:177], v[132:133], v[128:129]
	v_lshlrev_b64 v[128:129], 5, v[154:155]
	v_lshl_add_u64 v[132:133], s[4:5], 0, v[128:129]
	global_load_dwordx4 v[128:131], v[132:133], off offset:16
	s_nop 0
	global_load_dwordx4 v[132:135], v[132:133], off
	s_waitcnt vmcnt(0)
	v_mov_b32_e32 v178, v133
	v_mov_b32_e32 v179, v134
	v_mov_b32_e32 v133, v135
	v_pk_add_f32 v[132:133], v[178:179], v[132:133]
	v_mov_b32_e32 v134, v130
	v_mov_b32_e32 v135, v128
	v_mov_b32_e32 v128, v131
	v_pk_add_f32 v[128:129], v[134:135], v[128:129]
	v_mov_b32_e32 v130, v132
	v_mov_b32_e32 v131, v174
	v_mov_b32_e32 v174, v133
	v_pk_add_f32 v[130:131], v[130:131], v[174:175]
	v_mov_b32_e32 v132, v129
	v_mov_b32_e32 v133, v177
	v_pk_add_f32 v[130:131], v[130:131], v[132:133]
	v_mov_b32_e32 v129, v176
	v_pk_add_f32 v[128:129], v[128:129], v[130:131]
	v_add_u32_e32 v174, 0x80, v142
	v_pk_fma_f32 v[128:129], v[128:129], s[18:19], v[150:151] op_sel_hi:[1,0,0]
	v_ashrrev_i32_e32 v175, 31, v174
	v_mul_f32_e32 v130, 0x4b800000, v129
	v_cmp_gt_f32_e64 s[0:1], s11, v129
	v_cmp_gt_f32_e32 vcc, s11, v128
	s_nop 0
	v_cndmask_b32_e64 v129, v129, v130, s[0:1]
	v_rsq_f32_e32 v129, v129
	s_nop 0
	v_mul_f32_e32 v130, 0x45800000, v129
	v_cndmask_b32_e64 v158, v129, v130, s[0:1]
	v_mul_f32_e32 v129, 0x4b800000, v128
	v_cndmask_b32_e32 v128, v128, v129, vcc
	v_rsq_f32_e32 v128, v128
	v_pk_mul_f32 v[74:75], v[74:75], v[158:159] op_sel_hi:[1,0]
	v_pk_mul_f32 v[72:73], v[72:73], v[158:159] op_sel_hi:[1,0]
	v_pk_mul_f32 v[82:83], v[82:83], v[158:159] op_sel_hi:[1,0]
	v_mul_f32_e32 v129, 0x45800000, v128
	v_cndmask_b32_e32 v156, v128, v129, vcc
	v_lshlrev_b64 v[128:129], 5, v[174:175]
	v_lshl_add_u64 v[132:133], s[4:5], 0, v[128:129]
	global_load_dwordx4 v[128:131], v[132:133], off offset:16
	s_nop 0
	global_load_dwordx4 v[132:135], v[132:133], off
	v_cvt_pk_bf16_f32 v72, v72, v73
	v_cvt_pk_bf16_f32 v73, v74, v75
	v_pk_mul_f32 v[66:67], v[66:67], v[156:157] op_sel_hi:[1,0]
	v_pk_mul_f32 v[64:65], v[64:65], v[156:157] op_sel_hi:[1,0]
	v_pk_mul_f32 v[80:81], v[80:81], v[158:159] op_sel_hi:[1,0]
	v_cvt_pk_bf16_f32 v64, v64, v65
	v_cvt_pk_bf16_f32 v65, v66, v67
	v_cvt_pk_bf16_f32 v80, v80, v81
	v_cvt_pk_bf16_f32 v81, v82, v83
	v_pk_mul_f32 v[90:91], v[102:103], v[158:159] op_sel_hi:[1,0]
	v_pk_mul_f32 v[94:95], v[94:95], v[158:159] op_sel_hi:[1,0]
	v_pk_mul_f32 v[92:93], v[92:93], v[158:159] op_sel_hi:[1,0]
	v_pk_mul_f32 v[74:75], v[86:87], v[156:157] op_sel_hi:[1,0]
	v_pk_mul_f32 v[78:79], v[78:79], v[156:157] op_sel_hi:[1,0]
	v_pk_mul_f32 v[76:77], v[76:77], v[156:157] op_sel_hi:[1,0]
	v_pk_mul_f32 v[70:71], v[70:71], v[156:157] op_sel_hi:[1,0]
	v_pk_mul_f32 v[68:69], v[68:69], v[156:157] op_sel_hi:[1,0]
	s_waitcnt vmcnt(0)
	v_mov_b32_e32 v176, v133
	v_mov_b32_e32 v177, v134
	v_mov_b32_e32 v133, v135
	v_pk_add_f32 v[178:179], v[176:177], v[132:133]
	v_add_u32_e32 v176, 0x90, v142
	v_mov_b32_e32 v132, v130
	v_mov_b32_e32 v133, v128
	v_mov_b32_e32 v128, v131
	v_ashrrev_i32_e32 v177, 31, v176
	v_pk_add_f32 v[180:181], v[132:133], v[128:129]
	v_lshlrev_b64 v[128:129], 5, v[176:177]
	v_lshl_add_u64 v[132:133], s[4:5], 0, v[128:129]
	global_load_dwordx4 v[128:131], v[132:133], off offset:16
	s_nop 0
	global_load_dwordx4 v[132:135], v[132:133], off
	v_cvt_pk_bf16_f32 v68, v68, v69
	v_cvt_pk_bf16_f32 v69, v70, v71
	s_waitcnt vmcnt(0)
	v_mov_b32_e32 v182, v133
	v_mov_b32_e32 v183, v134
	v_mov_b32_e32 v133, v135
	v_pk_add_f32 v[132:133], v[182:183], v[132:133]
	v_mov_b32_e32 v134, v130
	v_mov_b32_e32 v135, v128
	v_mov_b32_e32 v128, v131
	v_pk_add_f32 v[128:129], v[134:135], v[128:129]
	v_mov_b32_e32 v130, v132
	v_mov_b32_e32 v131, v178
	v_mov_b32_e32 v178, v133
	v_pk_add_f32 v[130:131], v[130:131], v[178:179]
	v_mov_b32_e32 v132, v129
	v_mov_b32_e32 v133, v181
	v_pk_add_f32 v[130:131], v[130:131], v[132:133]
	v_mov_b32_e32 v129, v180
	v_pk_add_f32 v[128:129], v[128:129], v[130:131]
	v_add_u32_e32 v182, 0xa0, v142
	v_pk_fma_f32 v[128:129], v[128:129], s[18:19], v[150:151] op_sel_hi:[1,0,0]
	v_ashrrev_i32_e32 v183, 31, v182
	v_mul_f32_e32 v130, 0x4b800000, v129
	v_cmp_gt_f32_e64 s[0:1], s11, v129
	v_cmp_gt_f32_e32 vcc, s11, v128
	s_nop 0
	v_cndmask_b32_e64 v129, v129, v130, s[0:1]
	v_rsq_f32_e32 v129, v129
	s_nop 0
	v_mul_f32_e32 v130, 0x45800000, v129
	v_cndmask_b32_e64 v180, v129, v130, s[0:1]
	v_mul_f32_e32 v129, 0x4b800000, v128
	v_cndmask_b32_e32 v128, v128, v129, vcc
	v_rsq_f32_e32 v128, v128
	v_pk_mul_f32 v[42:43], v[42:43], v[180:181] op_sel_hi:[1,0]
	v_pk_mul_f32 v[40:41], v[40:41], v[180:181] op_sel_hi:[1,0]
	v_pk_mul_f32 v[50:51], v[50:51], v[180:181] op_sel_hi:[1,0]
	v_mul_f32_e32 v129, 0x45800000, v128
	v_cndmask_b32_e32 v178, v128, v129, vcc
	v_lshlrev_b64 v[128:129], 5, v[182:183]
	v_lshl_add_u64 v[132:133], s[4:5], 0, v[128:129]
	global_load_dwordx4 v[128:131], v[132:133], off offset:16
	s_nop 0
	global_load_dwordx4 v[132:135], v[132:133], off
	v_cvt_pk_bf16_f32 v40, v40, v41
	v_cvt_pk_bf16_f32 v41, v42, v43
	v_pk_mul_f32 v[26:27], v[26:27], v[178:179] op_sel_hi:[1,0]
	v_pk_mul_f32 v[24:25], v[24:25], v[178:179] op_sel_hi:[1,0]
	v_pk_mul_f32 v[48:49], v[48:49], v[180:181] op_sel_hi:[1,0]
	v_cvt_pk_bf16_f32 v24, v24, v25
	v_cvt_pk_bf16_f32 v25, v26, v27
	v_pk_mul_f32 v[34:35], v[34:35], v[178:179] op_sel_hi:[1,0]
	v_pk_mul_f32 v[32:33], v[32:33], v[178:179] op_sel_hi:[1,0]
	v_cvt_pk_bf16_f32 v48, v48, v49
	v_cvt_pk_bf16_f32 v49, v50, v51
	v_cvt_pk_bf16_f32 v32, v32, v33
	v_cvt_pk_bf16_f32 v33, v34, v35
	v_pk_mul_f32 v[62:63], v[62:63], v[180:181] op_sel_hi:[1,0]
	v_pk_mul_f32 v[60:61], v[60:61], v[180:181] op_sel_hi:[1,0]
	v_pk_mul_f32 v[58:59], v[58:59], v[180:181] op_sel_hi:[1,0]
	v_pk_mul_f32 v[56:57], v[56:57], v[180:181] op_sel_hi:[1,0]
	v_pk_mul_f32 v[42:43], v[54:55], v[178:179] op_sel_hi:[1,0]
	v_pk_mul_f32 v[46:47], v[46:47], v[178:179] op_sel_hi:[1,0]
	v_pk_mul_f32 v[44:45], v[44:45], v[178:179] op_sel_hi:[1,0]
	v_cvt_pk_bf16_f32 v60, v60, v61
	v_cvt_pk_bf16_f32 v61, v62, v63
	v_cvt_pk_bf16_f32 v56, v56, v57
	v_cvt_pk_bf16_f32 v57, v58, v59
	s_waitcnt vmcnt(0)
; DEV bf16x8 pack8(f32x4 a, f32x4 b) { u32x4 w; w.x = cvt_pk_bf16(a[0], a[1]); w.y = cvt_pk_bf16(a[2], a[3]); w.z = cvt_pk_bf16(b[0], b[1]); w.w = cvt_pk_bf16(b[2], b[3]); return __builtin_bit_cast(bf16x8, w); }
; DEV u32x2 pack4(f32x4 a) { u32x2 w; w.x = cvt_pk_bf16(a[0], a[1]); w.y = cvt_pk_bf16(a[2], a[3]); return w; }
; DEV f32x4 gelu4(f32x4 v) { f32x2 a = gelu_pk((f32x2){v[0], v[1]}), b = gelu_pk((f32x2){v[2], v[3]}); return (f32x4){a.x, a.y, b.x, b.y}; }
; #define PG8_WAIT_V(n) asm volatile("s_waitcnt vmcnt(" #n ")" ::: "memory")
; #define PG8_BAR __builtin_amdgcn_s_barrier()
; template <class Epi>
; DEV void gemm_phase(LAS unsigned char* lds, const Gemm g, const StaticOrder& S, const Epi& E) {
;     ...
;         E(acc, cur, wr, wc, fr, fq);
;         if (!has_next) break;
; #pragma unroll
;         for (int a = 0; a < 2; ++a)
; #pragma unroll
;             for (int b = 0; b < 2; ++b)
; #pragma unroll
;                 for (int m = 0; m < 4; ++m)
; #pragma unroll
;                     for (int n = 0; n < 2; ++n) acc[a][b][m][n] = (f32x4){0.f, 0.f, 0.f, 0.f};
;         cur = nxt; cA = nA; cB = nB; ++ui;
;     }
;     PG8_WAIT_V(0);
;     if (wr == 0) PG8_BAR;
;     PG8_BAR;
; template <int ACT, bool PERM>
; DEV void store_bf16_tile(AccRef acc, u16* O, int ld, int row0, int col0, const float* ss) {
;     float rsv[2][4];
; #pragma unroll
;     for (int ai = 0; ai < 2; ++ai)
; #pragma unroll
;         for (int m = 0; m < 4; ++m) rsv[ai][m] = ss ? rowscale(ss, row0 + ai * 128 + m * 16) : 1.0f;
; #pragma unroll
;     for (int ai = 0; ai < 2; ++ai)
; #pragma unroll
;         for (int m = 0; m < 4; ++m) { u16* rowp = O + (size_t)(row0 + ai * 128 + m * 16) * ld + col0; const float rs = rsv[ai][m];
; #pragma unroll
;             for (int bj = 0; bj < 2; ++bj) { f32x4 v0 = acc[ai][bj][m][0] * rs, v1 = acc[ai][bj][m][1] * rs; if (ACT == 1) { v0 = gelu4(v0); v1 = gelu4(v1); }
;                 if (PERM) *(u32x4*)(rowp + bj * 128) = __builtin_bit_cast(u32x4, pack8(v0, v1));
;                 else { *(u32x2*)(rowp + bj * 128) = pack4(v0); *(u32x2*)(rowp + bj * 128 + 16) = pack4(v1); } } }
	v_mov_b32_e32 v184, v133
	v_mov_b32_e32 v185, v134
	v_mov_b32_e32 v133, v135
	v_pk_add_f32 v[188:189], v[184:185], v[132:133]
	v_add_u32_e32 v184, 0xb0, v142
	v_mov_b32_e32 v132, v130
	v_mov_b32_e32 v133, v128
	v_mov_b32_e32 v128, v131
	v_ashrrev_i32_e32 v185, 31, v184
	v_pk_add_f32 v[186:187], v[132:133], v[128:129]
	v_lshlrev_b64 v[128:129], 5, v[184:185]
	v_lshl_add_u64 v[132:133], s[4:5], 0, v[128:129]
	global_load_dwordx4 v[128:131], v[132:133], off offset:16
	s_nop 0
	global_load_dwordx4 v[132:135], v[132:133], off
	s_waitcnt vmcnt(0)
	v_mov_b32_e32 v190, v133
	v_mov_b32_e32 v191, v134
	v_mov_b32_e32 v133, v135
	v_pk_add_f32 v[132:133], v[190:191], v[132:133]
	v_mov_b32_e32 v134, v130
	v_mov_b32_e32 v135, v128
	v_mov_b32_e32 v128, v131
	v_pk_add_f32 v[128:129], v[134:135], v[128:129]
	v_mov_b32_e32 v130, v132
	v_mov_b32_e32 v131, v188
	v_mov_b32_e32 v188, v133
	v_pk_add_f32 v[130:131], v[130:131], v[188:189]
	v_mov_b32_e32 v132, v129
	v_mov_b32_e32 v133, v187
	v_pk_add_f32 v[130:131], v[130:131], v[132:133]
	v_mov_b32_e32 v129, v186
	v_pk_add_f32 v[128:129], v[128:129], v[130:131]
	v_lshl_or_b32 v132, s40, 8, v157
	v_pk_fma_f32 v[128:129], v[128:129], s[18:19], v[150:151] op_sel_hi:[1,0,0]
	v_ashrrev_i32_e32 v133, 31, v132
	v_mul_f32_e32 v130, 0x4b800000, v129
	v_cmp_gt_f32_e64 s[0:1], s11, v129
	v_lshlrev_b64 v[134:135], 10, v[142:143]
	v_cmp_gt_f32_e32 vcc, s11, v128
	v_cndmask_b32_e64 v129, v129, v130, s[0:1]
	v_rsq_f32_e32 v129, v129
	s_mov_b32 s40, s10
	s_mov_b64 s[18:19], s[14:15]
	v_mul_f32_e32 v130, 0x45800000, v129
	v_cndmask_b32_e64 v130, v129, v130, s[0:1]
	v_readlane_b32 s0, v250, 11
	v_readlane_b32 s1, v250, 12
	v_mul_f32_e32 v129, 0x4b800000, v128
	v_cndmask_b32_e32 v128, v128, v129, vcc
	v_lshl_add_u64 v[132:133], v[132:133], 1, s[0:1]
	v_lshl_add_u64 v[134:135], v[132:133], 0, v[134:135]
	global_store_dwordx2 v[134:135], v[104:105], off offset:288
	v_lshlrev_b64 v[104:105], 10, v[144:145]
	v_lshl_add_u64 v[104:105], v[132:133], 0, v[104:105]
	global_store_dwordx2 v[104:105], v[88:89], off offset:288
	v_lshlrev_b64 v[88:89], 10, v[152:153]
	v_lshl_add_u64 v[88:89], v[132:133], 0, v[88:89]
	global_store_dwordx2 v[88:89], v[72:73], off offset:288
	v_lshlrev_b64 v[72:73], 10, v[154:155]
	v_lshl_add_u64 v[72:73], v[132:133], 0, v[72:73]
	v_rsq_f32_e32 v128, v128
	global_store_dwordx2 v[72:73], v[64:65], off offset:288
	v_lshlrev_b64 v[64:65], 10, v[174:175]
	v_lshl_add_u64 v[64:65], v[132:133], 0, v[64:65]
	global_store_dwordx2 v[64:65], v[40:41], off offset:288
	v_lshlrev_b64 v[40:41], 10, v[176:177]
	v_lshl_add_u64 v[40:41], v[132:133], 0, v[40:41]
	v_mul_f32_e32 v129, 0x45800000, v128
	global_store_dwordx2 v[40:41], v[24:25], off offset:288
	v_lshlrev_b64 v[24:25], 10, v[182:183]
	v_pk_mul_f32 v[18:19], v[18:19], v[130:131] op_sel_hi:[1,0]
	v_pk_mul_f32 v[16:17], v[16:17], v[130:131] op_sel_hi:[1,0]
	v_pk_mul_f32 v[10:11], v[10:11], v[130:131] op_sel_hi:[1,0]
	v_pk_mul_f32 v[8:9], v[8:9], v[130:131] op_sel_hi:[1,0]
	v_cndmask_b32_e32 v128, v128, v129, vcc
	v_lshl_add_u64 v[24:25], v[132:133], 0, v[24:25]
	v_cvt_pk_bf16_f32 v16, v16, v17
	v_cvt_pk_bf16_f32 v17, v18, v19
	v_cvt_pk_bf16_f32 v8, v8, v9
	v_cvt_pk_bf16_f32 v9, v10, v11
	global_store_dwordx2 v[134:135], v[112:113], off offset:256
	v_pk_mul_f32 v[112:113], v[116:117], v[146:147] op_sel_hi:[1,0]
	global_store_dwordx2 v[104:105], v[96:97], off offset:256
	v_pk_mul_f32 v[96:97], v[100:101], v[158:159] op_sel_hi:[1,0]
	global_store_dwordx2 v[88:89], v[80:81], off offset:256
	v_pk_mul_f32 v[80:81], v[84:85], v[156:157] op_sel_hi:[1,0]
	global_store_dwordx2 v[64:65], v[48:49], off offset:256
	v_pk_mul_f32 v[48:49], v[52:53], v[178:179] op_sel_hi:[1,0]
	global_store_dwordx2 v[40:41], v[32:33], off offset:256
	v_pk_mul_f32 v[26:27], v[38:39], v[130:131] op_sel_hi:[1,0]
	v_pk_mul_f32 v[32:33], v[36:37], v[130:131] op_sel_hi:[1,0]
	v_pk_mul_f32 v[30:31], v[30:31], v[130:131] op_sel_hi:[1,0]
	v_pk_mul_f32 v[28:29], v[28:29], v[130:131] op_sel_hi:[1,0]
	global_store_dwordx2 v[24:25], v[16:17], off offset:256
	global_store_dwordx2 v[24:25], v[8:9], off offset:288
	v_lshlrev_b64 v[8:9], 10, v[184:185]
	v_pk_mul_f32 v[10:11], v[22:23], v[128:129] op_sel_hi:[1,0]
	v_pk_mul_f32 v[16:17], v[20:21], v[128:129] op_sel_hi:[1,0]
	v_pk_mul_f32 v[14:15], v[14:15], v[128:129] op_sel_hi:[1,0]
	v_pk_mul_f32 v[12:13], v[12:13], v[128:129] op_sel_hi:[1,0]
	v_pk_mul_f32 v[6:7], v[6:7], v[128:129] op_sel_hi:[1,0]
	v_pk_mul_f32 v[4:5], v[4:5], v[128:129] op_sel_hi:[1,0]
	v_pk_mul_f32 v[2:3], v[2:3], v[128:129] op_sel_hi:[1,0]
	v_pk_mul_f32 v[0:1], v[0:1], v[128:129] op_sel_hi:[1,0]
	v_cvt_pk_bf16_f32 v112, v112, v113
	v_cvt_pk_bf16_f32 v113, v106, v107
	v_cvt_pk_bf16_f32 v106, v108, v109
	v_cvt_pk_bf16_f32 v107, v110, v111
	v_cvt_pk_bf16_f32 v96, v96, v97
	v_cvt_pk_bf16_f32 v97, v90, v91
	v_cvt_pk_bf16_f32 v90, v92, v93
	v_cvt_pk_bf16_f32 v91, v94, v95
	v_cvt_pk_bf16_f32 v80, v80, v81
	v_cvt_pk_bf16_f32 v81, v74, v75
	v_cvt_pk_bf16_f32 v74, v76, v77
	v_cvt_pk_bf16_f32 v75, v78, v79
	v_cvt_pk_bf16_f32 v48, v48, v49
	v_cvt_pk_bf16_f32 v49, v42, v43
	v_cvt_pk_bf16_f32 v42, v44, v45
	v_cvt_pk_bf16_f32 v43, v46, v47
	v_cvt_pk_bf16_f32 v32, v32, v33
	v_cvt_pk_bf16_f32 v33, v26, v27
	v_cvt_pk_bf16_f32 v26, v28, v29
	v_cvt_pk_bf16_f32 v27, v30, v31
	v_lshl_add_u64 v[8:9], v[132:133], 0, v[8:9]
	v_cvt_pk_bf16_f32 v16, v16, v17
	v_cvt_pk_bf16_f32 v17, v10, v11
	v_cvt_pk_bf16_f32 v10, v12, v13
	v_cvt_pk_bf16_f32 v11, v14, v15
	v_cvt_pk_bf16_f32 v4, v4, v5
	v_cvt_pk_bf16_f32 v5, v6, v7
	v_cvt_pk_bf16_f32 v0, v0, v1
	v_cvt_pk_bf16_f32 v1, v2, v3
	s_and_b64 vcc, exec, s[6:7]
	s_mov_b32 s0, s12
	global_store_dwordx2 v[134:135], v[124:125], off
	global_store_dwordx2 v[134:135], v[120:121], off offset:32
	global_store_dwordx2 v[104:105], v[112:113], off
	global_store_dwordx2 v[104:105], v[106:107], off offset:32
	global_store_dwordx2 v[88:89], v[96:97], off
	global_store_dwordx2 v[88:89], v[90:91], off offset:32
	global_store_dwordx2 v[72:73], v[80:81], off
	global_store_dwordx2 v[72:73], v[74:75], off offset:32
	global_store_dwordx2 v[72:73], v[68:69], off offset:256
	global_store_dwordx2 v[64:65], v[60:61], off
	global_store_dwordx2 v[64:65], v[56:57], off offset:32
	global_store_dwordx2 v[40:41], v[48:49], off
	global_store_dwordx2 v[40:41], v[42:43], off offset:32
	global_store_dwordx2 v[24:25], v[32:33], off
	global_store_dwordx2 v[24:25], v[26:27], off offset:32
	global_store_dwordx2 v[8:9], v[16:17], off
	global_store_dwordx2 v[8:9], v[10:11], off offset:32
	global_store_dwordx2 v[8:9], v[4:5], off offset:256
	global_store_dwordx2 v[8:9], v[0:1], off offset:288
	s_cbranch_vccz .LBB0_337
	s_waitcnt vmcnt(0)
	s_cmpk_gt_u32 s25, 0xff
	s_cbranch_scc1 .LBB0_348
	s_barrier

; #define PG8_STAGE(bufoff, gbase, voff) do { _Pragma("unroll") for (int _i = 0; _i < 2; ++_i) \
;         __builtin_amdgcn_global_load_lds((const unsigned*)((const char*)(gbase) + (voff)[_i]), (LAS unsigned*)(lds + (bufoff) + ldsw + _i * 8192), 16, 0, 0); } while (0)
; #define PG8_LDA(dst, b, h) do { _Pragma("unroll") for (int m = 0; m < 4; ++m) _Pragma("unroll") for (int k = 0; k < 2; ++k) dst[m][k] = *(const LAS bf16x8*)(lds + PG8_SA(b, h) + aoff + m * 2048 + k * 1024); } while (0)
; #define PG8_LDB(dst, b, h) do { _Pragma("unroll") for (int n = 0; n < 2; ++n) _Pragma("unroll") for (int k = 0; k < 2; ++k) dst[n][k] = *(const LAS bf16x8*)(lds + PG8_SB(b, h) + boff + n * 2048 + k * 1024); } while (0)
; #define PG8_MMA(ai, bj, At, Bt) do { __builtin_amdgcn_s_setprio(1); _Pragma("unroll") for (int m = 0; m < 4; ++m) _Pragma("unroll") for (int n = 0; n < 2; ++n) _Pragma("unroll") for (int k = 0; k < 2; ++k) \
;         acc[ai][bj][m][n] = __builtin_amdgcn_mfma_f32_16x16x32_bf16(Bt[n][k], At[m][k], acc[ai][bj][m][n], 0, 0, 0); __builtin_amdgcn_s_setprio(0); } while (0)
; #define PG8_WAIT_V(n) asm volatile("s_waitcnt vmcnt(" #n ")" ::: "memory")
; #define PG8_WAIT_L(n) asm volatile("s_waitcnt lgkmcnt(" #n ")" ::: "memory")
; #define PG8_BAR __builtin_amdgcn_s_barrier()
; #define PG8_SCHED __builtin_amdgcn_sched_barrier(0)
; template <class Epi>
; DEV void gemm_phase(LAS unsigned char* lds, const Gemm g, const StaticOrder& S, const Epi& E) {
;     ...
;             const bool last = (t == nt - 2);
;             const char* a1 = cA + (size_t)(t + 1) * kstep;
;             const char* a2 = last ? nA : cA + (size_t)(t + 2) * kstep; const char* b2 = last ? nB : cB + (size_t)(t + 2) * kstep;
;             const char* a3 = a2 + kstep; const char* b3 = b2 + kstep;
;             PG8_LDB(B0, 0, 0); PG8_SCHED; PG8_LDA(At, 0, 0); PG8_STAGE(PG8_SA(1, 1), a1 + hstep, voffA);
;             PG8_WAIT_L(8); PG8_BAR; PG8_WAIT_L(0); PG8_MMA(0, 0, At, B0); PG8_BAR; PG8_SCHED;
;             PG8_LDB(B1, 0, 1); PG8_STAGE(PG8_SB(0, 0), b2, voffB);
;             PG8_BAR; PG8_WAIT_L(0); PG8_MMA(0, 1, At, B1); PG8_BAR;
;             PG8_LDA(At, 0, 1); PG8_STAGE(PG8_SA(0, 0), a2, voffA);
;             PG8_BAR; PG8_WAIT_L(0); PG8_MMA(1, 0, At, B0); PG8_BAR; PG8_SCHED;
;             PG8_STAGE(PG8_SB(0, 1), b2 + hstep, voffB);
;             PG8_WAIT_V(6); PG8_BAR; PG8_MMA(1, 1, At, B1); PG8_BAR;
.LBB0_362:
	s_add_u32 s26, s24, 0xfff80080
	s_addc_u32 s27, s25, -1
	s_add_i32 s56, 0, 0x10000
	v_add_u32_e32 v150, s56, v135
	ds_read_b128 v[138:141], v150
	ds_read_b128 v[142:145], v150 offset:1024
	ds_read_b128 v[146:149], v150 offset:2048
	ds_read_b128 v[150:153], v150 offset:3072
	s_cmp_eq_u32 s55, 28
	s_cselect_b32 s29, s19, s27
	s_cselect_b32 s28, s51, s26
	s_cselect_b32 s27, s17, s54
	s_cselect_b32 s26, s52, s53
	s_add_i32 m0, s13, 0xc000
	ds_read_b128 v[154:157], v137
	ds_read_b128 v[174:177], v137 offset:1024
	ds_read_b128 v[178:181], v137 offset:2048
	ds_read_b128 v[182:185], v137 offset:3072
	ds_read_b128 v[186:189], v137 offset:4096
	ds_read_b128 v[190:193], v137 offset:5120
	ds_read_b128 v[194:197], v137 offset:6144
	ds_read_b128 v[214:217], v137 offset:7168
	global_load_lds_dwordx4 v130, s[24:25]
	s_add_i32 m0, s13, 0xe000
	s_nop 0
	global_load_lds_dwordx4 v132, s[24:25]
	s_waitcnt lgkmcnt(8)
	s_barrier
	s_waitcnt lgkmcnt(0)
	v_mfma_f32_16x16x32_bf16 v[124:127], v[138:141], v[154:157], v[124:127]
	v_mfma_f32_16x16x32_bf16 v[120:123], v[146:149], v[154:157], v[120:123]
	v_mfma_f32_16x16x32_bf16 v[116:119], v[138:141], v[178:181], v[116:119]
	v_mfma_f32_16x16x32_bf16 v[108:111], v[146:149], v[178:181], v[108:111]
	v_mfma_f32_16x16x32_bf16 v[100:103], v[138:141], v[186:189], v[100:103]
	v_mfma_f32_16x16x32_bf16 v[92:95], v[146:149], v[186:189], v[92:95]
	v_mfma_f32_16x16x32_bf16 v[84:87], v[138:141], v[194:197], v[84:87]
	v_mfma_f32_16x16x32_bf16 v[76:79], v[146:149], v[194:197], v[76:79]
	v_mfma_f32_16x16x32_bf16 v[124:127], v[142:145], v[174:177], v[124:127]
	v_mfma_f32_16x16x32_bf16 v[120:123], v[150:153], v[174:177], v[120:123]
	v_mfma_f32_16x16x32_bf16 v[116:119], v[142:145], v[182:185], v[116:119]
	v_mfma_f32_16x16x32_bf16 v[108:111], v[150:153], v[182:185], v[108:111]
	v_mfma_f32_16x16x32_bf16 v[100:103], v[142:145], v[190:193], v[100:103]
	v_mfma_f32_16x16x32_bf16 v[92:95], v[150:153], v[190:193], v[92:95]
	v_mfma_f32_16x16x32_bf16 v[84:87], v[142:145], v[214:217], v[84:87]
	v_mfma_f32_16x16x32_bf16 v[76:79], v[150:153], v[214:217], v[76:79]
	s_barrier
	s_add_i32 s58, 0, 0x14000
	v_add_u32_e32 v158, s58, v135
	s_add_i32 s56, s56, s41
	ds_read_b128 v[218:221], v158
	ds_read_b128 v[222:225], v158 offset:1024
	ds_read_b128 v[226:229], v158 offset:2048
	ds_read_b128 v[230:233], v158 offset:3072
	s_mov_b32 m0, s56
	s_nop 0
	global_load_lds_dwordx4 v160, s[26:27]
	s_add_i32 m0, s56, 0x2000
	s_nop 0
	global_load_lds_dwordx4 v128, s[26:27]
	s_barrier
	s_waitcnt lgkmcnt(0)
	v_mfma_f32_16x16x32_bf16 v[112:115], v[218:221], v[154:157], v[112:115]
	v_mfma_f32_16x16x32_bf16 v[104:107], v[226:229], v[154:157], v[104:107]
	v_mfma_f32_16x16x32_bf16 v[96:99], v[218:221], v[178:181], v[96:99]
	v_mfma_f32_16x16x32_bf16 v[88:91], v[226:229], v[178:181], v[88:91]
	v_mfma_f32_16x16x32_bf16 v[80:83], v[218:221], v[186:189], v[80:83]
	v_mfma_f32_16x16x32_bf16 v[72:75], v[226:229], v[186:189], v[72:75]
	v_mfma_f32_16x16x32_bf16 v[68:71], v[218:221], v[194:197], v[68:71]
	v_mfma_f32_16x16x32_bf16 v[64:67], v[226:229], v[194:197], v[64:67]
	v_mfma_f32_16x16x32_bf16 v[112:115], v[222:225], v[174:177], v[112:115]
	v_mfma_f32_16x16x32_bf16 v[104:107], v[230:233], v[174:177], v[104:107]
	v_mfma_f32_16x16x32_bf16 v[96:99], v[222:225], v[182:185], v[96:99]
	v_mfma_f32_16x16x32_bf16 v[88:91], v[230:233], v[182:185], v[88:91]
	v_mfma_f32_16x16x32_bf16 v[80:83], v[222:225], v[190:193], v[80:83]
	v_mfma_f32_16x16x32_bf16 v[72:75], v[230:233], v[190:193], v[72:75]
	v_mfma_f32_16x16x32_bf16 v[68:71], v[222:225], v[214:217], v[68:71]
	v_mfma_f32_16x16x32_bf16 v[64:67], v[230:233], v[214:217], v[64:67]
	s_mov_b32 m0, s13
	v_lshl_add_u64 v[236:237], s[28:29], 0, v[160:161]
	s_barrier
	ds_read_b128 v[154:157], v137 offset:16384
	ds_read_b128 v[174:177], v137 offset:17408
	ds_read_b128 v[178:181], v137 offset:18432
	ds_read_b128 v[182:185], v137 offset:19456
	ds_read_b128 v[186:189], v137 offset:20480
	ds_read_b128 v[190:193], v137 offset:21504
	ds_read_b128 v[194:197], v137 offset:22528
	ds_read_b128 v[214:217], v137 offset:23552
	global_load_lds_dwordx4 v160, s[28:29]
	v_lshl_add_u64 v[238:239], s[28:29], 0, v[128:129]
	s_mov_b32 m0, s43
	s_nop 0
	global_load_lds_dwordx4 v128, s[28:29]
	s_barrier
	s_waitcnt lgkmcnt(0)
	v_mfma_f32_16x16x32_bf16 v[60:63], v[138:141], v[154:157], v[60:63]
	v_mfma_f32_16x16x32_bf16 v[56:59], v[146:149], v[154:157], v[56:59]
	v_mfma_f32_16x16x32_bf16 v[52:55], v[138:141], v[178:181], v[52:55]
	v_mfma_f32_16x16x32_bf16 v[44:47], v[146:149], v[178:181], v[44:47]
	v_mfma_f32_16x16x32_bf16 v[36:39], v[138:141], v[186:189], v[36:39]
	v_mfma_f32_16x16x32_bf16 v[28:31], v[146:149], v[186:189], v[28:31]
	v_mfma_f32_16x16x32_bf16 v[20:23], v[138:141], v[194:197], v[20:23]
	v_mfma_f32_16x16x32_bf16 v[12:15], v[146:149], v[194:197], v[12:15]
	v_mfma_f32_16x16x32_bf16 v[60:63], v[142:145], v[174:177], v[60:63]
	v_mfma_f32_16x16x32_bf16 v[56:59], v[150:153], v[174:177], v[56:59]
	v_mfma_f32_16x16x32_bf16 v[52:55], v[142:145], v[182:185], v[52:55]
	v_mfma_f32_16x16x32_bf16 v[44:47], v[150:153], v[182:185], v[44:47]
	v_mfma_f32_16x16x32_bf16 v[36:39], v[142:145], v[190:193], v[36:39]
	v_mfma_f32_16x16x32_bf16 v[28:31], v[150:153], v[190:193], v[28:31]
	v_mfma_f32_16x16x32_bf16 v[20:23], v[142:145], v[214:217], v[20:23]
	v_mfma_f32_16x16x32_bf16 v[12:15], v[150:153], v[214:217], v[12:15]
	s_barrier
	s_add_u32 s56, s26, 0x80000
	s_addc_u32 s57, s27, 0
	s_add_i32 s58, s58, s41
	s_mov_b32 m0, s58
	s_nop 0
	global_load_lds_dwordx4 v160, s[56:57]
	s_add_i32 m0, s58, 0x2000
	s_nop 0
	global_load_lds_dwordx4 v128, s[56:57]
	s_waitcnt vmcnt(6)
	s_barrier
; #define PG8_STAGE(bufoff, gbase, voff) do { _Pragma("unroll") for (int _i = 0; _i < 2; ++_i) \
;         __builtin_amdgcn_global_load_lds((const unsigned*)((const char*)(gbase) + (voff)[_i]), (LAS unsigned*)(lds + (bufoff) + ldsw + _i * 8192), 16, 0, 0); } while (0)
; #define PG8_LDA(dst, b, h) do { _Pragma("unroll") for (int m = 0; m < 4; ++m) _Pragma("unroll") for (int k = 0; k < 2; ++k) dst[m][k] = *(const LAS bf16x8*)(lds + PG8_SA(b, h) + aoff + m * 2048 + k * 1024); } while (0)
; #define PG8_LDB(dst, b, h) do { _Pragma("unroll") for (int n = 0; n < 2; ++n) _Pragma("unroll") for (int k = 0; k < 2; ++k) dst[n][k] = *(const LAS bf16x8*)(lds + PG8_SB(b, h) + boff + n * 2048 + k * 1024); } while (0)
; #define PG8_MMA(ai, bj, At, Bt) do { __builtin_amdgcn_s_setprio(1); _Pragma("unroll") for (int m = 0; m < 4; ++m) _Pragma("unroll") for (int n = 0; n < 2; ++n) _Pragma("unroll") for (int k = 0; k < 2; ++k) \
;         acc[ai][bj][m][n] = __builtin_amdgcn_mfma_f32_16x16x32_bf16(Bt[n][k], At[m][k], acc[ai][bj][m][n], 0, 0, 0); __builtin_amdgcn_s_setprio(0); } while (0)
; #define PG8_WAIT_V(n) asm volatile("s_waitcnt vmcnt(" #n ")" ::: "memory")
; #define PG8_WAIT_L(n) asm volatile("s_waitcnt lgkmcnt(" #n ")" ::: "memory")
; #define PG8_BAR __builtin_amdgcn_s_barrier()
; #define PG8_SCHED __builtin_amdgcn_sched_barrier(0)
; template <class Epi>
; DEV void gemm_phase(LAS unsigned char* lds, const Gemm g, const StaticOrder& S, const Epi& E) {
;     ...
;             PG8_WAIT_V(6); PG8_BAR; PG8_MMA(1, 1, At, B1); PG8_BAR;
;             PG8_LDB(B0, 1, 0); PG8_SCHED; PG8_LDA(At, 1, 0); PG8_STAGE(PG8_SA(0, 1), a2 + hstep, voffA);
;             PG8_WAIT_L(8); PG8_BAR; PG8_WAIT_L(0); PG8_MMA(0, 0, At, B0); PG8_BAR; PG8_SCHED;
;             PG8_LDB(B1, 1, 1); PG8_STAGE(PG8_SB(1, 0), b3, voffB);
;             PG8_BAR; PG8_WAIT_L(0); PG8_MMA(0, 1, At, B1); PG8_BAR;
;             PG8_LDA(At, 1, 1); PG8_STAGE(PG8_SA(1, 0), a3, voffA);
	v_mfma_f32_16x16x32_bf16 v[48:51], v[218:221], v[154:157], v[48:51]
	v_mfma_f32_16x16x32_bf16 v[40:43], v[226:229], v[154:157], v[40:43]
	v_mfma_f32_16x16x32_bf16 v[32:35], v[218:221], v[178:181], v[32:35]
	v_mfma_f32_16x16x32_bf16 v[24:27], v[226:229], v[178:181], v[24:27]
	v_mfma_f32_16x16x32_bf16 v[16:19], v[218:221], v[186:189], v[16:19]
	v_mfma_f32_16x16x32_bf16 v[8:11], v[226:229], v[186:189], v[8:11]
	v_mfma_f32_16x16x32_bf16 v[4:7], v[218:221], v[194:197], v[4:7]
	v_mfma_f32_16x16x32_bf16 v[0:3], v[226:229], v[194:197], v[0:3]
	v_mfma_f32_16x16x32_bf16 v[48:51], v[222:225], v[174:177], v[48:51]
	v_mfma_f32_16x16x32_bf16 v[40:43], v[230:233], v[174:177], v[40:43]
	v_mfma_f32_16x16x32_bf16 v[32:35], v[222:225], v[182:185], v[32:35]
	v_mfma_f32_16x16x32_bf16 v[24:27], v[230:233], v[182:185], v[24:27]
	v_mfma_f32_16x16x32_bf16 v[16:19], v[222:225], v[190:193], v[16:19]
	v_mfma_f32_16x16x32_bf16 v[8:11], v[230:233], v[190:193], v[8:11]
	v_mfma_f32_16x16x32_bf16 v[4:7], v[222:225], v[214:217], v[4:7]
	v_mfma_f32_16x16x32_bf16 v[0:3], v[230:233], v[214:217], v[0:3]
	s_add_i32 s56, 0, 0x18000
	v_add_u32_e32 v150, s56, v135
	s_barrier
	ds_read_b128 v[138:141], v150
	ds_read_b128 v[142:145], v150 offset:1024
	ds_read_b128 v[146:149], v150 offset:2048
	ds_read_b128 v[150:153], v150 offset:3072
	s_add_u32 s28, s28, 0x80000
	s_addc_u32 s29, s29, 0
	s_mov_b32 m0, s44
	ds_read_b128 v[154:157], v137 offset:32768
	ds_read_b128 v[174:177], v137 offset:33792
	ds_read_b128 v[178:181], v137 offset:34816
	ds_read_b128 v[182:185], v137 offset:35840
	ds_read_b128 v[186:189], v137 offset:36864
	ds_read_b128 v[190:193], v137 offset:37888
	ds_read_b128 v[194:197], v137 offset:38912
	ds_read_b128 v[214:217], v137 offset:39936
	global_load_lds_dwordx4 v160, s[28:29]
	s_mov_b32 m0, s45
	s_nop 0
	global_load_lds_dwordx4 v128, s[28:29]
	s_waitcnt lgkmcnt(8)
	s_barrier
	s_waitcnt lgkmcnt(0)
	v_mfma_f32_16x16x32_bf16 v[124:127], v[138:141], v[154:157], v[124:127]
	v_mfma_f32_16x16x32_bf16 v[120:123], v[146:149], v[154:157], v[120:123]
	v_mfma_f32_16x16x32_bf16 v[116:119], v[138:141], v[178:181], v[116:119]
	v_mfma_f32_16x16x32_bf16 v[108:111], v[146:149], v[178:181], v[108:111]
	v_mfma_f32_16x16x32_bf16 v[100:103], v[138:141], v[186:189], v[100:103]
	v_mfma_f32_16x16x32_bf16 v[92:95], v[146:149], v[186:189], v[92:95]
	v_mfma_f32_16x16x32_bf16 v[84:87], v[138:141], v[194:197], v[84:87]
	v_mfma_f32_16x16x32_bf16 v[76:79], v[146:149], v[194:197], v[76:79]
	v_mfma_f32_16x16x32_bf16 v[124:127], v[142:145], v[174:177], v[124:127]
	v_mfma_f32_16x16x32_bf16 v[120:123], v[150:153], v[174:177], v[120:123]
	v_mfma_f32_16x16x32_bf16 v[116:119], v[142:145], v[182:185], v[116:119]
	v_mfma_f32_16x16x32_bf16 v[108:111], v[150:153], v[182:185], v[108:111]
	v_mfma_f32_16x16x32_bf16 v[100:103], v[142:145], v[190:193], v[100:103]
	v_mfma_f32_16x16x32_bf16 v[92:95], v[150:153], v[190:193], v[92:95]
	v_mfma_f32_16x16x32_bf16 v[84:87], v[142:145], v[214:217], v[84:87]
	v_mfma_f32_16x16x32_bf16 v[76:79], v[150:153], v[214:217], v[76:79]
	s_barrier
	s_add_i32 s28, 0, 0x1c000
	s_add_i32 s29, s56, s41
	v_add_u32_e32 v167, s28, v135
	s_add_u32 s100, s26, 0x80
	s_addc_u32 s101, s27, 0
	s_mov_b32 m0, s29
	ds_read_b128 v[218:221], v167
	ds_read_b128 v[222:225], v167 offset:1024
	ds_read_b128 v[226:229], v167 offset:2048
	ds_read_b128 v[230:233], v167 offset:3072
	global_load_lds_dwordx4 v160, s[100:101]
	s_add_i32 m0, s29, 0x2000
	s_nop 0
	global_load_lds_dwordx4 v128, s[100:101]
	s_barrier
	s_waitcnt lgkmcnt(0)
	v_mfma_f32_16x16x32_bf16 v[112:115], v[218:221], v[154:157], v[112:115]
	v_mfma_f32_16x16x32_bf16 v[104:107], v[226:229], v[154:157], v[104:107]
	v_mfma_f32_16x16x32_bf16 v[96:99], v[218:221], v[178:181], v[96:99]
	v_mfma_f32_16x16x32_bf16 v[88:91], v[226:229], v[178:181], v[88:91]
	v_mfma_f32_16x16x32_bf16 v[80:83], v[218:221], v[186:189], v[80:83]
	v_mfma_f32_16x16x32_bf16 v[72:75], v[226:229], v[186:189], v[72:75]
	v_mfma_f32_16x16x32_bf16 v[68:71], v[218:221], v[194:197], v[68:71]
	v_mfma_f32_16x16x32_bf16 v[64:67], v[226:229], v[194:197], v[64:67]
	v_mfma_f32_16x16x32_bf16 v[112:115], v[222:225], v[174:177], v[112:115]
	v_mfma_f32_16x16x32_bf16 v[104:107], v[230:233], v[174:177], v[104:107]
	v_mfma_f32_16x16x32_bf16 v[96:99], v[222:225], v[182:185], v[96:99]
	v_mfma_f32_16x16x32_bf16 v[88:91], v[230:233], v[182:185], v[88:91]
	v_mfma_f32_16x16x32_bf16 v[80:83], v[222:225], v[190:193], v[80:83]
	v_mfma_f32_16x16x32_bf16 v[72:75], v[230:233], v[190:193], v[72:75]
	v_mfma_f32_16x16x32_bf16 v[68:71], v[222:225], v[214:217], v[68:71]
	v_mfma_f32_16x16x32_bf16 v[64:67], v[230:233], v[214:217], v[64:67]
	s_mov_b32 m0, s46
	v_lshl_add_u64 v[158:159], v[236:237], 0, s[2:3]
	s_barrier
	ds_read_b128 v[154:157], v137 offset:49152
	ds_read_b128 v[174:177], v137 offset:50176
	ds_read_b128 v[178:181], v137 offset:51200
	ds_read_b128 v[182:185], v137 offset:52224
	ds_read_b128 v[186:189], v137 offset:53248
	ds_read_b128 v[190:193], v137 offset:54272
	ds_read_b128 v[194:197], v137 offset:55296
	ds_read_b128 v[214:217], v137 offset:56320
	global_load_lds_dwordx4 v[158:159], off
	v_lshl_add_u64 v[158:159], v[238:239], 0, s[2:3]
	s_mov_b32 m0, s47
	s_nop 0
	global_load_lds_dwordx4 v[158:159], off
	s_barrier
; #define PG8_STAGE(bufoff, gbase, voff) do { _Pragma("unroll") for (int _i = 0; _i < 2; ++_i) \
;         __builtin_amdgcn_global_load_lds((const unsigned*)((const char*)(gbase) + (voff)[_i]), (LAS unsigned*)(lds + (bufoff) + ldsw + _i * 8192), 16, 0, 0); } while (0)
; #define PG8_MMA(ai, bj, At, Bt) do { __builtin_amdgcn_s_setprio(1); _Pragma("unroll") for (int m = 0; m < 4; ++m) _Pragma("unroll") for (int n = 0; n < 2; ++n) _Pragma("unroll") for (int k = 0; k < 2; ++k) \
;         acc[ai][bj][m][n] = __builtin_amdgcn_mfma_f32_16x16x32_bf16(Bt[n][k], At[m][k], acc[ai][bj][m][n], 0, 0, 0); __builtin_amdgcn_s_setprio(0); } while (0)
; #define PG8_WAIT_V(n) asm volatile("s_waitcnt vmcnt(" #n ")" ::: "memory")
; #define PG8_WAIT_L(n) asm volatile("s_waitcnt lgkmcnt(" #n ")" ::: "memory")
; #define PG8_BAR __builtin_amdgcn_s_barrier()
; #define PG8_SCHED __builtin_amdgcn_sched_barrier(0)
; template <class Epi>
; DEV void gemm_phase(LAS unsigned char* lds, const Gemm g, const StaticOrder& S, const Epi& E) {
;     ...
;             PG8_BAR; PG8_WAIT_L(0); PG8_MMA(1, 0, At, B0); PG8_BAR; PG8_SCHED;
;             PG8_STAGE(PG8_SB(1, 1), b3 + hstep, voffB);
;             PG8_WAIT_V(6); PG8_BAR; PG8_MMA(1, 1, At, B1); PG8_BAR;
;         }
	s_waitcnt lgkmcnt(0)
	v_mfma_f32_16x16x32_bf16 v[60:63], v[138:141], v[154:157], v[60:63]
	v_mfma_f32_16x16x32_bf16 v[56:59], v[146:149], v[154:157], v[56:59]
	v_mfma_f32_16x16x32_bf16 v[52:55], v[138:141], v[178:181], v[52:55]
	v_mfma_f32_16x16x32_bf16 v[44:47], v[146:149], v[178:181], v[44:47]
	v_mfma_f32_16x16x32_bf16 v[36:39], v[138:141], v[186:189], v[36:39]
	v_mfma_f32_16x16x32_bf16 v[28:31], v[146:149], v[186:189], v[28:31]
	v_mfma_f32_16x16x32_bf16 v[20:23], v[138:141], v[194:197], v[20:23]
	v_mfma_f32_16x16x32_bf16 v[12:15], v[146:149], v[194:197], v[12:15]
	v_mfma_f32_16x16x32_bf16 v[60:63], v[142:145], v[174:177], v[60:63]
	v_mfma_f32_16x16x32_bf16 v[56:59], v[150:153], v[174:177], v[56:59]
	v_mfma_f32_16x16x32_bf16 v[52:55], v[142:145], v[182:185], v[52:55]
	v_mfma_f32_16x16x32_bf16 v[44:47], v[150:153], v[182:185], v[44:47]
	v_mfma_f32_16x16x32_bf16 v[36:39], v[142:145], v[190:193], v[36:39]
	v_mfma_f32_16x16x32_bf16 v[28:31], v[150:153], v[190:193], v[28:31]
	v_mfma_f32_16x16x32_bf16 v[20:23], v[142:145], v[214:217], v[20:23]
	v_mfma_f32_16x16x32_bf16 v[12:15], v[150:153], v[214:217], v[12:15]
	s_barrier
	s_add_u32 s26, s26, 0x80080
	s_addc_u32 s27, s27, 0
	s_add_i32 s28, s28, s41
	s_mov_b32 m0, s28
	s_nop 0
	global_load_lds_dwordx4 v160, s[26:27]
	s_add_i32 m0, s28, 0x2000
	s_nop 0
	global_load_lds_dwordx4 v128, s[26:27]
	s_waitcnt vmcnt(6)
	s_barrier
	v_mfma_f32_16x16x32_bf16 v[48:51], v[218:221], v[154:157], v[48:51]
	v_mfma_f32_16x16x32_bf16 v[40:43], v[226:229], v[154:157], v[40:43]
	v_mfma_f32_16x16x32_bf16 v[32:35], v[218:221], v[178:181], v[32:35]
	v_mfma_f32_16x16x32_bf16 v[24:27], v[226:229], v[178:181], v[24:27]
	v_mfma_f32_16x16x32_bf16 v[16:19], v[218:221], v[186:189], v[16:19]
	v_mfma_f32_16x16x32_bf16 v[8:11], v[226:229], v[186:189], v[8:11]
	v_mfma_f32_16x16x32_bf16 v[4:7], v[218:221], v[194:197], v[4:7]
	v_mfma_f32_16x16x32_bf16 v[0:3], v[226:229], v[194:197], v[0:3]
	v_mfma_f32_16x16x32_bf16 v[48:51], v[222:225], v[174:177], v[48:51]
	v_mfma_f32_16x16x32_bf16 v[40:43], v[230:233], v[174:177], v[40:43]
	v_mfma_f32_16x16x32_bf16 v[32:35], v[222:225], v[182:185], v[32:35]
	v_mfma_f32_16x16x32_bf16 v[24:27], v[230:233], v[182:185], v[24:27]
	v_mfma_f32_16x16x32_bf16 v[16:19], v[222:225], v[190:193], v[16:19]
	v_mfma_f32_16x16x32_bf16 v[8:11], v[230:233], v[190:193], v[8:11]
	v_mfma_f32_16x16x32_bf16 v[4:7], v[222:225], v[214:217], v[4:7]
	v_mfma_f32_16x16x32_bf16 v[0:3], v[230:233], v[214:217], v[0:3]
	s_add_i32 s55, s55, 2
	s_add_u32 s24, s24, 0x100
	s_addc_u32 s25, s25, 0
	s_add_u32 s53, s53, 0x100
	s_addc_u32 s54, s54, 0
	s_cmp_gt_u32 s55, 29
	s_barrier
	s_cbranch_scc0 .LBB0_362
; DEV bf16x8 pack8(f32x4 a, f32x4 b) { u32x4 w; w.x = cvt_pk_bf16(a[0], a[1]); w.y = cvt_pk_bf16(a[2], a[3]); w.z = cvt_pk_bf16(b[0], b[1]); w.w = cvt_pk_bf16(b[2], b[3]); return __builtin_bit_cast(bf16x8, w); }
; DEV u32x2 pack4(f32x4 a) { u32x2 w; w.x = cvt_pk_bf16(a[0], a[1]); w.y = cvt_pk_bf16(a[2], a[3]); return w; }
; DEV f32x4 gelu4(f32x4 v) { f32x2 a = gelu_pk((f32x2){v[0], v[1]}), b = gelu_pk((f32x2){v[2], v[3]}); return (f32x4){a.x, a.y, b.x, b.y}; }
; #define PG8_WAIT_V(n) asm volatile("s_waitcnt vmcnt(" #n ")" ::: "memory")
; #define PG8_BAR __builtin_amdgcn_s_barrier()
; template <class Epi>
; DEV void gemm_phase(LAS unsigned char* lds, const Gemm g, const StaticOrder& S, const Epi& E) {
;     ...
;         E(acc, cur, wr, wc, fr, fq);
;         if (!has_next) break;
; #pragma unroll
;         for (int a = 0; a < 2; ++a)
; #pragma unroll
;             for (int b = 0; b < 2; ++b)
; #pragma unroll
;                 for (int m = 0; m < 4; ++m)
; #pragma unroll
;                     for (int n = 0; n < 2; ++n) acc[a][b][m][n] = (f32x4){0.f, 0.f, 0.f, 0.f};
;         cur = nxt; cA = nA; cB = nB; ++ui;
;     }
;     PG8_WAIT_V(0);
;     if (wr == 0) PG8_BAR;
;     PG8_BAR;
; template <int ACT, bool PERM>
; DEV void store_bf16_tile(AccRef acc, u16* O, int ld, int row0, int col0, const float* ss) {
;     float rsv[2][4];
; #pragma unroll
;     for (int ai = 0; ai < 2; ++ai)
; #pragma unroll
;         for (int m = 0; m < 4; ++m) rsv[ai][m] = ss ? rowscale(ss, row0 + ai * 128 + m * 16) : 1.0f;
; #pragma unroll
;     for (int ai = 0; ai < 2; ++ai)
; #pragma unroll
;         for (int m = 0; m < 4; ++m) { u16* rowp = O + (size_t)(row0 + ai * 128 + m * 16) * ld + col0; const float rs = rsv[ai][m];
; #pragma unroll
;             for (int bj = 0; bj < 2; ++bj) { f32x4 v0 = acc[ai][bj][m][0] * rs, v1 = acc[ai][bj][m][1] * rs; if (ACT == 1) { v0 = gelu4(v0); v1 = gelu4(v1); }
;                 if (PERM) *(u32x4*)(rowp + bj * 128) = __builtin_bit_cast(u32x4, pack8(v0, v1));
;                 else { *(u32x2*)(rowp + bj * 128) = pack4(v0); *(u32x2*)(rowp + bj * 128 + 16) = pack4(v1); } } }
	v_lshl_add_u32 v138, s12, 8, v134
	v_lshl_or_b32 v140, s50, 8, v136
	v_ashrrev_i32_e32 v141, 31, v140
	v_ashrrev_i32_e32 v139, 31, v138
	v_lshl_add_u64 v[140:141], v[140:141], 1, s[10:11]
	v_lshlrev_b64 v[142:143], 11, v[138:139]
	v_lshl_add_u64 v[142:143], v[140:141], 0, v[142:143]
	v_cvt_pk_bf16_f32 v104, v104, v105
	v_cvt_pk_bf16_f32 v105, v106, v107
	global_store_dwordx2 v[142:143], v[104:105], off offset:288
	v_or_b32_e32 v104, 16, v138
	v_ashrrev_i32_e32 v105, 31, v104
	v_lshlrev_b64 v[104:105], 11, v[104:105]
	v_lshl_add_u64 v[104:105], v[140:141], 0, v[104:105]
	v_cvt_pk_bf16_f32 v88, v88, v89
	v_cvt_pk_bf16_f32 v89, v90, v91
	global_store_dwordx2 v[104:105], v[88:89], off offset:288
	v_or_b32_e32 v88, 32, v138
	v_ashrrev_i32_e32 v89, 31, v88
	v_lshlrev_b64 v[88:89], 11, v[88:89]
	v_lshl_add_u64 v[88:89], v[140:141], 0, v[88:89]
	v_cvt_pk_bf16_f32 v72, v72, v73
	v_cvt_pk_bf16_f32 v73, v74, v75
	global_store_dwordx2 v[88:89], v[72:73], off offset:288
	v_or_b32_e32 v72, 48, v138
	v_ashrrev_i32_e32 v73, 31, v72
	v_lshlrev_b64 v[72:73], 11, v[72:73]
	s_mov_b32 s12, 0x40000
	v_lshl_add_u64 v[72:73], v[140:141], 0, v[72:73]
	v_cvt_pk_bf16_f32 v64, v64, v65
	v_cvt_pk_bf16_f32 v65, v66, v67
	s_mov_b64 s[24:25], 0x40000
	v_cvt_pk_bf16_f32 v60, v60, v61
	v_cvt_pk_bf16_f32 v61, v62, v63
	v_add_co_u32_e32 v62, vcc, s12, v142
	global_store_dwordx2 v[72:73], v[64:65], off offset:288
	v_lshl_add_u64 v[64:65], v[142:143], 0, s[24:25]
	v_addc_co_u32_e32 v63, vcc, 0, v143, vcc
	v_cvt_pk_bf16_f32 v48, v48, v49
	v_cvt_pk_bf16_f32 v49, v50, v51
	s_mov_b32 s12, 0x48000
	global_store_dwordx2 v[64:65], v[48:49], off offset:256
	v_cvt_pk_bf16_f32 v40, v40, v41
	v_cvt_pk_bf16_f32 v41, v42, v43
	s_mov_b64 s[24:25], 0x48000
	v_add_co_u32_e32 v48, vcc, s12, v142
	global_store_dwordx2 v[64:65], v[40:41], off offset:288
	v_lshl_add_u64 v[40:41], v[142:143], 0, s[24:25]
	v_addc_co_u32_e32 v49, vcc, 0, v143, vcc
	v_cvt_pk_bf16_f32 v32, v32, v33
	v_cvt_pk_bf16_f32 v33, v34, v35
	s_mov_b32 s12, 0x50000
	global_store_dwordx2 v[40:41], v[32:33], off offset:256
	v_cvt_pk_bf16_f32 v24, v24, v25
	v_cvt_pk_bf16_f32 v25, v26, v27
	s_mov_b64 s[24:25], 0x50000
	v_add_co_u32_e32 v32, vcc, s12, v142
	global_store_dwordx2 v[40:41], v[24:25], off offset:288
	v_lshl_add_u64 v[24:25], v[142:143], 0, s[24:25]
	v_addc_co_u32_e32 v33, vcc, 0, v143, vcc
	v_cvt_pk_bf16_f32 v16, v16, v17
	v_cvt_pk_bf16_f32 v17, v18, v19
	global_store_dwordx2 v[24:25], v[16:17], off offset:256
	v_add_co_u32_e32 v16, vcc, s59, v142
	v_cvt_pk_bf16_f32 v106, v116, v117
	v_cvt_pk_bf16_f32 v107, v118, v119
	v_cvt_pk_bf16_f32 v90, v100, v101
	v_cvt_pk_bf16_f32 v91, v102, v103
	v_cvt_pk_bf16_f32 v74, v84, v85
	v_cvt_pk_bf16_f32 v75, v86, v87
	v_cvt_pk_bf16_f32 v42, v52, v53
	v_cvt_pk_bf16_f32 v43, v54, v55
	v_cvt_pk_bf16_f32 v26, v36, v37
	v_cvt_pk_bf16_f32 v27, v38, v39
	v_cvt_pk_bf16_f32 v8, v8, v9
	v_cvt_pk_bf16_f32 v9, v10, v11
	s_mov_b64 s[24:25], 0x58000
	v_cvt_pk_bf16_f32 v10, v20, v21
	v_cvt_pk_bf16_f32 v11, v22, v23
	v_addc_co_u32_e32 v17, vcc, 0, v143, vcc
	v_cvt_pk_bf16_f32 v124, v124, v125
	v_cvt_pk_bf16_f32 v125, v126, v127
	v_cvt_pk_bf16_f32 v120, v120, v121
	v_cvt_pk_bf16_f32 v121, v122, v123
	v_cvt_pk_bf16_f32 v112, v112, v113
	v_cvt_pk_bf16_f32 v113, v114, v115
	global_store_dwordx2 v[104:105], v[106:107], off
	v_cvt_pk_bf16_f32 v106, v108, v109
	v_cvt_pk_bf16_f32 v107, v110, v111
	v_cvt_pk_bf16_f32 v96, v96, v97
	v_cvt_pk_bf16_f32 v97, v98, v99
	global_store_dwordx2 v[88:89], v[90:91], off
	v_cvt_pk_bf16_f32 v90, v92, v93
	v_cvt_pk_bf16_f32 v91, v94, v95
	v_cvt_pk_bf16_f32 v80, v80, v81
	v_cvt_pk_bf16_f32 v81, v82, v83
	global_store_dwordx2 v[72:73], v[74:75], off
	v_cvt_pk_bf16_f32 v74, v76, v77
	v_cvt_pk_bf16_f32 v75, v78, v79
	v_cvt_pk_bf16_f32 v68, v68, v69
	v_cvt_pk_bf16_f32 v69, v70, v71
	v_cvt_pk_bf16_f32 v56, v56, v57
	v_cvt_pk_bf16_f32 v57, v58, v59
	global_store_dwordx2 v[48:49], v[42:43], off
	v_cvt_pk_bf16_f32 v42, v44, v45
	v_cvt_pk_bf16_f32 v43, v46, v47
	global_store_dwordx2 v[32:33], v[26:27], off
	v_cvt_pk_bf16_f32 v26, v28, v29
	v_cvt_pk_bf16_f32 v27, v30, v31
	global_store_dwordx2 v[24:25], v[8:9], off offset:288
	v_lshl_add_u64 v[8:9], v[142:143], 0, s[24:25]
	global_store_dwordx2 v[16:17], v[10:11], off
	v_cvt_pk_bf16_f32 v10, v12, v13
	v_cvt_pk_bf16_f32 v11, v14, v15
	v_cvt_pk_bf16_f32 v4, v4, v5
	v_cvt_pk_bf16_f32 v5, v6, v7
	v_cvt_pk_bf16_f32 v0, v0, v1
	v_cvt_pk_bf16_f32 v1, v2, v3
	s_and_b64 vcc, exec, s[14:15]
	s_mov_b32 s50, s16
	s_mov_b32 s12, s18
	s_mov_b64 s[26:27], s[22:23]
	s_mov_b64 s[24:25], s[20:21]
	global_store_dwordx2 v[142:143], v[124:125], off
	global_store_dwordx2 v[142:143], v[120:121], off offset:32
	global_store_dwordx2 v[142:143], v[112:113], off offset:256
	global_store_dwordx2 v[104:105], v[106:107], off offset:32
	global_store_dwordx2 v[104:105], v[96:97], off offset:256
	global_store_dwordx2 v[88:89], v[90:91], off offset:32
	global_store_dwordx2 v[88:89], v[80:81], off offset:256
	global_store_dwordx2 v[72:73], v[74:75], off offset:32
	global_store_dwordx2 v[72:73], v[68:69], off offset:256
	global_store_dwordx2 v[62:63], v[60:61], off
	global_store_dwordx2 v[64:65], v[56:57], off offset:32
	global_store_dwordx2 v[40:41], v[42:43], off offset:32
	global_store_dwordx2 v[24:25], v[26:27], off offset:32
	global_store_dwordx2 v[8:9], v[10:11], off offset:32
	global_store_dwordx2 v[8:9], v[4:5], off offset:256
	global_store_dwordx2 v[8:9], v[0:1], off offset:288
	s_cbranch_vccz .LBB0_359
	s_waitcnt vmcnt(0)
	s_cmpk_gt_u32 s36, 0xff
	s_cbranch_scc1 .LBB0_353
	s_barrier
	s_branch .LBB0_353

; #define PG8_STAGE(bufoff, gbase, voff) do { _Pragma("unroll") for (int _i = 0; _i < 2; ++_i) \
;         __builtin_amdgcn_global_load_lds((const unsigned*)((const char*)(gbase) + (voff)[_i]), (LAS unsigned*)(lds + (bufoff) + ldsw + _i * 8192), 16, 0, 0); } while (0)
; #define PG8_LDA(dst, b, h) do { _Pragma("unroll") for (int m = 0; m < 4; ++m) _Pragma("unroll") for (int k = 0; k < 2; ++k) dst[m][k] = *(const LAS bf16x8*)(lds + PG8_SA(b, h) + aoff + m * 2048 + k * 1024); } while (0)
; #define PG8_LDB(dst, b, h) do { _Pragma("unroll") for (int n = 0; n < 2; ++n) _Pragma("unroll") for (int k = 0; k < 2; ++k) dst[n][k] = *(const LAS bf16x8*)(lds + PG8_SB(b, h) + boff + n * 2048 + k * 1024); } while (0)
; #define PG8_MMA(ai, bj, At, Bt) do { __builtin_amdgcn_s_setprio(1); _Pragma("unroll") for (int m = 0; m < 4; ++m) _Pragma("unroll") for (int n = 0; n < 2; ++n) _Pragma("unroll") for (int k = 0; k < 2; ++k) \
;         acc[ai][bj][m][n] = __builtin_amdgcn_mfma_f32_16x16x32_bf16(Bt[n][k], At[m][k], acc[ai][bj][m][n], 0, 0, 0); __builtin_amdgcn_s_setprio(0); } while (0)
; #define PG8_WAIT_V(n) asm volatile("s_waitcnt vmcnt(" #n ")" ::: "memory")
; #define PG8_WAIT_L(n) asm volatile("s_waitcnt lgkmcnt(" #n ")" ::: "memory")
; #define PG8_BAR __builtin_amdgcn_s_barrier()
; #define PG8_SCHED __builtin_amdgcn_sched_barrier(0)
; template <class Epi>
; DEV void gemm_phase(LAS unsigned char* lds, const Gemm g, const StaticOrder& S, const Epi& E) {
;     ...
;             const bool last = (t == nt - 2);
;             const char* a1 = cA + (size_t)(t + 1) * kstep;
;             const char* a2 = last ? nA : cA + (size_t)(t + 2) * kstep; const char* b2 = last ? nB : cB + (size_t)(t + 2) * kstep;
;             const char* a3 = a2 + kstep; const char* b3 = b2 + kstep;
;             PG8_LDB(B0, 0, 0); PG8_SCHED; PG8_LDA(At, 0, 0); PG8_STAGE(PG8_SA(1, 1), a1 + hstep, voffA);
;             PG8_WAIT_L(8); PG8_BAR; PG8_WAIT_L(0); PG8_MMA(0, 0, At, B0); PG8_BAR; PG8_SCHED;
;             PG8_LDB(B1, 0, 1); PG8_STAGE(PG8_SB(0, 0), b2, voffB);
;             PG8_BAR; PG8_WAIT_L(0); PG8_MMA(0, 1, At, B1); PG8_BAR;
;             PG8_LDA(At, 0, 1); PG8_STAGE(PG8_SA(0, 0), a2, voffA);
;             PG8_BAR; PG8_WAIT_L(0); PG8_MMA(1, 0, At, B0); PG8_BAR; PG8_SCHED;
;             PG8_STAGE(PG8_SB(0, 1), b2 + hstep, voffB);
;             PG8_WAIT_V(6); PG8_BAR; PG8_MMA(1, 1, At, B1); PG8_BAR;
.LBB0_404:
	s_add_u32 s28, s26, 0xfff00080
	s_addc_u32 s29, s27, -1
	s_add_i32 s49, 0, 0x10000
	v_add_u32_e32 v140, s49, v178
	ds_read_b128 v[128:131], v140
	ds_read_b128 v[132:135], v140 offset:1024
	ds_read_b128 v[136:139], v140 offset:2048
	ds_read_b128 v[140:143], v140 offset:3072
	s_cmp_eq_u32 s48, 60
	s_cselect_b32 s31, s15, s29
	s_cselect_b32 s30, s19, s28
	s_cselect_b32 s29, s17, s47
	s_cselect_b32 s28, s25, s46
	s_add_i32 m0, s37, 0xc000
	ds_read_b128 v[154:157], v181
	ds_read_b128 v[174:177], v181 offset:1024
	ds_read_b128 v[182:185], v181 offset:2048
	ds_read_b128 v[186:189], v181 offset:3072
	ds_read_b128 v[190:193], v181 offset:4096
	ds_read_b128 v[194:197], v181 offset:5120
	ds_read_b128 v[214:217], v181 offset:6144
	ds_read_b128 v[218:221], v181 offset:7168
	global_load_lds_dwordx4 v150, s[26:27]
	s_add_i32 m0, s37, 0xe000
	s_nop 0
	global_load_lds_dwordx4 v152, s[26:27]
	s_waitcnt lgkmcnt(8)
	s_barrier
	s_waitcnt lgkmcnt(0)
	v_mfma_f32_16x16x32_bf16 v[124:127], v[128:131], v[154:157], v[124:127]
	v_mfma_f32_16x16x32_bf16 v[120:123], v[136:139], v[154:157], v[120:123]
	v_mfma_f32_16x16x32_bf16 v[108:111], v[128:131], v[182:185], v[108:111]
	v_mfma_f32_16x16x32_bf16 v[104:107], v[136:139], v[182:185], v[104:107]
	v_mfma_f32_16x16x32_bf16 v[92:95], v[128:131], v[190:193], v[92:95]
	v_mfma_f32_16x16x32_bf16 v[88:91], v[136:139], v[190:193], v[88:91]
	v_mfma_f32_16x16x32_bf16 v[76:79], v[128:131], v[214:217], v[76:79]
	v_mfma_f32_16x16x32_bf16 v[72:75], v[136:139], v[214:217], v[72:75]
	v_mfma_f32_16x16x32_bf16 v[124:127], v[132:135], v[174:177], v[124:127]
	v_mfma_f32_16x16x32_bf16 v[120:123], v[140:143], v[174:177], v[120:123]
	v_mfma_f32_16x16x32_bf16 v[108:111], v[132:135], v[186:189], v[108:111]
	v_mfma_f32_16x16x32_bf16 v[104:107], v[140:143], v[186:189], v[104:107]
	v_mfma_f32_16x16x32_bf16 v[92:95], v[132:135], v[194:197], v[92:95]
	v_mfma_f32_16x16x32_bf16 v[88:91], v[140:143], v[194:197], v[88:91]
	v_mfma_f32_16x16x32_bf16 v[76:79], v[132:135], v[218:221], v[76:79]
	v_mfma_f32_16x16x32_bf16 v[72:75], v[140:143], v[218:221], v[72:75]
	s_barrier
	s_add_i32 s52, 0, 0x14000
	v_add_u32_e32 v158, s52, v178
	s_add_i32 s49, s49, s36
	ds_read_b128 v[222:225], v158
	ds_read_b128 v[226:229], v158 offset:1024
	ds_read_b128 v[230:233], v158 offset:2048
	ds_read_b128 v[234:237], v158 offset:3072
	s_mov_b32 m0, s49
	s_nop 0
	global_load_lds_dwordx4 v160, s[28:29]
	s_add_i32 m0, s49, 0x2000
	s_nop 0
	global_load_lds_dwordx4 v148, s[28:29]
	s_barrier
	s_waitcnt lgkmcnt(0)
	v_mfma_f32_16x16x32_bf16 v[116:119], v[222:225], v[154:157], v[116:119]
	v_mfma_f32_16x16x32_bf16 v[112:115], v[230:233], v[154:157], v[112:115]
	v_mfma_f32_16x16x32_bf16 v[100:103], v[222:225], v[182:185], v[100:103]
	v_mfma_f32_16x16x32_bf16 v[96:99], v[230:233], v[182:185], v[96:99]
	v_mfma_f32_16x16x32_bf16 v[84:87], v[222:225], v[190:193], v[84:87]
	v_mfma_f32_16x16x32_bf16 v[80:83], v[230:233], v[190:193], v[80:83]
	v_mfma_f32_16x16x32_bf16 v[68:71], v[222:225], v[214:217], v[68:71]
	v_mfma_f32_16x16x32_bf16 v[64:67], v[230:233], v[214:217], v[64:67]
	v_mfma_f32_16x16x32_bf16 v[116:119], v[226:229], v[174:177], v[116:119]
	v_mfma_f32_16x16x32_bf16 v[112:115], v[234:237], v[174:177], v[112:115]
	v_mfma_f32_16x16x32_bf16 v[100:103], v[226:229], v[186:189], v[100:103]
	v_mfma_f32_16x16x32_bf16 v[96:99], v[234:237], v[186:189], v[96:99]
	v_mfma_f32_16x16x32_bf16 v[84:87], v[226:229], v[194:197], v[84:87]
	v_mfma_f32_16x16x32_bf16 v[80:83], v[234:237], v[194:197], v[80:83]
	v_mfma_f32_16x16x32_bf16 v[68:71], v[226:229], v[218:221], v[68:71]
	v_mfma_f32_16x16x32_bf16 v[64:67], v[234:237], v[218:221], v[64:67]
	s_mov_b32 m0, s37
	v_lshl_add_u64 v[240:241], s[30:31], 0, v[144:145]
	s_barrier
	ds_read_b128 v[154:157], v181 offset:16384
	ds_read_b128 v[174:177], v181 offset:17408
	ds_read_b128 v[182:185], v181 offset:18432
	ds_read_b128 v[186:189], v181 offset:19456
	ds_read_b128 v[190:193], v181 offset:20480
	ds_read_b128 v[194:197], v181 offset:21504
	ds_read_b128 v[214:217], v181 offset:22528
	ds_read_b128 v[218:221], v181 offset:23552
	global_load_lds_dwordx4 v144, s[30:31]
	v_lshl_add_u64 v[242:243], s[30:31], 0, v[146:147]
	s_mov_b32 m0, s38
	s_nop 0
	global_load_lds_dwordx4 v146, s[30:31]
	s_barrier
	s_waitcnt lgkmcnt(0)
	v_mfma_f32_16x16x32_bf16 v[60:63], v[128:131], v[154:157], v[60:63]
	v_mfma_f32_16x16x32_bf16 v[56:59], v[136:139], v[154:157], v[56:59]
	v_mfma_f32_16x16x32_bf16 v[44:47], v[128:131], v[182:185], v[44:47]
	v_mfma_f32_16x16x32_bf16 v[40:43], v[136:139], v[182:185], v[40:43]
	v_mfma_f32_16x16x32_bf16 v[28:31], v[128:131], v[190:193], v[28:31]
	v_mfma_f32_16x16x32_bf16 v[24:27], v[136:139], v[190:193], v[24:27]
	v_mfma_f32_16x16x32_bf16 v[12:15], v[128:131], v[214:217], v[12:15]
	v_mfma_f32_16x16x32_bf16 v[8:11], v[136:139], v[214:217], v[8:11]
	v_mfma_f32_16x16x32_bf16 v[60:63], v[132:135], v[174:177], v[60:63]
	v_mfma_f32_16x16x32_bf16 v[56:59], v[140:143], v[174:177], v[56:59]
	v_mfma_f32_16x16x32_bf16 v[44:47], v[132:135], v[186:189], v[44:47]
	v_mfma_f32_16x16x32_bf16 v[40:43], v[140:143], v[186:189], v[40:43]
	v_mfma_f32_16x16x32_bf16 v[28:31], v[132:135], v[194:197], v[28:31]
	v_mfma_f32_16x16x32_bf16 v[24:27], v[140:143], v[194:197], v[24:27]
	v_mfma_f32_16x16x32_bf16 v[12:15], v[132:135], v[218:221], v[12:15]
	v_mfma_f32_16x16x32_bf16 v[8:11], v[140:143], v[218:221], v[8:11]
	s_barrier
	s_add_u32 s50, s28, 0x100000
	s_addc_u32 s51, s29, 0
	s_add_i32 s49, s52, s36
	s_mov_b32 m0, s49
	s_nop 0
	global_load_lds_dwordx4 v160, s[50:51]
	s_add_i32 m0, s49, 0x2000
	s_nop 0
	global_load_lds_dwordx4 v148, s[50:51]
	s_waitcnt vmcnt(6)
	s_barrier
; #define PG8_STAGE(bufoff, gbase, voff) do { _Pragma("unroll") for (int _i = 0; _i < 2; ++_i) \
;         __builtin_amdgcn_global_load_lds((const unsigned*)((const char*)(gbase) + (voff)[_i]), (LAS unsigned*)(lds + (bufoff) + ldsw + _i * 8192), 16, 0, 0); } while (0)
; #define PG8_LDA(dst, b, h) do { _Pragma("unroll") for (int m = 0; m < 4; ++m) _Pragma("unroll") for (int k = 0; k < 2; ++k) dst[m][k] = *(const LAS bf16x8*)(lds + PG8_SA(b, h) + aoff + m * 2048 + k * 1024); } while (0)
; #define PG8_LDB(dst, b, h) do { _Pragma("unroll") for (int n = 0; n < 2; ++n) _Pragma("unroll") for (int k = 0; k < 2; ++k) dst[n][k] = *(const LAS bf16x8*)(lds + PG8_SB(b, h) + boff + n * 2048 + k * 1024); } while (0)
; #define PG8_MMA(ai, bj, At, Bt) do { __builtin_amdgcn_s_setprio(1); _Pragma("unroll") for (int m = 0; m < 4; ++m) _Pragma("unroll") for (int n = 0; n < 2; ++n) _Pragma("unroll") for (int k = 0; k < 2; ++k) \
;         acc[ai][bj][m][n] = __builtin_amdgcn_mfma_f32_16x16x32_bf16(Bt[n][k], At[m][k], acc[ai][bj][m][n], 0, 0, 0); __builtin_amdgcn_s_setprio(0); } while (0)
; #define PG8_WAIT_V(n) asm volatile("s_waitcnt vmcnt(" #n ")" ::: "memory")
; #define PG8_WAIT_L(n) asm volatile("s_waitcnt lgkmcnt(" #n ")" ::: "memory")
; #define PG8_BAR __builtin_amdgcn_s_barrier()
; #define PG8_SCHED __builtin_amdgcn_sched_barrier(0)
; template <class Epi>
; DEV void gemm_phase(LAS unsigned char* lds, const Gemm g, const StaticOrder& S, const Epi& E) {
;     ...
;             PG8_WAIT_V(6); PG8_BAR; PG8_MMA(1, 1, At, B1); PG8_BAR;
;             PG8_LDB(B0, 1, 0); PG8_SCHED; PG8_LDA(At, 1, 0); PG8_STAGE(PG8_SA(0, 1), a2 + hstep, voffA);
;             PG8_WAIT_L(8); PG8_BAR; PG8_WAIT_L(0); PG8_MMA(0, 0, At, B0); PG8_BAR; PG8_SCHED;
;             PG8_LDB(B1, 1, 1); PG8_STAGE(PG8_SB(1, 0), b3, voffB);
;             PG8_BAR; PG8_WAIT_L(0); PG8_MMA(0, 1, At, B1); PG8_BAR;
;             PG8_LDA(At, 1, 1); PG8_STAGE(PG8_SA(1, 0), a3, voffA);
	v_mfma_f32_16x16x32_bf16 v[52:55], v[222:225], v[154:157], v[52:55]
	v_mfma_f32_16x16x32_bf16 v[48:51], v[230:233], v[154:157], v[48:51]
	v_mfma_f32_16x16x32_bf16 v[36:39], v[222:225], v[182:185], v[36:39]
	v_mfma_f32_16x16x32_bf16 v[32:35], v[230:233], v[182:185], v[32:35]
	v_mfma_f32_16x16x32_bf16 v[20:23], v[222:225], v[190:193], v[20:23]
	v_mfma_f32_16x16x32_bf16 v[16:19], v[230:233], v[190:193], v[16:19]
	v_mfma_f32_16x16x32_bf16 v[4:7], v[222:225], v[214:217], v[4:7]
	v_mfma_f32_16x16x32_bf16 v[0:3], v[230:233], v[214:217], v[0:3]
	v_mfma_f32_16x16x32_bf16 v[52:55], v[226:229], v[174:177], v[52:55]
	v_mfma_f32_16x16x32_bf16 v[48:51], v[234:237], v[174:177], v[48:51]
	v_mfma_f32_16x16x32_bf16 v[36:39], v[226:229], v[186:189], v[36:39]
	v_mfma_f32_16x16x32_bf16 v[32:35], v[234:237], v[186:189], v[32:35]
	v_mfma_f32_16x16x32_bf16 v[20:23], v[226:229], v[194:197], v[20:23]
	v_mfma_f32_16x16x32_bf16 v[16:19], v[234:237], v[194:197], v[16:19]
	v_mfma_f32_16x16x32_bf16 v[4:7], v[226:229], v[218:221], v[4:7]
	v_mfma_f32_16x16x32_bf16 v[0:3], v[234:237], v[218:221], v[0:3]
	s_add_i32 s49, 0, 0x18000
	v_add_u32_e32 v140, s49, v178
	s_barrier
	ds_read_b128 v[128:131], v140
	ds_read_b128 v[132:135], v140 offset:1024
	ds_read_b128 v[136:139], v140 offset:2048
	ds_read_b128 v[140:143], v140 offset:3072
	s_add_u32 s30, s30, 0x100000
	s_addc_u32 s31, s31, 0
	s_mov_b32 m0, s39
	ds_read_b128 v[154:157], v181 offset:32768
	ds_read_b128 v[174:177], v181 offset:33792
	ds_read_b128 v[182:185], v181 offset:34816
	ds_read_b128 v[186:189], v181 offset:35840
	ds_read_b128 v[190:193], v181 offset:36864
	ds_read_b128 v[194:197], v181 offset:37888
	ds_read_b128 v[214:217], v181 offset:38912
	ds_read_b128 v[218:221], v181 offset:39936
	global_load_lds_dwordx4 v144, s[30:31]
	s_mov_b32 m0, s40
	s_nop 0
	global_load_lds_dwordx4 v146, s[30:31]
	s_waitcnt lgkmcnt(8)
	s_barrier
	s_waitcnt lgkmcnt(0)
	v_mfma_f32_16x16x32_bf16 v[124:127], v[128:131], v[154:157], v[124:127]
	v_mfma_f32_16x16x32_bf16 v[120:123], v[136:139], v[154:157], v[120:123]
	v_mfma_f32_16x16x32_bf16 v[108:111], v[128:131], v[182:185], v[108:111]
	v_mfma_f32_16x16x32_bf16 v[104:107], v[136:139], v[182:185], v[104:107]
	v_mfma_f32_16x16x32_bf16 v[92:95], v[128:131], v[190:193], v[92:95]
	v_mfma_f32_16x16x32_bf16 v[88:91], v[136:139], v[190:193], v[88:91]
	v_mfma_f32_16x16x32_bf16 v[76:79], v[128:131], v[214:217], v[76:79]
	v_mfma_f32_16x16x32_bf16 v[72:75], v[136:139], v[214:217], v[72:75]
	v_mfma_f32_16x16x32_bf16 v[124:127], v[132:135], v[174:177], v[124:127]
	v_mfma_f32_16x16x32_bf16 v[120:123], v[140:143], v[174:177], v[120:123]
	v_mfma_f32_16x16x32_bf16 v[108:111], v[132:135], v[186:189], v[108:111]
	v_mfma_f32_16x16x32_bf16 v[104:107], v[140:143], v[186:189], v[104:107]
	v_mfma_f32_16x16x32_bf16 v[92:95], v[132:135], v[194:197], v[92:95]
	v_mfma_f32_16x16x32_bf16 v[88:91], v[140:143], v[194:197], v[88:91]
	v_mfma_f32_16x16x32_bf16 v[76:79], v[132:135], v[218:221], v[76:79]
	v_mfma_f32_16x16x32_bf16 v[72:75], v[140:143], v[218:221], v[72:75]
	s_barrier
	s_add_i32 s30, 0, 0x1c000
	s_add_i32 s31, s49, s36
	v_add_u32_e32 v234, s30, v178
	s_add_u32 s100, s28, 0x80
	s_addc_u32 s101, s29, 0
	s_mov_b32 m0, s31
	ds_read_b128 v[222:225], v234
	ds_read_b128 v[226:229], v234 offset:1024
	ds_read_b128 v[230:233], v234 offset:2048
	ds_read_b128 v[234:237], v234 offset:3072
	global_load_lds_dwordx4 v160, s[100:101]
	s_add_i32 m0, s31, 0x2000
	s_nop 0
	global_load_lds_dwordx4 v148, s[100:101]
	s_barrier
	s_waitcnt lgkmcnt(0)
	v_mfma_f32_16x16x32_bf16 v[116:119], v[222:225], v[154:157], v[116:119]
	v_mfma_f32_16x16x32_bf16 v[112:115], v[230:233], v[154:157], v[112:115]
	v_mfma_f32_16x16x32_bf16 v[100:103], v[222:225], v[182:185], v[100:103]
	v_mfma_f32_16x16x32_bf16 v[96:99], v[230:233], v[182:185], v[96:99]
	v_mfma_f32_16x16x32_bf16 v[84:87], v[222:225], v[190:193], v[84:87]
	v_mfma_f32_16x16x32_bf16 v[80:83], v[230:233], v[190:193], v[80:83]
	v_mfma_f32_16x16x32_bf16 v[68:71], v[222:225], v[214:217], v[68:71]
	v_mfma_f32_16x16x32_bf16 v[64:67], v[230:233], v[214:217], v[64:67]
	v_mfma_f32_16x16x32_bf16 v[116:119], v[226:229], v[174:177], v[116:119]
	v_mfma_f32_16x16x32_bf16 v[112:115], v[234:237], v[174:177], v[112:115]
	v_mfma_f32_16x16x32_bf16 v[100:103], v[226:229], v[186:189], v[100:103]
	v_mfma_f32_16x16x32_bf16 v[96:99], v[234:237], v[186:189], v[96:99]
	v_mfma_f32_16x16x32_bf16 v[84:87], v[226:229], v[194:197], v[84:87]
	v_mfma_f32_16x16x32_bf16 v[80:83], v[234:237], v[194:197], v[80:83]
	v_mfma_f32_16x16x32_bf16 v[68:71], v[226:229], v[218:221], v[68:71]
	v_mfma_f32_16x16x32_bf16 v[64:67], v[234:237], v[218:221], v[64:67]
	s_mov_b32 m0, s41
	v_lshl_add_u64 v[158:159], v[240:241], 0, s[2:3]
	s_barrier
	ds_read_b128 v[154:157], v181 offset:49152
	ds_read_b128 v[174:177], v181 offset:50176
	ds_read_b128 v[182:185], v181 offset:51200
	ds_read_b128 v[186:189], v181 offset:52224
	ds_read_b128 v[190:193], v181 offset:53248
	ds_read_b128 v[194:197], v181 offset:54272
	ds_read_b128 v[214:217], v181 offset:55296
	ds_read_b128 v[218:221], v181 offset:56320
	global_load_lds_dwordx4 v[158:159], off
	v_lshl_add_u64 v[158:159], v[242:243], 0, s[2:3]
	s_mov_b32 m0, s42
	s_nop 0
	global_load_lds_dwordx4 v[158:159], off
	s_barrier
; DEV bf16x8 pack8(f32x4 a, f32x4 b) { u32x4 w; w.x = cvt_pk_bf16(a[0], a[1]); w.y = cvt_pk_bf16(a[2], a[3]); w.z = cvt_pk_bf16(b[0], b[1]); w.w = cvt_pk_bf16(b[2], b[3]); return __builtin_bit_cast(bf16x8, w); }
; #define PG8_WAIT_V(n) asm volatile("s_waitcnt vmcnt(" #n ")" ::: "memory")
; #define PG8_WAIT_L(n) asm volatile("s_waitcnt lgkmcnt(" #n ")" ::: "memory")
; #define PG8_BAR __builtin_amdgcn_s_barrier()
; template <class Epi>
; DEV void gemm_phase(LAS unsigned char* lds, const Gemm g, const StaticOrder& S, const Epi& E) {
;     ...
;             PG8_BAR; PG8_WAIT_L(0); PG8_MMA(1, 0, At, B0); PG8_BAR; PG8_SCHED;
;             PG8_STAGE(PG8_SB(1, 1), b3 + hstep, voffB);
;             PG8_WAIT_V(6); PG8_BAR; PG8_MMA(1, 1, At, B1); PG8_BAR;
;         }
;     DEV void operator()(AccRef acc, const pg8::Unit& u, int wr, int wc, int fr, int fq) const {
;         const int row0 = u.pm * 256 + wr * 64 + fr, col0 = u.pn * 256 + wc * 32 + 8 * fq;
; #pragma unroll
;         for (int am = 0; am < 4; ++am) { const int ai = am >> 1, m0 = (am & 1) * 2;
;             f32x4 bv[4][2][2];
; #pragma unroll
;             for (int m = m0; m < m0 + 2; ++m)
; #pragma unroll
;                 for (int bj = 0; bj < 2; ++bj)
; #pragma unroll
;                     for (int n = 0; n < 2; ++n) bv[m][bj][n] = *(const f32x4*)(base + (size_t)(row0 + ai * 128 + m * 16) * 2048 + col0 + bj * 128 + n * 4);
; #pragma unroll
;             for (int m = m0; m < m0 + 2; ++m) { const size_t off = (size_t)(row0 + ai * 128 + m * 16) * 2048 + col0; float sq = 0.f;
; #pragma unroll
;                 for (int bj = 0; bj < 2; ++bj) { const f32x4 o0 = bv[m][bj][0] + scale * acc[ai][bj][m][0], o1 = bv[m][bj][1] + scale * acc[ai][bj][m][1];
;                     *(f32x4*)(out + off + bj * 128) = o0; *(f32x4*)(out + off + bj * 128 + 4) = o1;
;                     if (xb) { *(u32x4*)(xb + off + bj * 128) = __builtin_bit_cast(u32x4, pack8(o0, o1));
;                         sq += (o0[0] * o0[0] + o0[1] * o0[1] + o0[2] * o0[2] + o0[3] * o0[3]) + (o1[0] * o1[0] + o1[1] * o1[1] + o1[2] * o1[2] + o1[3] * o1[3]); } }
;                 if (ssout) { sq += __shfl_xor(sq, 16); sq += __shfl_xor(sq, 32);
;                     if (fq == 0) { if (red) red[(ai * 128 + wr * 64 + m * 16 + fr) * 4 + wc] = sq; else atomicAdd(ssout + (size_t)(row0 + ai * 128 + m * 16) * 8 + u.pn, sq); } } }
	s_waitcnt lgkmcnt(0)
	v_mfma_f32_16x16x32_bf16 v[60:63], v[128:131], v[154:157], v[60:63]
	v_mfma_f32_16x16x32_bf16 v[56:59], v[136:139], v[154:157], v[56:59]
	v_mfma_f32_16x16x32_bf16 v[44:47], v[128:131], v[182:185], v[44:47]
	v_mfma_f32_16x16x32_bf16 v[40:43], v[136:139], v[182:185], v[40:43]
	v_mfma_f32_16x16x32_bf16 v[28:31], v[128:131], v[190:193], v[28:31]
	v_mfma_f32_16x16x32_bf16 v[24:27], v[136:139], v[190:193], v[24:27]
	v_mfma_f32_16x16x32_bf16 v[12:15], v[128:131], v[214:217], v[12:15]
	v_mfma_f32_16x16x32_bf16 v[8:11], v[136:139], v[214:217], v[8:11]
	v_mfma_f32_16x16x32_bf16 v[60:63], v[132:135], v[174:177], v[60:63]
	v_mfma_f32_16x16x32_bf16 v[56:59], v[140:143], v[174:177], v[56:59]
	v_mfma_f32_16x16x32_bf16 v[44:47], v[132:135], v[186:189], v[44:47]
	v_mfma_f32_16x16x32_bf16 v[40:43], v[140:143], v[186:189], v[40:43]
	v_mfma_f32_16x16x32_bf16 v[28:31], v[132:135], v[194:197], v[28:31]
	v_mfma_f32_16x16x32_bf16 v[24:27], v[140:143], v[194:197], v[24:27]
	v_mfma_f32_16x16x32_bf16 v[12:15], v[132:135], v[218:221], v[12:15]
	v_mfma_f32_16x16x32_bf16 v[8:11], v[140:143], v[218:221], v[8:11]
	s_barrier
	s_add_u32 s28, s28, 0x100080
	s_addc_u32 s29, s29, 0
	s_add_i32 s30, s30, s36
	s_mov_b32 m0, s30
	s_nop 0
	global_load_lds_dwordx4 v160, s[28:29]
	s_add_i32 m0, s30, 0x2000
	s_nop 0
	global_load_lds_dwordx4 v148, s[28:29]
	s_waitcnt vmcnt(6)
	s_barrier
	v_mfma_f32_16x16x32_bf16 v[52:55], v[222:225], v[154:157], v[52:55]
	v_mfma_f32_16x16x32_bf16 v[48:51], v[230:233], v[154:157], v[48:51]
	v_mfma_f32_16x16x32_bf16 v[36:39], v[222:225], v[182:185], v[36:39]
	v_mfma_f32_16x16x32_bf16 v[32:35], v[230:233], v[182:185], v[32:35]
	v_mfma_f32_16x16x32_bf16 v[20:23], v[222:225], v[190:193], v[20:23]
	v_mfma_f32_16x16x32_bf16 v[16:19], v[230:233], v[190:193], v[16:19]
	v_mfma_f32_16x16x32_bf16 v[4:7], v[222:225], v[214:217], v[4:7]
	v_mfma_f32_16x16x32_bf16 v[0:3], v[230:233], v[214:217], v[0:3]
	v_mfma_f32_16x16x32_bf16 v[52:55], v[226:229], v[174:177], v[52:55]
	v_mfma_f32_16x16x32_bf16 v[48:51], v[234:237], v[174:177], v[48:51]
	v_mfma_f32_16x16x32_bf16 v[36:39], v[226:229], v[186:189], v[36:39]
	v_mfma_f32_16x16x32_bf16 v[32:35], v[234:237], v[186:189], v[32:35]
	v_mfma_f32_16x16x32_bf16 v[20:23], v[226:229], v[194:197], v[20:23]
	v_mfma_f32_16x16x32_bf16 v[16:19], v[234:237], v[194:197], v[16:19]
	v_mfma_f32_16x16x32_bf16 v[4:7], v[226:229], v[218:221], v[4:7]
	v_mfma_f32_16x16x32_bf16 v[0:3], v[234:237], v[218:221], v[0:3]
	s_add_i32 s48, s48, 2
	s_add_u32 s26, s26, 0x100
	s_addc_u32 s27, s27, 0
	s_add_u32 s46, s46, 0x100
	s_addc_u32 s47, s47, 0
	s_cmp_gt_u32 s48, 61
	s_barrier
	s_cbranch_scc0 .LBB0_404
	v_lshl_add_u32 v156, s24, 8, v167
	v_lshl_or_b32 v154, s14, 8, v179
	v_readlane_b32 s24, v254, 16
	v_ashrrev_i32_e32 v155, 31, v154
	v_readlane_b32 s25, v254, 17
	v_ashrrev_i32_e32 v157, 31, v156
	v_lshlrev_b64 v[128:129], 13, v[156:157]
	v_lshl_add_u64 v[158:159], v[154:155], 2, s[24:25]
	v_lshl_add_u64 v[214:215], v[158:159], 0, v[128:129]
	global_load_dwordx4 v[182:185], v[214:215], off offset:16
	global_load_dwordx4 v[186:189], v[214:215], off
	global_load_dwordx4 v[190:193], v[214:215], off offset:528
	global_load_dwordx4 v[194:197], v[214:215], off offset:512
	v_or_b32_e32 v174, 16, v156
	v_ashrrev_i32_e32 v175, 31, v174
	v_lshlrev_b64 v[128:129], 13, v[174:175]
	v_lshl_add_u64 v[176:177], v[158:159], 0, v[128:129]
	global_load_dwordx4 v[136:139], v[176:177], off offset:16
	global_load_dwordx4 v[140:143], v[176:177], off
	global_load_dwordx4 v[128:131], v[176:177], off offset:528
	global_load_dwordx4 v[132:135], v[176:177], off offset:512
	v_lshlrev_b64 v[216:217], 11, v[156:157]
	v_readlane_b32 s24, v250, 9
	v_lshl_add_u64 v[216:217], v[216:217], 0, v[154:155]
	v_readlane_b32 s25, v250, 10
	v_cmp_lt_i32_e32 vcc, v208, v206
	s_ashr_i32 s15, s14, 31
	s_waitcnt vmcnt(0)
	v_pk_add_f32 v[120:121], v[120:121], v[182:183]
	v_pk_add_f32 v[126:127], v[126:127], v[188:189]
	v_pk_add_f32 v[124:125], v[124:125], v[186:187]
	v_pk_add_f32 v[122:123], v[122:123], v[184:185]
	global_store_dwordx4 v[214:215], v[124:127], off
	global_store_dwordx4 v[214:215], v[120:123], off offset:16
	v_cvt_pk_bf16_f32 v184, v120, v121
	v_cvt_pk_bf16_f32 v182, v124, v125
	v_mul_f32_e32 v121, v121, v121
	v_cvt_pk_bf16_f32 v183, v126, v127
	v_cvt_pk_bf16_f32 v185, v122, v123
	v_lshl_add_u64 v[186:187], v[216:217], 1, s[24:25]
	v_fmac_f32_e32 v121, v120, v120
	v_pk_add_f32 v[118:119], v[118:119], v[196:197]
	v_pk_add_f32 v[116:117], v[116:117], v[194:195]
	v_pk_add_f32 v[112:113], v[112:113], v[190:191]
	global_store_dwordx4 v[186:187], v[182:185], off
	v_mul_f32_e32 v125, v125, v125
	v_fmac_f32_e32 v121, v122, v122
	v_pk_add_f32 v[114:115], v[114:115], v[192:193]
	global_store_dwordx4 v[214:215], v[116:119], off offset:512
	global_store_dwordx4 v[214:215], v[112:115], off offset:528
	v_cvt_pk_bf16_f32 v120, v116, v117
	v_cvt_pk_bf16_f32 v122, v112, v113
	v_mul_f32_e32 v117, v117, v117
	v_mul_f32_e32 v113, v113, v113
	v_fmac_f32_e32 v125, v124, v124
	v_fmac_f32_e32 v117, v116, v116
	v_fmac_f32_e32 v113, v112, v112
	v_fmac_f32_e32 v125, v126, v126
	v_fmac_f32_e32 v117, v118, v118
	v_fmac_f32_e32 v113, v114, v114
	v_fmac_f32_e32 v125, v127, v127
	v_fmac_f32_e32 v121, v123, v123
	v_fmac_f32_e32 v117, v119, v119
	v_fmac_f32_e32 v113, v115, v115
	v_add_f32_e32 v124, v125, v121
	v_add_f32_e32 v112, v117, v113
	v_cndmask_b32_e32 v113, v204, v208, vcc
	v_cvt_pk_bf16_f32 v121, v118, v119
	v_add_f32_e32 v112, v124, v112
	v_lshlrev_b32_e32 v118, 2, v113
	ds_bpermute_b32 v113, v118, v112
	v_cmp_lt_i32_e32 vcc, v207, v206
	v_cvt_pk_bf16_f32 v123, v114, v115
	global_store_dwordx4 v[186:187], v[120:123], off offset:256
	s_waitcnt lgkmcnt(0)
	v_add_f32_e32 v112, v112, v113
	v_cndmask_b32_e32 v113, v204, v207, vcc
	v_lshlrev_b32_e32 v119, 2, v113
	ds_bpermute_b32 v113, v119, v112
	s_and_saveexec_b64 s[24:25], s[6:7]
	s_cbranch_execz .LBB0_410
	s_waitcnt lgkmcnt(0)
	v_add_f32_e32 v112, v112, v113
	s_mov_b64 s[26:27], -1
	s_and_b64 vcc, exec, s[12:13]
	s_cbranch_vccz .LBB0_408
	v_readlane_b32 s26, v250, 59
	v_lshlrev_b64 v[114:115], 5, v[156:157]
	v_readlane_b32 s27, v250, 60
	s_nop 1
	v_lshl_add_u64 v[114:115], s[26:27], 0, v[114:115]
	v_lshl_add_u64 v[114:115], s[14:15], 2, v[114:115]
	global_atomic_add_f32 v[114:115], v112, off
	s_mov_b64 s[26:27], 0

; #define PG8_STAGE(bufoff, gbase, voff) do { _Pragma("unroll") for (int _i = 0; _i < 2; ++_i) \
;         __builtin_amdgcn_global_load_lds((const unsigned*)((const char*)(gbase) + (voff)[_i]), (LAS unsigned*)(lds + (bufoff) + ldsw + _i * 8192), 16, 0, 0); } while (0)
; #define PG8_LDA(dst, b, h) do { _Pragma("unroll") for (int m = 0; m < 4; ++m) _Pragma("unroll") for (int k = 0; k < 2; ++k) dst[m][k] = *(const LAS bf16x8*)(lds + PG8_SA(b, h) + aoff + m * 2048 + k * 1024); } while (0)
; #define PG8_LDB(dst, b, h) do { _Pragma("unroll") for (int n = 0; n < 2; ++n) _Pragma("unroll") for (int k = 0; k < 2; ++k) dst[n][k] = *(const LAS bf16x8*)(lds + PG8_SB(b, h) + boff + n * 2048 + k * 1024); } while (0)
; #define PG8_MMA(ai, bj, At, Bt) do { __builtin_amdgcn_s_setprio(1); _Pragma("unroll") for (int m = 0; m < 4; ++m) _Pragma("unroll") for (int n = 0; n < 2; ++n) _Pragma("unroll") for (int k = 0; k < 2; ++k) \
;         acc[ai][bj][m][n] = __builtin_amdgcn_mfma_f32_16x16x32_bf16(Bt[n][k], At[m][k], acc[ai][bj][m][n], 0, 0, 0); __builtin_amdgcn_s_setprio(0); } while (0)
; #define PG8_WAIT_V(n) asm volatile("s_waitcnt vmcnt(" #n ")" ::: "memory")
; #define PG8_WAIT_L(n) asm volatile("s_waitcnt lgkmcnt(" #n ")" ::: "memory")
; #define PG8_BAR __builtin_amdgcn_s_barrier()
; #define PG8_SCHED __builtin_amdgcn_sched_barrier(0)
; template <class Epi>
; DEV void gemm_phase(LAS unsigned char* lds, const Gemm g, const StaticOrder& S, const Epi& E) {
;     ...
;             const bool last = (t == nt - 2);
;             const char* a1 = cA + (size_t)(t + 1) * kstep;
;             const char* a2 = last ? nA : cA + (size_t)(t + 2) * kstep; const char* b2 = last ? nB : cB + (size_t)(t + 2) * kstep;
;             const char* a3 = a2 + kstep; const char* b3 = b2 + kstep;
;             PG8_LDB(B0, 0, 0); PG8_SCHED; PG8_LDA(At, 0, 0); PG8_STAGE(PG8_SA(1, 1), a1 + hstep, voffA);
;             PG8_WAIT_L(8); PG8_BAR; PG8_WAIT_L(0); PG8_MMA(0, 0, At, B0); PG8_BAR; PG8_SCHED;
;             PG8_LDB(B1, 0, 1); PG8_STAGE(PG8_SB(0, 0), b2, voffB);
;             PG8_BAR; PG8_WAIT_L(0); PG8_MMA(0, 1, At, B1); PG8_BAR;
;             PG8_LDA(At, 0, 1); PG8_STAGE(PG8_SA(0, 0), a2, voffA);
;             PG8_BAR; PG8_WAIT_L(0); PG8_MMA(1, 0, At, B0); PG8_BAR; PG8_SCHED;
;             PG8_STAGE(PG8_SB(0, 1), b2 + hstep, voffB);
;             PG8_WAIT_V(6); PG8_BAR; PG8_MMA(1, 1, At, B1); PG8_BAR;
.LBB0_588:
	s_add_u32 s16, s14, 0xfff80080
	s_addc_u32 s17, s15, -1
	s_add_i32 s41, 0, 0x10000
	v_add_u32_e32 v154, s41, v167
	ds_read_b128 v[128:131], v154
	ds_read_b128 v[132:135], v154 offset:1024
	ds_read_b128 v[150:153], v154 offset:2048
	ds_read_b128 v[174:177], v154 offset:3072
	s_cmp_eq_u32 s40, 28
	s_cselect_b32 s19, s1, s17
	s_cselect_b32 s18, s9, s16
	s_cselect_b32 s17, s7, s37
	s_cselect_b32 s16, s35, s36
	s_add_i32 m0, s24, 0xc000
	ds_read_b128 v[182:185], v219
	ds_read_b128 v[190:193], v219 offset:1024
	ds_read_b128 v[194:197], v219 offset:2048
	ds_read_b128 v[220:223], v219 offset:3072
	ds_read_b128 v[224:227], v219 offset:4096
	ds_read_b128 v[228:231], v219 offset:5120
	ds_read_b128 v[232:235], v219 offset:6144
	ds_read_b128 v[236:239], v219 offset:7168
	global_load_lds_dwordx4 v146, s[14:15]
	s_add_i32 m0, s24, 0xe000
	s_nop 0
	global_load_lds_dwordx4 v148, s[14:15]
	s_waitcnt lgkmcnt(8)
	s_barrier
	s_waitcnt lgkmcnt(0)
	v_mfma_f32_16x16x32_bf16 v[124:127], v[128:131], v[182:185], v[124:127]
	v_mfma_f32_16x16x32_bf16 v[120:123], v[150:153], v[182:185], v[120:123]
	v_mfma_f32_16x16x32_bf16 v[108:111], v[128:131], v[194:197], v[108:111]
	v_mfma_f32_16x16x32_bf16 v[104:107], v[150:153], v[194:197], v[104:107]
	v_mfma_f32_16x16x32_bf16 v[92:95], v[128:131], v[224:227], v[92:95]
	v_mfma_f32_16x16x32_bf16 v[88:91], v[150:153], v[224:227], v[88:91]
	v_mfma_f32_16x16x32_bf16 v[76:79], v[128:131], v[232:235], v[76:79]
	v_mfma_f32_16x16x32_bf16 v[72:75], v[150:153], v[232:235], v[72:75]
	v_mfma_f32_16x16x32_bf16 v[124:127], v[132:135], v[190:193], v[124:127]
	v_mfma_f32_16x16x32_bf16 v[120:123], v[174:177], v[190:193], v[120:123]
	v_mfma_f32_16x16x32_bf16 v[108:111], v[132:135], v[220:223], v[108:111]
	v_mfma_f32_16x16x32_bf16 v[104:107], v[174:177], v[220:223], v[104:107]
	v_mfma_f32_16x16x32_bf16 v[92:95], v[132:135], v[228:231], v[92:95]
	v_mfma_f32_16x16x32_bf16 v[88:91], v[174:177], v[228:231], v[88:91]
	v_mfma_f32_16x16x32_bf16 v[76:79], v[132:135], v[236:239], v[76:79]
	v_mfma_f32_16x16x32_bf16 v[72:75], v[174:177], v[236:239], v[72:75]
	s_barrier
	s_add_i32 s44, 0, 0x14000
	v_add_u32_e32 v154, s44, v167
	s_add_i32 s41, s41, s22
	ds_read_b128 v[240:243], v154
	ds_read_b128 v[244:247], v154 offset:1024
	ds_read_b128 v[186:189], v154 offset:2048
	ds_read_b128 v[214:217], v154 offset:3072
	s_mov_b32 m0, s41
	s_nop 0
	global_load_lds_dwordx4 v140, s[16:17]
	s_add_i32 m0, s41, 0x2000
	s_nop 0
	global_load_lds_dwordx4 v136, s[16:17]
	s_barrier
	s_waitcnt lgkmcnt(0)
	v_mfma_f32_16x16x32_bf16 v[116:119], v[240:243], v[182:185], v[116:119]
	v_mfma_f32_16x16x32_bf16 v[112:115], v[186:189], v[182:185], v[112:115]
	v_mfma_f32_16x16x32_bf16 v[100:103], v[240:243], v[194:197], v[100:103]
	v_mfma_f32_16x16x32_bf16 v[96:99], v[186:189], v[194:197], v[96:99]
	v_mfma_f32_16x16x32_bf16 v[84:87], v[240:243], v[224:227], v[84:87]
	v_mfma_f32_16x16x32_bf16 v[80:83], v[186:189], v[224:227], v[80:83]
	v_mfma_f32_16x16x32_bf16 v[68:71], v[240:243], v[232:235], v[68:71]
	v_mfma_f32_16x16x32_bf16 v[64:67], v[186:189], v[232:235], v[64:67]
	v_mfma_f32_16x16x32_bf16 v[116:119], v[244:247], v[190:193], v[116:119]
	v_mfma_f32_16x16x32_bf16 v[112:115], v[214:217], v[190:193], v[112:115]
	v_mfma_f32_16x16x32_bf16 v[100:103], v[244:247], v[220:223], v[100:103]
	v_mfma_f32_16x16x32_bf16 v[96:99], v[214:217], v[220:223], v[96:99]
	v_mfma_f32_16x16x32_bf16 v[84:87], v[244:247], v[228:231], v[84:87]
	v_mfma_f32_16x16x32_bf16 v[80:83], v[214:217], v[228:231], v[80:83]
	v_mfma_f32_16x16x32_bf16 v[68:71], v[244:247], v[236:239], v[68:71]
	v_mfma_f32_16x16x32_bf16 v[64:67], v[214:217], v[236:239], v[64:67]
	s_mov_b32 m0, s24
	v_lshl_add_u64 v[178:179], s[18:19], 0, v[142:143]
	s_barrier
	ds_read_b128 v[182:185], v219 offset:16384
	ds_read_b128 v[190:193], v219 offset:17408
	ds_read_b128 v[194:197], v219 offset:18432
	ds_read_b128 v[220:223], v219 offset:19456
	ds_read_b128 v[224:227], v219 offset:20480
	ds_read_b128 v[228:231], v219 offset:21504
	ds_read_b128 v[232:235], v219 offset:22528
	ds_read_b128 v[236:239], v219 offset:23552
	global_load_lds_dwordx4 v142, s[18:19]
	v_lshl_add_u64 v[248:249], s[18:19], 0, v[138:139]
	s_mov_b32 m0, s25
	s_nop 0
	global_load_lds_dwordx4 v138, s[18:19]
	s_barrier
	s_waitcnt lgkmcnt(0)
	v_mfma_f32_16x16x32_bf16 v[60:63], v[128:131], v[182:185], v[60:63]
	v_mfma_f32_16x16x32_bf16 v[56:59], v[150:153], v[182:185], v[56:59]
	v_mfma_f32_16x16x32_bf16 v[44:47], v[128:131], v[194:197], v[44:47]
	v_mfma_f32_16x16x32_bf16 v[40:43], v[150:153], v[194:197], v[40:43]
	v_mfma_f32_16x16x32_bf16 v[28:31], v[128:131], v[224:227], v[28:31]
	v_mfma_f32_16x16x32_bf16 v[24:27], v[150:153], v[224:227], v[24:27]
	v_mfma_f32_16x16x32_bf16 v[12:15], v[128:131], v[232:235], v[12:15]
	v_mfma_f32_16x16x32_bf16 v[8:11], v[150:153], v[232:235], v[8:11]
	v_mfma_f32_16x16x32_bf16 v[60:63], v[132:135], v[190:193], v[60:63]
	v_mfma_f32_16x16x32_bf16 v[56:59], v[174:177], v[190:193], v[56:59]
	v_mfma_f32_16x16x32_bf16 v[44:47], v[132:135], v[220:223], v[44:47]
	v_mfma_f32_16x16x32_bf16 v[40:43], v[174:177], v[220:223], v[40:43]
	v_mfma_f32_16x16x32_bf16 v[28:31], v[132:135], v[228:231], v[28:31]
	v_mfma_f32_16x16x32_bf16 v[24:27], v[174:177], v[228:231], v[24:27]
	v_mfma_f32_16x16x32_bf16 v[12:15], v[132:135], v[236:239], v[12:15]
	v_mfma_f32_16x16x32_bf16 v[8:11], v[174:177], v[236:239], v[8:11]
	s_barrier
	s_add_u32 s42, s16, 0x80000
	s_addc_u32 s43, s17, 0
	s_add_i32 s41, s44, s22
	s_mov_b32 m0, s41
	s_nop 0
	global_load_lds_dwordx4 v140, s[42:43]
	s_add_i32 m0, s41, 0x2000
	s_nop 0
	global_load_lds_dwordx4 v136, s[42:43]
	s_waitcnt vmcnt(6)
	s_barrier
; #define PG8_STAGE(bufoff, gbase, voff) do { _Pragma("unroll") for (int _i = 0; _i < 2; ++_i) \
;         __builtin_amdgcn_global_load_lds((const unsigned*)((const char*)(gbase) + (voff)[_i]), (LAS unsigned*)(lds + (bufoff) + ldsw + _i * 8192), 16, 0, 0); } while (0)
; #define PG8_LDA(dst, b, h) do { _Pragma("unroll") for (int m = 0; m < 4; ++m) _Pragma("unroll") for (int k = 0; k < 2; ++k) dst[m][k] = *(const LAS bf16x8*)(lds + PG8_SA(b, h) + aoff + m * 2048 + k * 1024); } while (0)
; #define PG8_LDB(dst, b, h) do { _Pragma("unroll") for (int n = 0; n < 2; ++n) _Pragma("unroll") for (int k = 0; k < 2; ++k) dst[n][k] = *(const LAS bf16x8*)(lds + PG8_SB(b, h) + boff + n * 2048 + k * 1024); } while (0)
; #define PG8_MMA(ai, bj, At, Bt) do { __builtin_amdgcn_s_setprio(1); _Pragma("unroll") for (int m = 0; m < 4; ++m) _Pragma("unroll") for (int n = 0; n < 2; ++n) _Pragma("unroll") for (int k = 0; k < 2; ++k) \
;         acc[ai][bj][m][n] = __builtin_amdgcn_mfma_f32_16x16x32_bf16(Bt[n][k], At[m][k], acc[ai][bj][m][n], 0, 0, 0); __builtin_amdgcn_s_setprio(0); } while (0)
; #define PG8_WAIT_V(n) asm volatile("s_waitcnt vmcnt(" #n ")" ::: "memory")
; #define PG8_WAIT_L(n) asm volatile("s_waitcnt lgkmcnt(" #n ")" ::: "memory")
; #define PG8_BAR __builtin_amdgcn_s_barrier()
; #define PG8_SCHED __builtin_amdgcn_sched_barrier(0)
; template <class Epi>
; DEV void gemm_phase(LAS unsigned char* lds, const Gemm g, const StaticOrder& S, const Epi& E) {
;     ...
;             PG8_WAIT_V(6); PG8_BAR; PG8_MMA(1, 1, At, B1); PG8_BAR;
;             PG8_LDB(B0, 1, 0); PG8_SCHED; PG8_LDA(At, 1, 0); PG8_STAGE(PG8_SA(0, 1), a2 + hstep, voffA);
;             PG8_WAIT_L(8); PG8_BAR; PG8_WAIT_L(0); PG8_MMA(0, 0, At, B0); PG8_BAR; PG8_SCHED;
;             PG8_LDB(B1, 1, 1); PG8_STAGE(PG8_SB(1, 0), b3, voffB);
;             PG8_BAR; PG8_WAIT_L(0); PG8_MMA(0, 1, At, B1); PG8_BAR;
;             PG8_LDA(At, 1, 1); PG8_STAGE(PG8_SA(1, 0), a3, voffA);
	v_mfma_f32_16x16x32_bf16 v[52:55], v[240:243], v[182:185], v[52:55]
	v_mfma_f32_16x16x32_bf16 v[48:51], v[186:189], v[182:185], v[48:51]
	v_mfma_f32_16x16x32_bf16 v[36:39], v[240:243], v[194:197], v[36:39]
	v_mfma_f32_16x16x32_bf16 v[32:35], v[186:189], v[194:197], v[32:35]
	v_mfma_f32_16x16x32_bf16 v[20:23], v[240:243], v[224:227], v[20:23]
	v_mfma_f32_16x16x32_bf16 v[16:19], v[186:189], v[224:227], v[16:19]
	v_mfma_f32_16x16x32_bf16 v[4:7], v[240:243], v[232:235], v[4:7]
	v_mfma_f32_16x16x32_bf16 v[0:3], v[186:189], v[232:235], v[0:3]
	v_mfma_f32_16x16x32_bf16 v[52:55], v[244:247], v[190:193], v[52:55]
	v_mfma_f32_16x16x32_bf16 v[48:51], v[214:217], v[190:193], v[48:51]
	v_mfma_f32_16x16x32_bf16 v[36:39], v[244:247], v[220:223], v[36:39]
	v_mfma_f32_16x16x32_bf16 v[32:35], v[214:217], v[220:223], v[32:35]
	v_mfma_f32_16x16x32_bf16 v[20:23], v[244:247], v[228:231], v[20:23]
	v_mfma_f32_16x16x32_bf16 v[16:19], v[214:217], v[228:231], v[16:19]
	v_mfma_f32_16x16x32_bf16 v[4:7], v[244:247], v[236:239], v[4:7]
	v_mfma_f32_16x16x32_bf16 v[0:3], v[214:217], v[236:239], v[0:3]
	s_add_i32 s41, 0, 0x18000
	v_add_u32_e32 v156, s41, v167
	s_barrier
	ds_read_b128 v[128:131], v156
	ds_read_b128 v[132:135], v156 offset:1024
	ds_read_b128 v[150:153], v156 offset:2048
	ds_read_b128 v[174:177], v156 offset:3072
	s_add_u32 s18, s18, 0x80000
	s_addc_u32 s19, s19, 0
	s_mov_b32 m0, s26
	ds_read_b128 v[182:185], v219 offset:32768
	ds_read_b128 v[186:189], v219 offset:33792
	ds_read_b128 v[190:193], v219 offset:34816
	ds_read_b128 v[194:197], v219 offset:35840
	ds_read_b128 v[214:217], v219 offset:36864
	ds_read_b128 v[220:223], v219 offset:37888
	ds_read_b128 v[224:227], v219 offset:38912
	ds_read_b128 v[228:231], v219 offset:39936
	global_load_lds_dwordx4 v142, s[18:19]
	s_mov_b32 m0, s27
	s_nop 0
	global_load_lds_dwordx4 v138, s[18:19]
	s_waitcnt lgkmcnt(8)
	s_barrier
	s_waitcnt lgkmcnt(0)
	v_mfma_f32_16x16x32_bf16 v[124:127], v[128:131], v[182:185], v[124:127]
	v_mfma_f32_16x16x32_bf16 v[120:123], v[150:153], v[182:185], v[120:123]
	v_mfma_f32_16x16x32_bf16 v[108:111], v[128:131], v[190:193], v[108:111]
	v_mfma_f32_16x16x32_bf16 v[104:107], v[150:153], v[190:193], v[104:107]
	v_mfma_f32_16x16x32_bf16 v[92:95], v[128:131], v[214:217], v[92:95]
	v_mfma_f32_16x16x32_bf16 v[88:91], v[150:153], v[214:217], v[88:91]
	v_mfma_f32_16x16x32_bf16 v[76:79], v[128:131], v[224:227], v[76:79]
	v_mfma_f32_16x16x32_bf16 v[72:75], v[150:153], v[224:227], v[72:75]
	v_mfma_f32_16x16x32_bf16 v[124:127], v[132:135], v[186:189], v[124:127]
	v_mfma_f32_16x16x32_bf16 v[120:123], v[174:177], v[186:189], v[120:123]
	v_mfma_f32_16x16x32_bf16 v[108:111], v[132:135], v[194:197], v[108:111]
	v_mfma_f32_16x16x32_bf16 v[104:107], v[174:177], v[194:197], v[104:107]
	v_mfma_f32_16x16x32_bf16 v[92:95], v[132:135], v[220:223], v[92:95]
	v_mfma_f32_16x16x32_bf16 v[88:91], v[174:177], v[220:223], v[88:91]
	v_mfma_f32_16x16x32_bf16 v[76:79], v[132:135], v[228:231], v[76:79]
	v_mfma_f32_16x16x32_bf16 v[72:75], v[174:177], v[228:231], v[72:75]
	s_barrier
	s_add_i32 s18, 0, 0x1c000
	s_add_i32 s19, s41, s22
	v_add_u32_e32 v156, s18, v167
	s_add_u32 s100, s16, 0x80
	s_addc_u32 s101, s17, 0
	s_mov_b32 m0, s19
	ds_read_b128 v[232:235], v156
	ds_read_b128 v[236:239], v156 offset:1024
	ds_read_b128 v[240:243], v156 offset:2048
	ds_read_b128 v[244:247], v156 offset:3072
	global_load_lds_dwordx4 v140, s[100:101]
	s_add_i32 m0, s19, 0x2000
	s_nop 0
	global_load_lds_dwordx4 v136, s[100:101]
	s_barrier
	s_waitcnt lgkmcnt(0)
	v_mfma_f32_16x16x32_bf16 v[116:119], v[232:235], v[182:185], v[116:119]
	v_mfma_f32_16x16x32_bf16 v[112:115], v[240:243], v[182:185], v[112:115]
	v_mfma_f32_16x16x32_bf16 v[100:103], v[232:235], v[190:193], v[100:103]
	v_mfma_f32_16x16x32_bf16 v[96:99], v[240:243], v[190:193], v[96:99]
	v_mfma_f32_16x16x32_bf16 v[84:87], v[232:235], v[214:217], v[84:87]
	v_mfma_f32_16x16x32_bf16 v[80:83], v[240:243], v[214:217], v[80:83]
	v_mfma_f32_16x16x32_bf16 v[68:71], v[232:235], v[224:227], v[68:71]
	v_mfma_f32_16x16x32_bf16 v[64:67], v[240:243], v[224:227], v[64:67]
	v_mfma_f32_16x16x32_bf16 v[116:119], v[236:239], v[186:189], v[116:119]
	v_mfma_f32_16x16x32_bf16 v[112:115], v[244:247], v[186:189], v[112:115]
	v_mfma_f32_16x16x32_bf16 v[100:103], v[236:239], v[194:197], v[100:103]
	v_mfma_f32_16x16x32_bf16 v[96:99], v[244:247], v[194:197], v[96:99]
	v_mfma_f32_16x16x32_bf16 v[84:87], v[236:239], v[220:223], v[84:87]
	v_mfma_f32_16x16x32_bf16 v[80:83], v[244:247], v[220:223], v[80:83]
	v_mfma_f32_16x16x32_bf16 v[68:71], v[236:239], v[228:231], v[68:71]
	v_mfma_f32_16x16x32_bf16 v[64:67], v[244:247], v[228:231], v[64:67]
	s_mov_b32 m0, s28
	v_lshl_add_u64 v[154:155], v[178:179], 0, s[2:3]
	s_barrier
	ds_read_b128 v[182:185], v219 offset:49152
	ds_read_b128 v[186:189], v219 offset:50176
	ds_read_b128 v[190:193], v219 offset:51200
	ds_read_b128 v[194:197], v219 offset:52224
	ds_read_b128 v[214:217], v219 offset:53248
	ds_read_b128 v[220:223], v219 offset:54272
	ds_read_b128 v[224:227], v219 offset:55296
	ds_read_b128 v[228:231], v219 offset:56320
	global_load_lds_dwordx4 v[154:155], off
	v_lshl_add_u64 v[154:155], v[248:249], 0, s[2:3]
	s_mov_b32 m0, s29
	s_nop 0
	global_load_lds_dwordx4 v[154:155], off
	s_barrier
; #define PG8_STAGE(bufoff, gbase, voff) do { _Pragma("unroll") for (int _i = 0; _i < 2; ++_i) \
;         __builtin_amdgcn_global_load_lds((const unsigned*)((const char*)(gbase) + (voff)[_i]), (LAS unsigned*)(lds + (bufoff) + ldsw + _i * 8192), 16, 0, 0); } while (0)
; #define PG8_MMA(ai, bj, At, Bt) do { __builtin_amdgcn_s_setprio(1); _Pragma("unroll") for (int m = 0; m < 4; ++m) _Pragma("unroll") for (int n = 0; n < 2; ++n) _Pragma("unroll") for (int k = 0; k < 2; ++k) \
;         acc[ai][bj][m][n] = __builtin_amdgcn_mfma_f32_16x16x32_bf16(Bt[n][k], At[m][k], acc[ai][bj][m][n], 0, 0, 0); __builtin_amdgcn_s_setprio(0); } while (0)
; #define PG8_WAIT_V(n) asm volatile("s_waitcnt vmcnt(" #n ")" ::: "memory")
; #define PG8_WAIT_L(n) asm volatile("s_waitcnt lgkmcnt(" #n ")" ::: "memory")
; #define PG8_BAR __builtin_amdgcn_s_barrier()
; #define PG8_SCHED __builtin_amdgcn_sched_barrier(0)
;     DEV void operator()(AccRef acc, const pg8::Unit& u, int wr, int wc, int fr, int fq) const { store_bf16_tile<0, false>(acc, O, ld, u.pm * 256 + wr * 64 + fr, u.pn * 256 + wc * 32 + 4 * fq, ss); }
; template <class Epi>
; DEV void gemm_phase(LAS unsigned char* lds, const Gemm g, const StaticOrder& S, const Epi& E) {
;     ...
;             PG8_BAR; PG8_WAIT_L(0); PG8_MMA(1, 0, At, B0); PG8_BAR; PG8_SCHED;
;             PG8_STAGE(PG8_SB(1, 1), b3 + hstep, voffB);
;             PG8_WAIT_V(6); PG8_BAR; PG8_MMA(1, 1, At, B1); PG8_BAR;
;         }
;     DEV void operator()(AccRef acc, const pg8::Unit& u, int wr, int wc, int fr, int fq) const {
;         const int ct = u.pn * 256, row0 = u.pm * 256 + wr * 64 + fr, cw = wc * 32 + 8 * fq;
;         if (ct < 4096) store_bf16_tile<1, true>(acc, UV, 4096, row0, ct + cw, ss);
;         else if (ct < 6144) store_bf16_tile<0, true>(acc, Z, 2048, row0, ct - 4096 + cw, ss);
;         else if (ct < 9216) store_bf16_tile<0, true>(acc, XBC, 3072, row0, ct - 6144 + cw, ss);
;         else if (wc == 0) {
; #pragma unroll
;             for (int ai = 0; ai < 2; ++ai)
; #pragma unroll
;                 for (int m = 0; m < 4; ++m) { const float rs = rowscale(ss, row0 + ai * 128 + m * 16);
; #pragma unroll
;                     for (int n = 0; n < 2; ++n) *(f32x4*)(DTR + (size_t)(row0 + ai * 128 + m * 16) * 32 + 8 * fq + 4 * n) = acc[ai][0][m][n] * rs; }
	s_waitcnt lgkmcnt(0)
	v_mfma_f32_16x16x32_bf16 v[60:63], v[128:131], v[182:185], v[60:63]
	v_mfma_f32_16x16x32_bf16 v[56:59], v[150:153], v[182:185], v[56:59]
	v_mfma_f32_16x16x32_bf16 v[44:47], v[128:131], v[190:193], v[44:47]
	v_mfma_f32_16x16x32_bf16 v[40:43], v[150:153], v[190:193], v[40:43]
	v_mfma_f32_16x16x32_bf16 v[28:31], v[128:131], v[214:217], v[28:31]
	v_mfma_f32_16x16x32_bf16 v[24:27], v[150:153], v[214:217], v[24:27]
	v_mfma_f32_16x16x32_bf16 v[12:15], v[128:131], v[224:227], v[12:15]
	v_mfma_f32_16x16x32_bf16 v[8:11], v[150:153], v[224:227], v[8:11]
	v_mfma_f32_16x16x32_bf16 v[60:63], v[132:135], v[186:189], v[60:63]
	v_mfma_f32_16x16x32_bf16 v[56:59], v[174:177], v[186:189], v[56:59]
	v_mfma_f32_16x16x32_bf16 v[44:47], v[132:135], v[194:197], v[44:47]
	v_mfma_f32_16x16x32_bf16 v[40:43], v[174:177], v[194:197], v[40:43]
	v_mfma_f32_16x16x32_bf16 v[28:31], v[132:135], v[220:223], v[28:31]
	v_mfma_f32_16x16x32_bf16 v[24:27], v[174:177], v[220:223], v[24:27]
	v_mfma_f32_16x16x32_bf16 v[12:15], v[132:135], v[228:231], v[12:15]
	v_mfma_f32_16x16x32_bf16 v[8:11], v[174:177], v[228:231], v[8:11]
	s_barrier
	s_add_u32 s16, s16, 0x80080
	s_addc_u32 s17, s17, 0
	s_add_i32 s18, s18, s22
	s_mov_b32 m0, s18
	s_nop 0
	global_load_lds_dwordx4 v140, s[16:17]
	s_add_i32 m0, s18, 0x2000
	s_nop 0
	global_load_lds_dwordx4 v136, s[16:17]
	s_waitcnt vmcnt(6)
	s_barrier
	v_mfma_f32_16x16x32_bf16 v[52:55], v[232:235], v[182:185], v[52:55]
	v_mfma_f32_16x16x32_bf16 v[48:51], v[240:243], v[182:185], v[48:51]
	v_mfma_f32_16x16x32_bf16 v[36:39], v[232:235], v[190:193], v[36:39]
	v_mfma_f32_16x16x32_bf16 v[32:35], v[240:243], v[190:193], v[32:35]
	v_mfma_f32_16x16x32_bf16 v[20:23], v[232:235], v[214:217], v[20:23]
	v_mfma_f32_16x16x32_bf16 v[16:19], v[240:243], v[214:217], v[16:19]
	v_mfma_f32_16x16x32_bf16 v[4:7], v[232:235], v[224:227], v[4:7]
	v_mfma_f32_16x16x32_bf16 v[0:3], v[240:243], v[224:227], v[0:3]
	v_mfma_f32_16x16x32_bf16 v[52:55], v[236:239], v[186:189], v[52:55]
	v_mfma_f32_16x16x32_bf16 v[48:51], v[244:247], v[186:189], v[48:51]
	v_mfma_f32_16x16x32_bf16 v[36:39], v[236:239], v[194:197], v[36:39]
	v_mfma_f32_16x16x32_bf16 v[32:35], v[244:247], v[194:197], v[32:35]
	v_mfma_f32_16x16x32_bf16 v[20:23], v[236:239], v[220:223], v[20:23]
	v_mfma_f32_16x16x32_bf16 v[16:19], v[244:247], v[220:223], v[16:19]
	v_mfma_f32_16x16x32_bf16 v[4:7], v[236:239], v[228:231], v[4:7]
	v_mfma_f32_16x16x32_bf16 v[0:3], v[244:247], v[228:231], v[0:3]
	s_add_i32 s40, s40, 2
	s_add_u32 s14, s14, 0x100
	s_addc_u32 s15, s15, 0
	s_add_u32 s36, s36, 0x100
	s_addc_u32 s37, s37, 0
	s_cmp_gt_u32 s40, 29
	s_barrier
	s_cbranch_scc0 .LBB0_588
	s_lshl_b32 s7, s34, 8
	v_lshl_add_u32 v150, s0, 8, v157
	s_cmp_gt_i32 s34, 15
	s_mov_b64 s[0:1], -1
	s_cbranch_scc0 .LBB0_601
	s_cmp_gt_u32 s34, 23
	s_cbranch_scc0 .LBB0_598
	s_cmp_gt_u32 s34, 35
	s_cbranch_scc0 .LBB0_595
	s_andn2_b64 vcc, exec, s[4:5]
	s_cbranch_vccnz .LBB0_594
	v_ashrrev_i32_e32 v151, 31, v150
	v_readlane_b32 s0, v251, 39
	v_lshlrev_b64 v[128:129], 5, v[150:151]
	v_readlane_b32 s1, v251, 40
	s_mov_b32 s9, 0x800000
	s_nop 0
	v_lshl_add_u64 v[132:133], s[0:1], 0, v[128:129]
	global_load_dwordx4 v[128:131], v[132:133], off offset:16
	s_nop 0
	global_load_dwordx4 v[132:135], v[132:133], off
	s_waitcnt vmcnt(0)
	v_mov_b32_e32 v152, v133
	v_mov_b32_e32 v153, v134
	v_mov_b32_e32 v133, v135
	v_pk_add_f32 v[132:133], v[152:153], v[132:133]
	v_mov_b32_e32 v134, v130
	v_mov_b32_e32 v135, v128
	v_mov_b32_e32 v128, v131
	v_pk_add_f32 v[128:129], v[134:135], v[128:129]
	v_add_f32_e32 v130, v132, v133
	v_add_f32_e32 v129, v130, v129
	v_add_f32_e32 v128, v128, v129
	v_fmamk_f32 v128, v128, 0x3a000000, v199
	v_cmp_gt_f32_e32 vcc, s9, v128
	v_mul_f32_e32 v129, 0x4b800000, v128
	v_lshlrev_b64 v[134:135], 7, v[150:151]
	v_cndmask_b32_e32 v128, v128, v129, vcc
	v_rsq_f32_e32 v128, v128
	v_lshl_add_u64 v[134:135], v[144:145], 0, v[134:135]
	v_or_b32_e32 v152, 16, v150
	v_ashrrev_i32_e32 v153, 31, v152
	v_mul_f32_e32 v129, 0x45800000, v128
	v_cndmask_b32_e32 v132, v128, v129, vcc
	v_pk_mul_f32 v[130:131], v[126:127], v[132:133] op_sel_hi:[1,0]
	v_pk_mul_f32 v[128:129], v[124:125], v[132:133] op_sel_hi:[1,0]
	global_store_dwordx4 v[134:135], v[128:131], off
	s_nop 1
	v_pk_mul_f32 v[130:131], v[122:123], v[132:133] op_sel_hi:[1,0]
	v_pk_mul_f32 v[128:129], v[120:121], v[132:133] op_sel_hi:[1,0]
	global_store_dwordx4 v[134:135], v[128:131], off offset:16
	s_nop 1
	v_lshlrev_b64 v[128:129], 5, v[152:153]
	v_lshl_add_u64 v[132:133], s[0:1], 0, v[128:129]
	global_load_dwordx4 v[128:131], v[132:133], off offset:16
	s_nop 0
	global_load_dwordx4 v[132:135], v[132:133], off
	s_waitcnt vmcnt(0)
	v_mov_b32_e32 v154, v133
	v_mov_b32_e32 v155, v134
	v_mov_b32_e32 v133, v135
	v_pk_add_f32 v[132:133], v[154:155], v[132:133]
	v_mov_b32_e32 v134, v130
	v_mov_b32_e32 v135, v128
	v_mov_b32_e32 v128, v131
	v_pk_add_f32 v[128:129], v[134:135], v[128:129]
	v_add_f32_e32 v130, v132, v133
	v_add_f32_e32 v129, v130, v129
	v_add_f32_e32 v128, v128, v129
	v_fmamk_f32 v128, v128, 0x3a000000, v199
	v_cmp_gt_f32_e32 vcc, s9, v128
	v_mul_f32_e32 v129, 0x4b800000, v128
	v_lshlrev_b64 v[134:135], 7, v[152:153]
	v_cndmask_b32_e32 v128, v128, v129, vcc
	v_rsq_f32_e32 v128, v128
	v_lshl_add_u64 v[134:135], v[144:145], 0, v[134:135]
	v_or_b32_e32 v152, 32, v150
	v_ashrrev_i32_e32 v153, 31, v152
	v_mul_f32_e32 v129, 0x45800000, v128
	v_cndmask_b32_e32 v132, v128, v129, vcc
	v_pk_mul_f32 v[130:131], v[110:111], v[132:133] op_sel_hi:[1,0]
	v_pk_mul_f32 v[128:129], v[108:109], v[132:133] op_sel_hi:[1,0]
	global_store_dwordx4 v[134:135], v[128:131], off
	s_nop 1
	v_pk_mul_f32 v[130:131], v[106:107], v[132:133] op_sel_hi:[1,0]
	v_pk_mul_f32 v[128:129], v[104:105], v[132:133] op_sel_hi:[1,0]
	global_store_dwordx4 v[134:135], v[128:131], off offset:16
	s_nop 1
	v_lshlrev_b64 v[128:129], 5, v[152:153]
	v_lshl_add_u64 v[132:133], s[0:1], 0, v[128:129]
	global_load_dwordx4 v[128:131], v[132:133], off offset:16
	s_nop 0
	global_load_dwordx4 v[132:135], v[132:133], off
	s_waitcnt vmcnt(0)
; DEV float rowscale(const float* ss, int row) { const f32x4 a = *(const f32x4*)(ss + (size_t)row * 8), b = *(const f32x4*)(ss + (size_t)row * 8 + 4);
;     return rsqrtf(((a[0] + a[1]) + (a[2] + a[3]) + (b[0] + b[1]) + (b[2] + b[3])) * (1.0f / 2048.0f) + EPS); }
;     DEV void operator()(AccRef acc, const pg8::Unit& u, int wr, int wc, int fr, int fq) const {
;     ...
;         else if (wc == 0) {
; #pragma unroll
;             for (int ai = 0; ai < 2; ++ai)
; #pragma unroll
;                 for (int m = 0; m < 4; ++m) { const float rs = rowscale(ss, row0 + ai * 128 + m * 16);
; #pragma unroll
;                     for (int n = 0; n < 2; ++n) *(f32x4*)(DTR + (size_t)(row0 + ai * 128 + m * 16) * 32 + 8 * fq + 4 * n) = acc[ai][0][m][n] * rs; }
	v_mov_b32_e32 v154, v133
	v_mov_b32_e32 v155, v134
	v_mov_b32_e32 v133, v135
	v_pk_add_f32 v[132:133], v[154:155], v[132:133]
	v_mov_b32_e32 v134, v130
	v_mov_b32_e32 v135, v128
	v_mov_b32_e32 v128, v131
	v_pk_add_f32 v[128:129], v[134:135], v[128:129]
	v_add_f32_e32 v130, v132, v133
	v_add_f32_e32 v129, v130, v129
	v_add_f32_e32 v128, v128, v129
	v_fmamk_f32 v128, v128, 0x3a000000, v199
	v_cmp_gt_f32_e32 vcc, s9, v128
	v_mul_f32_e32 v129, 0x4b800000, v128
	v_lshlrev_b64 v[134:135], 7, v[152:153]
	v_cndmask_b32_e32 v128, v128, v129, vcc
	v_rsq_f32_e32 v128, v128
	v_lshl_add_u64 v[134:135], v[144:145], 0, v[134:135]
	v_or_b32_e32 v152, 48, v150
	v_ashrrev_i32_e32 v153, 31, v152
	v_mul_f32_e32 v129, 0x45800000, v128
	v_cndmask_b32_e32 v132, v128, v129, vcc
	v_pk_mul_f32 v[130:131], v[94:95], v[132:133] op_sel_hi:[1,0]
	v_pk_mul_f32 v[128:129], v[92:93], v[132:133] op_sel_hi:[1,0]
	global_store_dwordx4 v[134:135], v[128:131], off
	s_nop 1
	v_pk_mul_f32 v[130:131], v[90:91], v[132:133] op_sel_hi:[1,0]
	v_pk_mul_f32 v[128:129], v[88:89], v[132:133] op_sel_hi:[1,0]
	global_store_dwordx4 v[134:135], v[128:131], off offset:16
	s_nop 1
	v_lshlrev_b64 v[128:129], 5, v[152:153]
	v_lshl_add_u64 v[132:133], s[0:1], 0, v[128:129]
	global_load_dwordx4 v[128:131], v[132:133], off offset:16
	s_nop 0
	global_load_dwordx4 v[132:135], v[132:133], off
	s_waitcnt vmcnt(0)
	v_mov_b32_e32 v154, v133
	v_mov_b32_e32 v155, v134
	v_mov_b32_e32 v133, v135
	v_pk_add_f32 v[132:133], v[154:155], v[132:133]
	v_mov_b32_e32 v134, v130
	v_mov_b32_e32 v135, v128
	v_mov_b32_e32 v128, v131
	v_pk_add_f32 v[128:129], v[134:135], v[128:129]
	v_add_f32_e32 v130, v132, v133
	v_add_f32_e32 v129, v130, v129
	v_add_f32_e32 v128, v128, v129
	v_fmamk_f32 v128, v128, 0x3a000000, v199
	v_cmp_gt_f32_e32 vcc, s9, v128
	v_mul_f32_e32 v129, 0x4b800000, v128
	v_lshlrev_b64 v[134:135], 7, v[152:153]
	v_cndmask_b32_e32 v128, v128, v129, vcc
	v_rsq_f32_e32 v128, v128
	v_lshl_add_u64 v[134:135], v[144:145], 0, v[134:135]
	v_add_u32_e32 v152, 0x80, v150
	v_ashrrev_i32_e32 v153, 31, v152
	v_mul_f32_e32 v129, 0x45800000, v128
	v_cndmask_b32_e32 v132, v128, v129, vcc
	v_pk_mul_f32 v[130:131], v[78:79], v[132:133] op_sel_hi:[1,0]
	v_pk_mul_f32 v[128:129], v[76:77], v[132:133] op_sel_hi:[1,0]
	global_store_dwordx4 v[134:135], v[128:131], off
	s_nop 1
	v_pk_mul_f32 v[130:131], v[74:75], v[132:133] op_sel_hi:[1,0]
	v_pk_mul_f32 v[128:129], v[72:73], v[132:133] op_sel_hi:[1,0]
	global_store_dwordx4 v[134:135], v[128:131], off offset:16
	s_nop 1
	v_lshlrev_b64 v[128:129], 5, v[152:153]
	v_lshl_add_u64 v[132:133], s[0:1], 0, v[128:129]
	global_load_dwordx4 v[128:131], v[132:133], off offset:16
	s_nop 0
	global_load_dwordx4 v[132:135], v[132:133], off
	s_waitcnt vmcnt(0)
	v_mov_b32_e32 v154, v133
	v_mov_b32_e32 v155, v134
	v_mov_b32_e32 v133, v135
	v_pk_add_f32 v[132:133], v[154:155], v[132:133]
	v_mov_b32_e32 v134, v130
	v_mov_b32_e32 v135, v128
	v_mov_b32_e32 v128, v131
	v_pk_add_f32 v[128:129], v[134:135], v[128:129]
	v_add_f32_e32 v130, v132, v133
	v_add_f32_e32 v129, v130, v129
	v_add_f32_e32 v128, v128, v129
	v_fmamk_f32 v128, v128, 0x3a000000, v199
	v_cmp_gt_f32_e32 vcc, s9, v128
	v_mul_f32_e32 v129, 0x4b800000, v128
	v_lshlrev_b64 v[134:135], 7, v[152:153]
	v_cndmask_b32_e32 v128, v128, v129, vcc
	v_rsq_f32_e32 v128, v128
	v_lshl_add_u64 v[134:135], v[144:145], 0, v[134:135]
	v_add_u32_e32 v152, 0x90, v150
	v_ashrrev_i32_e32 v153, 31, v152
	v_mul_f32_e32 v129, 0x45800000, v128
	v_cndmask_b32_e32 v132, v128, v129, vcc
	v_pk_mul_f32 v[130:131], v[62:63], v[132:133] op_sel_hi:[1,0]
	v_pk_mul_f32 v[128:129], v[60:61], v[132:133] op_sel_hi:[1,0]
	global_store_dwordx4 v[134:135], v[128:131], off
	s_nop 1
	v_pk_mul_f32 v[130:131], v[58:59], v[132:133] op_sel_hi:[1,0]
	v_pk_mul_f32 v[128:129], v[56:57], v[132:133] op_sel_hi:[1,0]
	global_store_dwordx4 v[134:135], v[128:131], off offset:16
	s_nop 1
	v_lshlrev_b64 v[128:129], 5, v[152:153]
	v_lshl_add_u64 v[132:133], s[0:1], 0, v[128:129]
	global_load_dwordx4 v[128:131], v[132:133], off offset:16
	s_nop 0
	global_load_dwordx4 v[132:135], v[132:133], off
	s_waitcnt vmcnt(0)
; DEV float rowscale(const float* ss, int row) { const f32x4 a = *(const f32x4*)(ss + (size_t)row * 8), b = *(const f32x4*)(ss + (size_t)row * 8 + 4);
;     return rsqrtf(((a[0] + a[1]) + (a[2] + a[3]) + (b[0] + b[1]) + (b[2] + b[3])) * (1.0f / 2048.0f) + EPS); }
;     DEV void operator()(AccRef acc, const pg8::Unit& u, int wr, int wc, int fr, int fq) const {
;     ...
;         else if (wc == 0) {
; #pragma unroll
;             for (int ai = 0; ai < 2; ++ai)
; #pragma unroll
;                 for (int m = 0; m < 4; ++m) { const float rs = rowscale(ss, row0 + ai * 128 + m * 16);
; #pragma unroll
;                     for (int n = 0; n < 2; ++n) *(f32x4*)(DTR + (size_t)(row0 + ai * 128 + m * 16) * 32 + 8 * fq + 4 * n) = acc[ai][0][m][n] * rs; }
	v_mov_b32_e32 v154, v133
	v_mov_b32_e32 v155, v134
	v_mov_b32_e32 v133, v135
	v_pk_add_f32 v[132:133], v[154:155], v[132:133]
	v_mov_b32_e32 v134, v130
	v_mov_b32_e32 v135, v128
	v_mov_b32_e32 v128, v131
	v_pk_add_f32 v[128:129], v[134:135], v[128:129]
	v_add_f32_e32 v130, v132, v133
	v_add_f32_e32 v129, v130, v129
	v_add_f32_e32 v128, v128, v129
	v_fmamk_f32 v128, v128, 0x3a000000, v199
	v_cmp_gt_f32_e32 vcc, s9, v128
	v_mul_f32_e32 v129, 0x4b800000, v128
	v_lshlrev_b64 v[134:135], 7, v[152:153]
	v_cndmask_b32_e32 v128, v128, v129, vcc
	v_rsq_f32_e32 v128, v128
	v_lshl_add_u64 v[134:135], v[144:145], 0, v[134:135]
	v_add_u32_e32 v152, 0xa0, v150
	v_ashrrev_i32_e32 v153, 31, v152
	v_mul_f32_e32 v129, 0x45800000, v128
	v_cndmask_b32_e32 v132, v128, v129, vcc
	v_pk_mul_f32 v[130:131], v[46:47], v[132:133] op_sel_hi:[1,0]
	v_pk_mul_f32 v[128:129], v[44:45], v[132:133] op_sel_hi:[1,0]
	global_store_dwordx4 v[134:135], v[128:131], off
	s_nop 1
	v_pk_mul_f32 v[130:131], v[42:43], v[132:133] op_sel_hi:[1,0]
	v_pk_mul_f32 v[128:129], v[40:41], v[132:133] op_sel_hi:[1,0]
	global_store_dwordx4 v[134:135], v[128:131], off offset:16
	s_nop 1
	v_lshlrev_b64 v[128:129], 5, v[152:153]
	v_lshl_add_u64 v[132:133], s[0:1], 0, v[128:129]
	global_load_dwordx4 v[128:131], v[132:133], off offset:16
	s_nop 0
	global_load_dwordx4 v[132:135], v[132:133], off
	s_waitcnt vmcnt(0)
	v_mov_b32_e32 v154, v133
	v_mov_b32_e32 v155, v134
	v_mov_b32_e32 v133, v135
	v_pk_add_f32 v[132:133], v[154:155], v[132:133]
	v_mov_b32_e32 v134, v130
	v_mov_b32_e32 v135, v128
	v_mov_b32_e32 v128, v131
	v_pk_add_f32 v[128:129], v[134:135], v[128:129]
	v_add_f32_e32 v130, v132, v133
	v_add_f32_e32 v129, v130, v129
	v_add_f32_e32 v128, v128, v129
	v_fmamk_f32 v128, v128, 0x3a000000, v199
	v_cmp_gt_f32_e32 vcc, s9, v128
	v_mul_f32_e32 v129, 0x4b800000, v128
	v_lshlrev_b64 v[134:135], 7, v[152:153]
	v_cndmask_b32_e32 v128, v128, v129, vcc
	v_rsq_f32_e32 v128, v128
	v_lshl_add_u64 v[134:135], v[144:145], 0, v[134:135]
	v_add_u32_e32 v152, 0xb0, v150
	v_ashrrev_i32_e32 v153, 31, v152
	v_mul_f32_e32 v129, 0x45800000, v128
	v_cndmask_b32_e32 v132, v128, v129, vcc
	v_pk_mul_f32 v[130:131], v[30:31], v[132:133] op_sel_hi:[1,0]
	v_pk_mul_f32 v[128:129], v[28:29], v[132:133] op_sel_hi:[1,0]
	global_store_dwordx4 v[134:135], v[128:131], off
	s_nop 1
	v_pk_mul_f32 v[130:131], v[26:27], v[132:133] op_sel_hi:[1,0]
	v_pk_mul_f32 v[128:129], v[24:25], v[132:133] op_sel_hi:[1,0]
	global_store_dwordx4 v[134:135], v[128:131], off offset:16
	s_nop 1
	v_lshlrev_b64 v[128:129], 5, v[152:153]
	v_lshl_add_u64 v[132:133], s[0:1], 0, v[128:129]
	global_load_dwordx4 v[128:131], v[132:133], off offset:16
	s_nop 0
	global_load_dwordx4 v[132:135], v[132:133], off
	s_waitcnt vmcnt(0)
	v_mov_b32_e32 v154, v133
	v_mov_b32_e32 v155, v134
	v_mov_b32_e32 v133, v135
	v_pk_add_f32 v[132:133], v[154:155], v[132:133]
	v_mov_b32_e32 v134, v130
	v_mov_b32_e32 v135, v128
	v_mov_b32_e32 v128, v131
	v_pk_add_f32 v[128:129], v[134:135], v[128:129]
	v_add_f32_e32 v130, v132, v133
	v_add_f32_e32 v129, v130, v129
	v_add_f32_e32 v128, v128, v129
	v_fmamk_f32 v128, v128, 0x3a000000, v199
	v_cmp_gt_f32_e32 vcc, s9, v128
	v_mul_f32_e32 v129, 0x4b800000, v128
	v_lshlrev_b64 v[134:135], 7, v[152:153]
	v_cndmask_b32_e32 v128, v128, v129, vcc
	v_rsq_f32_e32 v128, v128
	v_lshl_add_u64 v[134:135], v[144:145], 0, v[134:135]
	v_mul_f32_e32 v129, 0x45800000, v128
	v_cndmask_b32_e32 v132, v128, v129, vcc
	v_pk_mul_f32 v[130:131], v[14:15], v[132:133] op_sel_hi:[1,0]
	v_pk_mul_f32 v[128:129], v[12:13], v[132:133] op_sel_hi:[1,0]
	global_store_dwordx4 v[134:135], v[128:131], off
	s_nop 1
	v_pk_mul_f32 v[130:131], v[10:11], v[132:133] op_sel_hi:[1,0]
	v_pk_mul_f32 v[128:129], v[8:9], v[132:133] op_sel_hi:[1,0]
	global_store_dwordx4 v[134:135], v[128:131], off offset:16

; #define PG8_STAGE(bufoff, gbase, voff) do { _Pragma("unroll") for (int _i = 0; _i < 2; ++_i) \
;         __builtin_amdgcn_global_load_lds((const unsigned*)((const char*)(gbase) + (voff)[_i]), (LAS unsigned*)(lds + (bufoff) + ldsw + _i * 8192), 16, 0, 0); } while (0)
; #define PG8_LDA(dst, b, h) do { _Pragma("unroll") for (int m = 0; m < 4; ++m) _Pragma("unroll") for (int k = 0; k < 2; ++k) dst[m][k] = *(const LAS bf16x8*)(lds + PG8_SA(b, h) + aoff + m * 2048 + k * 1024); } while (0)
; #define PG8_LDB(dst, b, h) do { _Pragma("unroll") for (int n = 0; n < 2; ++n) _Pragma("unroll") for (int k = 0; k < 2; ++k) dst[n][k] = *(const LAS bf16x8*)(lds + PG8_SB(b, h) + boff + n * 2048 + k * 1024); } while (0)
; #define PG8_MMA(ai, bj, At, Bt) do { __builtin_amdgcn_s_setprio(1); _Pragma("unroll") for (int m = 0; m < 4; ++m) _Pragma("unroll") for (int n = 0; n < 2; ++n) _Pragma("unroll") for (int k = 0; k < 2; ++k) \
;         acc[ai][bj][m][n] = __builtin_amdgcn_mfma_f32_16x16x32_bf16(Bt[n][k], At[m][k], acc[ai][bj][m][n], 0, 0, 0); __builtin_amdgcn_s_setprio(0); } while (0)
; #define PG8_WAIT_V(n) asm volatile("s_waitcnt vmcnt(" #n ")" ::: "memory")
; #define PG8_WAIT_L(n) asm volatile("s_waitcnt lgkmcnt(" #n ")" ::: "memory")
; #define PG8_BAR __builtin_amdgcn_s_barrier()
; #define PG8_SCHED __builtin_amdgcn_sched_barrier(0)
; template <class Epi>
; DEV void gemm_phase(LAS unsigned char* lds, const Gemm g, const StaticOrder& S, const Epi& E) {
;     ...
;             const bool last = (t == nt - 2);
;             const char* a1 = cA + (size_t)(t + 1) * kstep;
;             const char* a2 = last ? nA : cA + (size_t)(t + 2) * kstep; const char* b2 = last ? nB : cB + (size_t)(t + 2) * kstep;
;             const char* a3 = a2 + kstep; const char* b3 = b2 + kstep;
;             PG8_LDB(B0, 0, 0); PG8_SCHED; PG8_LDA(At, 0, 0); PG8_STAGE(PG8_SA(1, 1), a1 + hstep, voffA);
;             PG8_WAIT_L(8); PG8_BAR; PG8_WAIT_L(0); PG8_MMA(0, 0, At, B0); PG8_BAR; PG8_SCHED;
;             PG8_LDB(B1, 0, 1); PG8_STAGE(PG8_SB(0, 0), b2, voffB);
;             PG8_BAR; PG8_WAIT_L(0); PG8_MMA(0, 1, At, B1); PG8_BAR;
;             PG8_LDA(At, 0, 1); PG8_STAGE(PG8_SA(0, 0), a2, voffA);
;             PG8_BAR; PG8_WAIT_L(0); PG8_MMA(1, 0, At, B0); PG8_BAR; PG8_SCHED;
;             PG8_STAGE(PG8_SB(0, 1), b2 + hstep, voffB);
;             PG8_WAIT_V(6); PG8_BAR; PG8_MMA(1, 1, At, B1); PG8_BAR;
.LBB0_657:
	s_add_u32 s6, s28, 0x100
	s_addc_u32 s7, s29, 0
	s_add_i32 s55, 0, 0x10000
	v_add_u32_e32 v140, s55, v196
	ds_read_b128 v[128:131], v140
	ds_read_b128 v[132:135], v140 offset:1024
	ds_read_b128 v[136:139], v140 offset:2048
	ds_read_b128 v[140:143], v140 offset:3072
	s_cmpk_eq_i32 s54, 0x54
	s_cselect_b32 s35, s27, s7
	s_cselect_b32 s34, s26, s6
	s_cselect_b32 s31, s9, s53
	s_cselect_b32 s30, s8, s52
	s_add_i32 m0, s41, 0xc000
	ds_read_b128 v[144:147], v219
	ds_read_b128 v[148:151], v219 offset:1024
	ds_read_b128 v[152:155], v219 offset:2048
	ds_read_b128 v[156:159], v219 offset:3072
	ds_read_b128 v[184:187], v219 offset:4096
	ds_read_b128 v[188:191], v219 offset:5120
	ds_read_b128 v[192:195], v219 offset:6144
	ds_read_b128 v[220:223], v219 offset:7168
	global_load_lds_dwordx4 v180, s[28:29]
	s_add_i32 m0, s41, 0xe000
	s_nop 0
	global_load_lds_dwordx4 v182, s[28:29]
	s_waitcnt lgkmcnt(8)
	s_barrier
	s_waitcnt lgkmcnt(0)
	v_mfma_f32_16x16x32_bf16 v[124:127], v[128:131], v[144:147], v[124:127]
	v_mfma_f32_16x16x32_bf16 v[120:123], v[136:139], v[144:147], v[120:123]
	v_mfma_f32_16x16x32_bf16 v[112:115], v[128:131], v[152:155], v[112:115]
	v_mfma_f32_16x16x32_bf16 v[104:107], v[136:139], v[152:155], v[104:107]
	v_mfma_f32_16x16x32_bf16 v[92:95], v[128:131], v[184:187], v[92:95]
	v_mfma_f32_16x16x32_bf16 v[88:91], v[136:139], v[184:187], v[88:91]
	v_mfma_f32_16x16x32_bf16 v[80:83], v[128:131], v[192:195], v[80:83]
	v_mfma_f32_16x16x32_bf16 v[72:75], v[136:139], v[192:195], v[72:75]
	v_mfma_f32_16x16x32_bf16 v[124:127], v[132:135], v[148:151], v[124:127]
	v_mfma_f32_16x16x32_bf16 v[120:123], v[140:143], v[148:151], v[120:123]
	v_mfma_f32_16x16x32_bf16 v[112:115], v[132:135], v[156:159], v[112:115]
	v_mfma_f32_16x16x32_bf16 v[104:107], v[140:143], v[156:159], v[104:107]
	v_mfma_f32_16x16x32_bf16 v[92:95], v[132:135], v[188:191], v[92:95]
	v_mfma_f32_16x16x32_bf16 v[88:91], v[140:143], v[188:191], v[88:91]
	v_mfma_f32_16x16x32_bf16 v[80:83], v[132:135], v[220:223], v[80:83]
	v_mfma_f32_16x16x32_bf16 v[72:75], v[140:143], v[220:223], v[72:75]
	s_barrier
	s_add_i32 s56, 0, 0x14000
	v_add_u32_e32 v214, s56, v196
	s_add_i32 s28, s55, s40
	ds_read_b128 v[224:227], v214
	ds_read_b128 v[228:231], v214 offset:1024
	ds_read_b128 v[232:235], v214 offset:2048
	ds_read_b128 v[236:239], v214 offset:3072
	s_mov_b32 m0, s28
	s_nop 0
	global_load_lds_dwordx4 v160, s[30:31]
	s_add_i32 m0, s28, 0x2000
	s_nop 0
	global_load_lds_dwordx4 v178, s[30:31]
	s_barrier
	s_waitcnt lgkmcnt(0)
	v_mfma_f32_16x16x32_bf16 v[116:119], v[224:227], v[144:147], v[116:119]
	v_mfma_f32_16x16x32_bf16 v[108:111], v[232:235], v[144:147], v[108:111]
	v_mfma_f32_16x16x32_bf16 v[100:103], v[224:227], v[152:155], v[100:103]
	v_mfma_f32_16x16x32_bf16 v[96:99], v[232:235], v[152:155], v[96:99]
	v_mfma_f32_16x16x32_bf16 v[84:87], v[224:227], v[184:187], v[84:87]
	v_mfma_f32_16x16x32_bf16 v[76:79], v[232:235], v[184:187], v[76:79]
	v_mfma_f32_16x16x32_bf16 v[68:71], v[224:227], v[192:195], v[68:71]
	v_mfma_f32_16x16x32_bf16 v[64:67], v[232:235], v[192:195], v[64:67]
	v_mfma_f32_16x16x32_bf16 v[116:119], v[228:231], v[148:151], v[116:119]
	v_mfma_f32_16x16x32_bf16 v[108:111], v[236:239], v[148:151], v[108:111]
	v_mfma_f32_16x16x32_bf16 v[100:103], v[228:231], v[156:159], v[100:103]
	v_mfma_f32_16x16x32_bf16 v[96:99], v[236:239], v[156:159], v[96:99]
	v_mfma_f32_16x16x32_bf16 v[84:87], v[228:231], v[188:191], v[84:87]
	v_mfma_f32_16x16x32_bf16 v[76:79], v[236:239], v[188:191], v[76:79]
	v_mfma_f32_16x16x32_bf16 v[68:71], v[228:231], v[220:223], v[68:71]
	v_mfma_f32_16x16x32_bf16 v[64:67], v[236:239], v[220:223], v[64:67]
	s_mov_b32 m0, s41
	v_lshl_add_u64 v[240:241], s[34:35], 0, v[174:175]
	s_barrier
	ds_read_b128 v[144:147], v219 offset:16384
	ds_read_b128 v[148:151], v219 offset:17408
	ds_read_b128 v[152:155], v219 offset:18432
	ds_read_b128 v[156:159], v219 offset:19456
	ds_read_b128 v[184:187], v219 offset:20480
	ds_read_b128 v[188:191], v219 offset:21504
	ds_read_b128 v[192:195], v219 offset:22528
	ds_read_b128 v[220:223], v219 offset:23552
	global_load_lds_dwordx4 v174, s[34:35]
	v_lshl_add_u64 v[242:243], s[34:35], 0, v[176:177]
	s_mov_b32 m0, s42
	s_nop 0
	global_load_lds_dwordx4 v176, s[34:35]
	s_barrier
	s_waitcnt lgkmcnt(0)
	v_mfma_f32_16x16x32_bf16 v[60:63], v[128:131], v[144:147], v[60:63]
	v_mfma_f32_16x16x32_bf16 v[56:59], v[136:139], v[144:147], v[56:59]
	v_mfma_f32_16x16x32_bf16 v[48:51], v[128:131], v[152:155], v[48:51]
	v_mfma_f32_16x16x32_bf16 v[40:43], v[136:139], v[152:155], v[40:43]
	v_mfma_f32_16x16x32_bf16 v[28:31], v[128:131], v[184:187], v[28:31]
	v_mfma_f32_16x16x32_bf16 v[24:27], v[136:139], v[184:187], v[24:27]
	v_mfma_f32_16x16x32_bf16 v[16:19], v[128:131], v[192:195], v[16:19]
	v_mfma_f32_16x16x32_bf16 v[8:11], v[136:139], v[192:195], v[8:11]
	v_mfma_f32_16x16x32_bf16 v[60:63], v[132:135], v[148:151], v[60:63]
	v_mfma_f32_16x16x32_bf16 v[56:59], v[140:143], v[148:151], v[56:59]
	v_mfma_f32_16x16x32_bf16 v[48:51], v[132:135], v[156:159], v[48:51]
	v_mfma_f32_16x16x32_bf16 v[40:43], v[140:143], v[156:159], v[40:43]
	v_mfma_f32_16x16x32_bf16 v[28:31], v[132:135], v[188:191], v[28:31]
	v_mfma_f32_16x16x32_bf16 v[24:27], v[140:143], v[188:191], v[24:27]
	v_mfma_f32_16x16x32_bf16 v[16:19], v[132:135], v[220:223], v[16:19]
	v_mfma_f32_16x16x32_bf16 v[8:11], v[140:143], v[220:223], v[8:11]
	s_barrier
	s_add_u32 s28, s30, 0x160000
	s_addc_u32 s29, s31, 0
	s_add_i32 s55, s56, s40
	s_mov_b32 m0, s55
	s_nop 0
	global_load_lds_dwordx4 v160, s[28:29]
	s_add_i32 m0, s55, 0x2000
	s_nop 0
	global_load_lds_dwordx4 v178, s[28:29]
	s_waitcnt vmcnt(6)
	s_barrier
; #define PG8_STAGE(bufoff, gbase, voff) do { _Pragma("unroll") for (int _i = 0; _i < 2; ++_i) \
;         __builtin_amdgcn_global_load_lds((const unsigned*)((const char*)(gbase) + (voff)[_i]), (LAS unsigned*)(lds + (bufoff) + ldsw + _i * 8192), 16, 0, 0); } while (0)
; #define PG8_LDA(dst, b, h) do { _Pragma("unroll") for (int m = 0; m < 4; ++m) _Pragma("unroll") for (int k = 0; k < 2; ++k) dst[m][k] = *(const LAS bf16x8*)(lds + PG8_SA(b, h) + aoff + m * 2048 + k * 1024); } while (0)
; #define PG8_LDB(dst, b, h) do { _Pragma("unroll") for (int n = 0; n < 2; ++n) _Pragma("unroll") for (int k = 0; k < 2; ++k) dst[n][k] = *(const LAS bf16x8*)(lds + PG8_SB(b, h) + boff + n * 2048 + k * 1024); } while (0)
; #define PG8_MMA(ai, bj, At, Bt) do { __builtin_amdgcn_s_setprio(1); _Pragma("unroll") for (int m = 0; m < 4; ++m) _Pragma("unroll") for (int n = 0; n < 2; ++n) _Pragma("unroll") for (int k = 0; k < 2; ++k) \
;         acc[ai][bj][m][n] = __builtin_amdgcn_mfma_f32_16x16x32_bf16(Bt[n][k], At[m][k], acc[ai][bj][m][n], 0, 0, 0); __builtin_amdgcn_s_setprio(0); } while (0)
; #define PG8_WAIT_V(n) asm volatile("s_waitcnt vmcnt(" #n ")" ::: "memory")
; #define PG8_WAIT_L(n) asm volatile("s_waitcnt lgkmcnt(" #n ")" ::: "memory")
; #define PG8_BAR __builtin_amdgcn_s_barrier()
; #define PG8_SCHED __builtin_amdgcn_sched_barrier(0)
; template <class Epi>
; DEV void gemm_phase(LAS unsigned char* lds, const Gemm g, const StaticOrder& S, const Epi& E) {
;     ...
;             PG8_WAIT_V(6); PG8_BAR; PG8_MMA(1, 1, At, B1); PG8_BAR;
;             PG8_LDB(B0, 1, 0); PG8_SCHED; PG8_LDA(At, 1, 0); PG8_STAGE(PG8_SA(0, 1), a2 + hstep, voffA);
;             PG8_WAIT_L(8); PG8_BAR; PG8_WAIT_L(0); PG8_MMA(0, 0, At, B0); PG8_BAR; PG8_SCHED;
;             PG8_LDB(B1, 1, 1); PG8_STAGE(PG8_SB(1, 0), b3, voffB);
;             PG8_BAR; PG8_WAIT_L(0); PG8_MMA(0, 1, At, B1); PG8_BAR;
;             PG8_LDA(At, 1, 1); PG8_STAGE(PG8_SA(1, 0), a3, voffA);
	v_mfma_f32_16x16x32_bf16 v[52:55], v[224:227], v[144:147], v[52:55]
	v_mfma_f32_16x16x32_bf16 v[44:47], v[232:235], v[144:147], v[44:47]
	v_mfma_f32_16x16x32_bf16 v[36:39], v[224:227], v[152:155], v[36:39]
	v_mfma_f32_16x16x32_bf16 v[32:35], v[232:235], v[152:155], v[32:35]
	v_mfma_f32_16x16x32_bf16 v[20:23], v[224:227], v[184:187], v[20:23]
	v_mfma_f32_16x16x32_bf16 v[12:15], v[232:235], v[184:187], v[12:15]
	v_mfma_f32_16x16x32_bf16 v[4:7], v[224:227], v[192:195], v[4:7]
	v_mfma_f32_16x16x32_bf16 v[0:3], v[232:235], v[192:195], v[0:3]
	v_mfma_f32_16x16x32_bf16 v[52:55], v[228:231], v[148:151], v[52:55]
	v_mfma_f32_16x16x32_bf16 v[44:47], v[236:239], v[148:151], v[44:47]
	v_mfma_f32_16x16x32_bf16 v[36:39], v[228:231], v[156:159], v[36:39]
	v_mfma_f32_16x16x32_bf16 v[32:35], v[236:239], v[156:159], v[32:35]
	v_mfma_f32_16x16x32_bf16 v[20:23], v[228:231], v[188:191], v[20:23]
	v_mfma_f32_16x16x32_bf16 v[12:15], v[236:239], v[188:191], v[12:15]
	v_mfma_f32_16x16x32_bf16 v[4:7], v[228:231], v[220:223], v[4:7]
	v_mfma_f32_16x16x32_bf16 v[0:3], v[236:239], v[220:223], v[0:3]
	s_add_i32 s55, 0, 0x18000
	v_add_u32_e32 v140, s55, v196
	s_barrier
	ds_read_b128 v[128:131], v140
	ds_read_b128 v[132:135], v140 offset:1024
	ds_read_b128 v[136:139], v140 offset:2048
	ds_read_b128 v[140:143], v140 offset:3072
	s_add_u32 s28, s34, 0x160000
	s_addc_u32 s29, s35, 0
	s_mov_b32 m0, s43
	ds_read_b128 v[144:147], v219 offset:32768
	ds_read_b128 v[148:151], v219 offset:33792
	ds_read_b128 v[152:155], v219 offset:34816
	ds_read_b128 v[156:159], v219 offset:35840
	ds_read_b128 v[184:187], v219 offset:36864
	ds_read_b128 v[188:191], v219 offset:37888
	ds_read_b128 v[192:195], v219 offset:38912
	ds_read_b128 v[220:223], v219 offset:39936
	global_load_lds_dwordx4 v174, s[28:29]
	s_mov_b32 m0, s44
	s_nop 0
	global_load_lds_dwordx4 v176, s[28:29]
	s_waitcnt lgkmcnt(8)
	s_barrier
	s_waitcnt lgkmcnt(0)
	v_mfma_f32_16x16x32_bf16 v[124:127], v[128:131], v[144:147], v[124:127]
	v_mfma_f32_16x16x32_bf16 v[120:123], v[136:139], v[144:147], v[120:123]
	v_mfma_f32_16x16x32_bf16 v[112:115], v[128:131], v[152:155], v[112:115]
	v_mfma_f32_16x16x32_bf16 v[104:107], v[136:139], v[152:155], v[104:107]
	v_mfma_f32_16x16x32_bf16 v[92:95], v[128:131], v[184:187], v[92:95]
	v_mfma_f32_16x16x32_bf16 v[88:91], v[136:139], v[184:187], v[88:91]
	v_mfma_f32_16x16x32_bf16 v[80:83], v[128:131], v[192:195], v[80:83]
	v_mfma_f32_16x16x32_bf16 v[72:75], v[136:139], v[192:195], v[72:75]
	v_mfma_f32_16x16x32_bf16 v[124:127], v[132:135], v[148:151], v[124:127]
	v_mfma_f32_16x16x32_bf16 v[120:123], v[140:143], v[148:151], v[120:123]
	v_mfma_f32_16x16x32_bf16 v[112:115], v[132:135], v[156:159], v[112:115]
	v_mfma_f32_16x16x32_bf16 v[104:107], v[140:143], v[156:159], v[104:107]
	v_mfma_f32_16x16x32_bf16 v[92:95], v[132:135], v[188:191], v[92:95]
	v_mfma_f32_16x16x32_bf16 v[88:91], v[140:143], v[188:191], v[88:91]
	v_mfma_f32_16x16x32_bf16 v[80:83], v[132:135], v[220:223], v[80:83]
	v_mfma_f32_16x16x32_bf16 v[72:75], v[140:143], v[220:223], v[72:75]
	s_barrier
	s_add_i32 s34, 0, 0x1c000
	s_add_i32 s28, s55, s40
	v_add_u32_e32 v236, s34, v196
	s_add_u32 s100, s30, 0x80
	s_addc_u32 s101, s31, 0
	s_mov_b32 m0, s28
	ds_read_b128 v[224:227], v236
	ds_read_b128 v[228:231], v236 offset:1024
	ds_read_b128 v[232:235], v236 offset:2048
	ds_read_b128 v[236:239], v236 offset:3072
	global_load_lds_dwordx4 v160, s[100:101]
	s_add_i32 m0, s28, 0x2000
	s_nop 0
	global_load_lds_dwordx4 v178, s[100:101]
	s_barrier
	s_waitcnt lgkmcnt(0)
	v_mfma_f32_16x16x32_bf16 v[116:119], v[224:227], v[144:147], v[116:119]
	v_mfma_f32_16x16x32_bf16 v[108:111], v[232:235], v[144:147], v[108:111]
	v_mfma_f32_16x16x32_bf16 v[100:103], v[224:227], v[152:155], v[100:103]
	v_mfma_f32_16x16x32_bf16 v[96:99], v[232:235], v[152:155], v[96:99]
	v_mfma_f32_16x16x32_bf16 v[84:87], v[224:227], v[184:187], v[84:87]
	v_mfma_f32_16x16x32_bf16 v[76:79], v[232:235], v[184:187], v[76:79]
	v_mfma_f32_16x16x32_bf16 v[68:71], v[224:227], v[192:195], v[68:71]
	v_mfma_f32_16x16x32_bf16 v[64:67], v[232:235], v[192:195], v[64:67]
	v_mfma_f32_16x16x32_bf16 v[116:119], v[228:231], v[148:151], v[116:119]
	v_mfma_f32_16x16x32_bf16 v[108:111], v[236:239], v[148:151], v[108:111]
	v_mfma_f32_16x16x32_bf16 v[100:103], v[228:231], v[156:159], v[100:103]
	v_mfma_f32_16x16x32_bf16 v[96:99], v[236:239], v[156:159], v[96:99]
	v_mfma_f32_16x16x32_bf16 v[84:87], v[228:231], v[188:191], v[84:87]
	v_mfma_f32_16x16x32_bf16 v[76:79], v[236:239], v[188:191], v[76:79]
	v_mfma_f32_16x16x32_bf16 v[68:71], v[228:231], v[220:223], v[68:71]
	v_mfma_f32_16x16x32_bf16 v[64:67], v[236:239], v[220:223], v[64:67]
	s_mov_b32 m0, s45
	v_lshl_add_u64 v[214:215], v[240:241], 0, s[2:3]
	s_barrier
	ds_read_b128 v[144:147], v219 offset:49152
	ds_read_b128 v[148:151], v219 offset:50176
	ds_read_b128 v[152:155], v219 offset:51200
	ds_read_b128 v[156:159], v219 offset:52224
	ds_read_b128 v[184:187], v219 offset:53248
	ds_read_b128 v[188:191], v219 offset:54272
	ds_read_b128 v[192:195], v219 offset:55296
	ds_read_b128 v[220:223], v219 offset:56320
	global_load_lds_dwordx4 v[214:215], off
	v_lshl_add_u64 v[214:215], v[242:243], 0, s[2:3]
	s_mov_b32 m0, s46
	s_nop 0
	global_load_lds_dwordx4 v[214:215], off
	s_barrier
; DEV bf16x8 pack8(f32x4 a, f32x4 b) { u32x4 w; w.x = cvt_pk_bf16(a[0], a[1]); w.y = cvt_pk_bf16(a[2], a[3]); w.z = cvt_pk_bf16(b[0], b[1]); w.w = cvt_pk_bf16(b[2], b[3]); return __builtin_bit_cast(bf16x8, w); }
; #define PG8_WAIT_V(n) asm volatile("s_waitcnt vmcnt(" #n ")" ::: "memory")
; #define PG8_WAIT_L(n) asm volatile("s_waitcnt lgkmcnt(" #n ")" ::: "memory")
; #define PG8_BAR __builtin_amdgcn_s_barrier()
; template <class Epi>
; DEV void gemm_phase(LAS unsigned char* lds, const Gemm g, const StaticOrder& S, const Epi& E) {
;     ...
;             PG8_BAR; PG8_WAIT_L(0); PG8_MMA(1, 0, At, B0); PG8_BAR; PG8_SCHED;
;             PG8_STAGE(PG8_SB(1, 1), b3 + hstep, voffB);
;             PG8_WAIT_V(6); PG8_BAR; PG8_MMA(1, 1, At, B1); PG8_BAR;
;         }
;     DEV void operator()(AccRef acc, const pg8::Unit& u, int wr, int wc, int fr, int fq) const {
;         const int row0 = u.pm * 256 + wr * 64 + fr, col0 = u.pn * 256 + wc * 32 + 8 * fq;
; #pragma unroll
;         for (int am = 0; am < 4; ++am) { const int ai = am >> 1, m0 = (am & 1) * 2;
;             f32x4 bv[4][2][2];
; #pragma unroll
;             for (int m = m0; m < m0 + 2; ++m)
; #pragma unroll
;                 for (int bj = 0; bj < 2; ++bj)
; #pragma unroll
;                     for (int n = 0; n < 2; ++n) bv[m][bj][n] = *(const f32x4*)(base + (size_t)(row0 + ai * 128 + m * 16) * 2048 + col0 + bj * 128 + n * 4);
; #pragma unroll
;             for (int m = m0; m < m0 + 2; ++m) { const size_t off = (size_t)(row0 + ai * 128 + m * 16) * 2048 + col0; float sq = 0.f;
; #pragma unroll
;                 for (int bj = 0; bj < 2; ++bj) { const f32x4 o0 = bv[m][bj][0] + scale * acc[ai][bj][m][0], o1 = bv[m][bj][1] + scale * acc[ai][bj][m][1];
;                     *(f32x4*)(out + off + bj * 128) = o0; *(f32x4*)(out + off + bj * 128 + 4) = o1;
;                     if (xb) { *(u32x4*)(xb + off + bj * 128) = __builtin_bit_cast(u32x4, pack8(o0, o1));
;                         sq += (o0[0] * o0[0] + o0[1] * o0[1] + o0[2] * o0[2] + o0[3] * o0[3]) + (o1[0] * o1[0] + o1[1] * o1[1] + o1[2] * o1[2] + o1[3] * o1[3]); } }
;                 if (ssout) { sq += __shfl_xor(sq, 16); sq += __shfl_xor(sq, 32);
;                     if (fq == 0) { if (red) red[(ai * 128 + wr * 64 + m * 16 + fr) * 4 + wc] = sq; else atomicAdd(ssout + (size_t)(row0 + ai * 128 + m * 16) * 8 + u.pn, sq); } } }
	s_waitcnt lgkmcnt(0)
	v_mfma_f32_16x16x32_bf16 v[60:63], v[128:131], v[144:147], v[60:63]
	v_mfma_f32_16x16x32_bf16 v[56:59], v[136:139], v[144:147], v[56:59]
	v_mfma_f32_16x16x32_bf16 v[48:51], v[128:131], v[152:155], v[48:51]
	v_mfma_f32_16x16x32_bf16 v[40:43], v[136:139], v[152:155], v[40:43]
	v_mfma_f32_16x16x32_bf16 v[28:31], v[128:131], v[184:187], v[28:31]
	v_mfma_f32_16x16x32_bf16 v[24:27], v[136:139], v[184:187], v[24:27]
	v_mfma_f32_16x16x32_bf16 v[16:19], v[128:131], v[192:195], v[16:19]
	v_mfma_f32_16x16x32_bf16 v[8:11], v[136:139], v[192:195], v[8:11]
	v_mfma_f32_16x16x32_bf16 v[60:63], v[132:135], v[148:151], v[60:63]
	v_mfma_f32_16x16x32_bf16 v[56:59], v[140:143], v[148:151], v[56:59]
	v_mfma_f32_16x16x32_bf16 v[48:51], v[132:135], v[156:159], v[48:51]
	v_mfma_f32_16x16x32_bf16 v[40:43], v[140:143], v[156:159], v[40:43]
	v_mfma_f32_16x16x32_bf16 v[28:31], v[132:135], v[188:191], v[28:31]
	v_mfma_f32_16x16x32_bf16 v[24:27], v[140:143], v[188:191], v[24:27]
	v_mfma_f32_16x16x32_bf16 v[16:19], v[132:135], v[220:223], v[16:19]
	v_mfma_f32_16x16x32_bf16 v[8:11], v[140:143], v[220:223], v[8:11]
	s_barrier
	s_add_u32 s28, s30, 0x160080
	s_addc_u32 s29, s31, 0
	s_add_i32 s30, s34, s40
	s_mov_b32 m0, s30
	s_nop 0
	global_load_lds_dwordx4 v160, s[28:29]
	s_add_i32 m0, s30, 0x2000
	s_nop 0
	global_load_lds_dwordx4 v178, s[28:29]
	s_waitcnt vmcnt(6)
	s_barrier
	v_mfma_f32_16x16x32_bf16 v[52:55], v[224:227], v[144:147], v[52:55]
	v_mfma_f32_16x16x32_bf16 v[44:47], v[232:235], v[144:147], v[44:47]
	v_mfma_f32_16x16x32_bf16 v[36:39], v[224:227], v[152:155], v[36:39]
	v_mfma_f32_16x16x32_bf16 v[32:35], v[232:235], v[152:155], v[32:35]
	v_mfma_f32_16x16x32_bf16 v[20:23], v[224:227], v[184:187], v[20:23]
	v_mfma_f32_16x16x32_bf16 v[12:15], v[232:235], v[184:187], v[12:15]
	v_mfma_f32_16x16x32_bf16 v[4:7], v[224:227], v[192:195], v[4:7]
	v_mfma_f32_16x16x32_bf16 v[0:3], v[232:235], v[192:195], v[0:3]
	v_mfma_f32_16x16x32_bf16 v[52:55], v[228:231], v[148:151], v[52:55]
	v_mfma_f32_16x16x32_bf16 v[44:47], v[236:239], v[148:151], v[44:47]
	v_mfma_f32_16x16x32_bf16 v[36:39], v[228:231], v[156:159], v[36:39]
	v_mfma_f32_16x16x32_bf16 v[32:35], v[236:239], v[156:159], v[32:35]
	v_mfma_f32_16x16x32_bf16 v[20:23], v[228:231], v[188:191], v[20:23]
	v_mfma_f32_16x16x32_bf16 v[12:15], v[236:239], v[188:191], v[12:15]
	v_mfma_f32_16x16x32_bf16 v[4:7], v[228:231], v[220:223], v[4:7]
	v_mfma_f32_16x16x32_bf16 v[0:3], v[236:239], v[220:223], v[0:3]
	s_add_i32 s54, s54, 2
	s_add_u32 s52, s52, 0x100
	s_addc_u32 s53, s53, 0
	s_cmpk_gt_u32 s54, 0x55
	s_mov_b64 s[28:29], s[6:7]
	s_barrier
	s_cbranch_scc0 .LBB0_657
	v_lshl_add_u32 v186, s23, 8, v167
	v_lshl_or_b32 v184, s22, 8, v197
	v_ashrrev_i32_e32 v185, 31, v184
	v_ashrrev_i32_e32 v187, 31, v186
	v_lshl_add_u64 v[188:189], v[184:185], 2, s[24:25]
	v_lshlrev_b64 v[128:129], 13, v[186:187]
	v_or_b32_e32 v190, 16, v186
	v_lshl_add_u64 v[128:129], v[188:189], 0, v[128:129]
	v_ashrrev_i32_e32 v191, 31, v190
	global_load_dwordx4 v[152:155], v[128:129], off offset:16
	global_load_dwordx4 v[156:159], v[128:129], off
	global_load_dwordx4 v[144:147], v[128:129], off offset:528
	global_load_dwordx4 v[148:151], v[128:129], off offset:512
	v_lshlrev_b64 v[128:129], 13, v[190:191]
	v_lshl_add_u64 v[132:133], v[188:189], 0, v[128:129]
	global_load_dwordx4 v[136:139], v[132:133], off offset:16
	global_load_dwordx4 v[140:143], v[132:133], off
	global_load_dwordx4 v[128:131], v[132:133], off offset:528
	s_nop 0
	global_load_dwordx4 v[132:135], v[132:133], off offset:512
	v_lshlrev_b64 v[192:193], 11, v[186:187]
	v_lshl_add_u64 v[194:195], v[192:193], 0, v[184:185]
	s_ashr_i32 s23, s22, 31
	v_lshl_add_u64 v[192:193], v[194:195], 2, s[68:69]
	s_mov_b64 s[28:29], -1
	s_andn2_b64 vcc, exec, s[18:19]
	s_waitcnt vmcnt(0)
	v_pk_fma_f32 v[152:153], v[120:121], 0.5, v[152:153] op_sel_hi:[1,0,1]
	v_cndmask_b32_e64 v120, 0, 1, s[18:19]
	v_pk_fma_f32 v[158:159], v[126:127], 0.5, v[158:159] op_sel_hi:[1,0,1]
	v_pk_fma_f32 v[156:157], v[124:125], 0.5, v[156:157] op_sel_hi:[1,0,1]
	v_pk_fma_f32 v[154:155], v[122:123], 0.5, v[154:155] op_sel_hi:[1,0,1]
	v_cmp_ne_u32_e64 s[6:7], 1, v120
	v_pk_fma_f32 v[120:121], v[116:117], 0.5, v[148:149] op_sel_hi:[1,0,1]
	v_pk_fma_f32 v[124:125], v[108:109], 0.5, v[144:145] op_sel_hi:[1,0,1]
	global_store_dwordx4 v[192:193], v[156:159], off
	global_store_dwordx4 v[192:193], v[152:155], off offset:16
	s_cbranch_vccnz .LBB0_665
	v_mul_f32_e32 v108, v157, v157
	v_mul_f32_e32 v109, v153, v153
	v_fmac_f32_e32 v108, v156, v156
	v_fmac_f32_e32 v109, v152, v152
	v_fmac_f32_e32 v108, v158, v158
	v_fmac_f32_e32 v109, v154, v154
	v_fmac_f32_e32 v108, v159, v159
	v_fmac_f32_e32 v109, v155, v155
	v_add_f32_e32 v108, v108, v109
	v_mul_f32_e32 v109, v121, v121
	v_mul_f32_e32 v144, v125, v125
	v_pk_fma_f32 v[122:123], v[118:119], 0.5, v[150:151] op_sel_hi:[1,0,1]
	v_pk_fma_f32 v[126:127], v[110:111], 0.5, v[146:147] op_sel_hi:[1,0,1]
	v_fmac_f32_e32 v109, v120, v120
	v_fmac_f32_e32 v144, v124, v124
	v_fmac_f32_e32 v109, v122, v122
	v_fmac_f32_e32 v144, v126, v126
	v_fmac_f32_e32 v109, v123, v123
	v_fmac_f32_e32 v144, v127, v127
	v_add_f32_e32 v109, v109, v144
	v_cmp_lt_i32_e32 vcc, v208, v206
	v_add_f32_e32 v108, v108, v109
	v_readlane_b32 s28, v250, 9
	v_cndmask_b32_e32 v109, v204, v208, vcc
	v_lshlrev_b32_e32 v109, 2, v109
	ds_bpermute_b32 v109, v109, v108
	v_cmp_lt_i32_e32 vcc, v207, v206
	v_readlane_b32 s29, v250, 10
	v_cvt_pk_bf16_f32 v220, v156, v157
	v_cvt_pk_bf16_f32 v221, v158, v159
	s_waitcnt lgkmcnt(0)
	v_add_f32_e32 v108, v108, v109
	v_cndmask_b32_e32 v109, v204, v207, vcc
	v_lshlrev_b32_e32 v109, 2, v109
	ds_bpermute_b32 v109, v109, v108
	v_cvt_pk_bf16_f32 v222, v152, v153
	v_cvt_pk_bf16_f32 v223, v154, v155
	v_lshl_add_u64 v[116:117], v[194:195], 1, s[28:29]
	v_cvt_pk_bf16_f32 v152, v120, v121
	v_cvt_pk_bf16_f32 v153, v122, v123
	v_cvt_pk_bf16_f32 v154, v124, v125
	v_cvt_pk_bf16_f32 v155, v126, v127
	global_store_dwordx4 v[116:117], v[220:223], off
	global_store_dwordx4 v[192:193], v[120:123], off offset:512
	global_store_dwordx4 v[192:193], v[124:127], off offset:528
	global_store_dwordx4 v[116:117], v[152:155], off offset:256
	s_and_saveexec_b64 s[28:29], s[10:11]
	s_cbranch_execz .LBB0_664
	s_waitcnt lgkmcnt(0)
	v_add_f32_e32 v108, v108, v109
	s_andn2_b64 vcc, exec, s[20:21]
	s_mov_b64 s[30:31], -1
	s_cbranch_vccnz .LBB0_662
	s_mov_b64 s[30:31], 0
	ds_write_b32 v218, v108

; #define PG8_STAGE(bufoff, gbase, voff) do { _Pragma("unroll") for (int _i = 0; _i < 2; ++_i) \
;         __builtin_amdgcn_global_load_lds((const unsigned*)((const char*)(gbase) + (voff)[_i]), (LAS unsigned*)(lds + (bufoff) + ldsw + _i * 8192), 16, 0, 0); } while (0)
; #define PG8_LDA(dst, b, h) do { _Pragma("unroll") for (int m = 0; m < 4; ++m) _Pragma("unroll") for (int k = 0; k < 2; ++k) dst[m][k] = *(const LAS bf16x8*)(lds + PG8_SA(b, h) + aoff + m * 2048 + k * 1024); } while (0)
; #define PG8_LDB(dst, b, h) do { _Pragma("unroll") for (int n = 0; n < 2; ++n) _Pragma("unroll") for (int k = 0; k < 2; ++k) dst[n][k] = *(const LAS bf16x8*)(lds + PG8_SB(b, h) + boff + n * 2048 + k * 1024); } while (0)
; #define PG8_MMA(ai, bj, At, Bt) do { __builtin_amdgcn_s_setprio(1); _Pragma("unroll") for (int m = 0; m < 4; ++m) _Pragma("unroll") for (int n = 0; n < 2; ++n) _Pragma("unroll") for (int k = 0; k < 2; ++k) \
;         acc[ai][bj][m][n] = __builtin_amdgcn_mfma_f32_16x16x32_bf16(Bt[n][k], At[m][k], acc[ai][bj][m][n], 0, 0, 0); __builtin_amdgcn_s_setprio(0); } while (0)
; #define PG8_WAIT_V(n) asm volatile("s_waitcnt vmcnt(" #n ")" ::: "memory")
; #define PG8_WAIT_L(n) asm volatile("s_waitcnt lgkmcnt(" #n ")" ::: "memory")
; #define PG8_BAR __builtin_amdgcn_s_barrier()
; #define PG8_SCHED __builtin_amdgcn_sched_barrier(0)
; template <class Epi>
; DEV void gemm_phase(LAS unsigned char* lds, const Gemm g, const StaticOrder& S, const Epi& E) {
;     ...
;             const bool last = (t == nt - 2);
;             const char* a1 = cA + (size_t)(t + 1) * kstep;
;             const char* a2 = last ? nA : cA + (size_t)(t + 2) * kstep; const char* b2 = last ? nB : cB + (size_t)(t + 2) * kstep;
;             const char* a3 = a2 + kstep; const char* b3 = b2 + kstep;
;             PG8_LDB(B0, 0, 0); PG8_SCHED; PG8_LDA(At, 0, 0); PG8_STAGE(PG8_SA(1, 1), a1 + hstep, voffA);
;             PG8_WAIT_L(8); PG8_BAR; PG8_WAIT_L(0); PG8_MMA(0, 0, At, B0); PG8_BAR; PG8_SCHED;
;             PG8_LDB(B1, 0, 1); PG8_STAGE(PG8_SB(0, 0), b2, voffB);
;             PG8_BAR; PG8_WAIT_L(0); PG8_MMA(0, 1, At, B1); PG8_BAR;
;             PG8_LDA(At, 0, 1); PG8_STAGE(PG8_SA(0, 0), a2, voffA);
;             PG8_BAR; PG8_WAIT_L(0); PG8_MMA(1, 0, At, B0); PG8_BAR; PG8_SCHED;
;             PG8_STAGE(PG8_SB(0, 1), b2 + hstep, voffB);
;             PG8_WAIT_V(6); PG8_BAR; PG8_MMA(1, 1, At, B1); PG8_BAR;
.LBB0_755:
	s_add_u32 s22, s20, 0xfff80080
	s_addc_u32 s23, s21, -1
	s_add_i32 s47, 0, 0x10000
	v_add_u32_e32 v146, s47, v155
	ds_read_b128 v[128:131], v146
	ds_read_b128 v[132:135], v146 offset:1024
	ds_read_b128 v[150:153], v146 offset:2048
	ds_read_b128 v[174:177], v146 offset:3072
	s_cmp_eq_u32 s46, 28
	s_cselect_b32 s25, s5, s23
	s_cselect_b32 s24, s15, s22
	s_cselect_b32 s23, s11, s45
	s_cselect_b32 s22, s43, s44
	s_add_i32 m0, s34, 0xc000
	ds_read_b128 v[178:181], v167
	ds_read_b128 v[182:185], v167 offset:1024
	ds_read_b128 v[186:189], v167 offset:2048
	ds_read_b128 v[190:193], v167 offset:3072
	ds_read_b128 v[194:197], v167 offset:4096
	ds_read_b128 v[218:221], v167 offset:5120
	ds_read_b128 v[222:225], v167 offset:6144
	ds_read_b128 v[226:229], v167 offset:7168
	global_load_lds_dwordx4 v142, s[20:21]
	s_add_i32 m0, s34, 0xe000
	s_nop 0
	global_load_lds_dwordx4 v144, s[20:21]
	s_waitcnt lgkmcnt(8)
	s_barrier
	s_waitcnt lgkmcnt(0)
	v_mfma_f32_16x16x32_bf16 v[124:127], v[128:131], v[178:181], v[124:127]
	v_mfma_f32_16x16x32_bf16 v[116:119], v[150:153], v[178:181], v[116:119]
	v_mfma_f32_16x16x32_bf16 v[108:111], v[128:131], v[186:189], v[108:111]
	v_mfma_f32_16x16x32_bf16 v[100:103], v[150:153], v[186:189], v[100:103]
	v_mfma_f32_16x16x32_bf16 v[92:95], v[128:131], v[194:197], v[92:95]
	v_mfma_f32_16x16x32_bf16 v[84:87], v[150:153], v[194:197], v[84:87]
	v_mfma_f32_16x16x32_bf16 v[76:79], v[128:131], v[222:225], v[76:79]
	v_mfma_f32_16x16x32_bf16 v[68:71], v[150:153], v[222:225], v[68:71]
	v_mfma_f32_16x16x32_bf16 v[124:127], v[132:135], v[182:185], v[124:127]
	v_mfma_f32_16x16x32_bf16 v[116:119], v[174:177], v[182:185], v[116:119]
	v_mfma_f32_16x16x32_bf16 v[108:111], v[132:135], v[190:193], v[108:111]
	v_mfma_f32_16x16x32_bf16 v[100:103], v[174:177], v[190:193], v[100:103]
	v_mfma_f32_16x16x32_bf16 v[92:95], v[132:135], v[218:221], v[92:95]
	v_mfma_f32_16x16x32_bf16 v[84:87], v[174:177], v[218:221], v[84:87]
	v_mfma_f32_16x16x32_bf16 v[76:79], v[132:135], v[226:229], v[76:79]
	v_mfma_f32_16x16x32_bf16 v[68:71], v[174:177], v[226:229], v[68:71]
	s_barrier
	s_add_i32 s50, 0, 0x14000
	v_add_u32_e32 v146, s50, v155
	s_add_i32 s47, s47, s30
	ds_read_b128 v[230:233], v146
	ds_read_b128 v[234:237], v146 offset:1024
	ds_read_b128 v[238:241], v146 offset:2048
	ds_read_b128 v[242:245], v146 offset:3072
	s_mov_b32 m0, s47
	s_nop 0
	global_load_lds_dwordx4 v160, s[22:23]
	s_add_i32 m0, s47, 0x2000
	s_nop 0
	global_load_lds_dwordx4 v136, s[22:23]
	s_barrier
	s_waitcnt lgkmcnt(0)
	v_mfma_f32_16x16x32_bf16 v[120:123], v[230:233], v[178:181], v[120:123]
	v_mfma_f32_16x16x32_bf16 v[112:115], v[238:241], v[178:181], v[112:115]
	v_mfma_f32_16x16x32_bf16 v[104:107], v[230:233], v[186:189], v[104:107]
	v_mfma_f32_16x16x32_bf16 v[96:99], v[238:241], v[186:189], v[96:99]
	v_mfma_f32_16x16x32_bf16 v[88:91], v[230:233], v[194:197], v[88:91]
	v_mfma_f32_16x16x32_bf16 v[80:83], v[238:241], v[194:197], v[80:83]
	v_mfma_f32_16x16x32_bf16 v[72:75], v[230:233], v[222:225], v[72:75]
	v_mfma_f32_16x16x32_bf16 v[64:67], v[238:241], v[222:225], v[64:67]
	v_mfma_f32_16x16x32_bf16 v[120:123], v[234:237], v[182:185], v[120:123]
	v_mfma_f32_16x16x32_bf16 v[112:115], v[242:245], v[182:185], v[112:115]
	v_mfma_f32_16x16x32_bf16 v[104:107], v[234:237], v[190:193], v[104:107]
	v_mfma_f32_16x16x32_bf16 v[96:99], v[242:245], v[190:193], v[96:99]
	v_mfma_f32_16x16x32_bf16 v[88:91], v[234:237], v[218:221], v[88:91]
	v_mfma_f32_16x16x32_bf16 v[80:83], v[242:245], v[218:221], v[80:83]
	v_mfma_f32_16x16x32_bf16 v[72:75], v[234:237], v[226:229], v[72:75]
	v_mfma_f32_16x16x32_bf16 v[64:67], v[242:245], v[226:229], v[64:67]
	s_mov_b32 m0, s34
	v_lshl_add_u64 v[214:215], s[24:25], 0, v[140:141]
	s_barrier
	ds_read_b128 v[178:181], v167 offset:16384
	ds_read_b128 v[182:185], v167 offset:17408
	ds_read_b128 v[186:189], v167 offset:18432
	ds_read_b128 v[190:193], v167 offset:19456
	ds_read_b128 v[194:197], v167 offset:20480
	ds_read_b128 v[218:221], v167 offset:21504
	ds_read_b128 v[222:225], v167 offset:22528
	ds_read_b128 v[226:229], v167 offset:23552
	global_load_lds_dwordx4 v140, s[24:25]
	v_lshl_add_u64 v[216:217], s[24:25], 0, v[138:139]
	s_mov_b32 m0, s35
	s_nop 0
	global_load_lds_dwordx4 v138, s[24:25]
	s_barrier
	s_waitcnt lgkmcnt(0)
	v_mfma_f32_16x16x32_bf16 v[60:63], v[128:131], v[178:181], v[60:63]
	v_mfma_f32_16x16x32_bf16 v[52:55], v[150:153], v[178:181], v[52:55]
	v_mfma_f32_16x16x32_bf16 v[44:47], v[128:131], v[186:189], v[44:47]
	v_mfma_f32_16x16x32_bf16 v[36:39], v[150:153], v[186:189], v[36:39]
	v_mfma_f32_16x16x32_bf16 v[28:31], v[128:131], v[194:197], v[28:31]
	v_mfma_f32_16x16x32_bf16 v[20:23], v[150:153], v[194:197], v[20:23]
	v_mfma_f32_16x16x32_bf16 v[12:15], v[128:131], v[222:225], v[12:15]
	v_mfma_f32_16x16x32_bf16 v[4:7], v[150:153], v[222:225], v[4:7]
	v_mfma_f32_16x16x32_bf16 v[60:63], v[132:135], v[182:185], v[60:63]
	v_mfma_f32_16x16x32_bf16 v[52:55], v[174:177], v[182:185], v[52:55]
	v_mfma_f32_16x16x32_bf16 v[44:47], v[132:135], v[190:193], v[44:47]
	v_mfma_f32_16x16x32_bf16 v[36:39], v[174:177], v[190:193], v[36:39]
	v_mfma_f32_16x16x32_bf16 v[28:31], v[132:135], v[218:221], v[28:31]
	v_mfma_f32_16x16x32_bf16 v[20:23], v[174:177], v[218:221], v[20:23]
	v_mfma_f32_16x16x32_bf16 v[12:15], v[132:135], v[226:229], v[12:15]
	v_mfma_f32_16x16x32_bf16 v[4:7], v[174:177], v[226:229], v[4:7]
	s_barrier
	s_add_u32 s48, s22, 0x80000
	s_addc_u32 s49, s23, 0
	s_add_i32 s47, s50, s30
	s_mov_b32 m0, s47
	s_nop 0
	global_load_lds_dwordx4 v160, s[48:49]
	s_add_i32 m0, s47, 0x2000
	s_nop 0
	global_load_lds_dwordx4 v136, s[48:49]
	s_waitcnt vmcnt(6)
	s_barrier
; #define PG8_STAGE(bufoff, gbase, voff) do { _Pragma("unroll") for (int _i = 0; _i < 2; ++_i) \
;         __builtin_amdgcn_global_load_lds((const unsigned*)((const char*)(gbase) + (voff)[_i]), (LAS unsigned*)(lds + (bufoff) + ldsw + _i * 8192), 16, 0, 0); } while (0)
; #define PG8_LDA(dst, b, h) do { _Pragma("unroll") for (int m = 0; m < 4; ++m) _Pragma("unroll") for (int k = 0; k < 2; ++k) dst[m][k] = *(const LAS bf16x8*)(lds + PG8_SA(b, h) + aoff + m * 2048 + k * 1024); } while (0)
; #define PG8_LDB(dst, b, h) do { _Pragma("unroll") for (int n = 0; n < 2; ++n) _Pragma("unroll") for (int k = 0; k < 2; ++k) dst[n][k] = *(const LAS bf16x8*)(lds + PG8_SB(b, h) + boff + n * 2048 + k * 1024); } while (0)
; #define PG8_MMA(ai, bj, At, Bt) do { __builtin_amdgcn_s_setprio(1); _Pragma("unroll") for (int m = 0; m < 4; ++m) _Pragma("unroll") for (int n = 0; n < 2; ++n) _Pragma("unroll") for (int k = 0; k < 2; ++k) \
;         acc[ai][bj][m][n] = __builtin_amdgcn_mfma_f32_16x16x32_bf16(Bt[n][k], At[m][k], acc[ai][bj][m][n], 0, 0, 0); __builtin_amdgcn_s_setprio(0); } while (0)
; #define PG8_WAIT_V(n) asm volatile("s_waitcnt vmcnt(" #n ")" ::: "memory")
; #define PG8_WAIT_L(n) asm volatile("s_waitcnt lgkmcnt(" #n ")" ::: "memory")
; #define PG8_BAR __builtin_amdgcn_s_barrier()
; #define PG8_SCHED __builtin_amdgcn_sched_barrier(0)
; template <class Epi>
; DEV void gemm_phase(LAS unsigned char* lds, const Gemm g, const StaticOrder& S, const Epi& E) {
;     ...
;             PG8_WAIT_V(6); PG8_BAR; PG8_MMA(1, 1, At, B1); PG8_BAR;
;             PG8_LDB(B0, 1, 0); PG8_SCHED; PG8_LDA(At, 1, 0); PG8_STAGE(PG8_SA(0, 1), a2 + hstep, voffA);
;             PG8_WAIT_L(8); PG8_BAR; PG8_WAIT_L(0); PG8_MMA(0, 0, At, B0); PG8_BAR; PG8_SCHED;
;             PG8_LDB(B1, 1, 1); PG8_STAGE(PG8_SB(1, 0), b3, voffB);
;             PG8_BAR; PG8_WAIT_L(0); PG8_MMA(0, 1, At, B1); PG8_BAR;
;             PG8_LDA(At, 1, 1); PG8_STAGE(PG8_SA(1, 0), a3, voffA);
	v_mfma_f32_16x16x32_bf16 v[56:59], v[230:233], v[178:181], v[56:59]
	v_mfma_f32_16x16x32_bf16 v[48:51], v[238:241], v[178:181], v[48:51]
	v_mfma_f32_16x16x32_bf16 v[40:43], v[230:233], v[186:189], v[40:43]
	v_mfma_f32_16x16x32_bf16 v[32:35], v[238:241], v[186:189], v[32:35]
	v_mfma_f32_16x16x32_bf16 v[24:27], v[230:233], v[194:197], v[24:27]
	v_mfma_f32_16x16x32_bf16 v[16:19], v[238:241], v[194:197], v[16:19]
	v_mfma_f32_16x16x32_bf16 v[8:11], v[230:233], v[222:225], v[8:11]
	v_mfma_f32_16x16x32_bf16 v[0:3], v[238:241], v[222:225], v[0:3]
	v_mfma_f32_16x16x32_bf16 v[56:59], v[234:237], v[182:185], v[56:59]
	v_mfma_f32_16x16x32_bf16 v[48:51], v[242:245], v[182:185], v[48:51]
	v_mfma_f32_16x16x32_bf16 v[40:43], v[234:237], v[190:193], v[40:43]
	v_mfma_f32_16x16x32_bf16 v[32:35], v[242:245], v[190:193], v[32:35]
	v_mfma_f32_16x16x32_bf16 v[24:27], v[234:237], v[218:221], v[24:27]
	v_mfma_f32_16x16x32_bf16 v[16:19], v[242:245], v[218:221], v[16:19]
	v_mfma_f32_16x16x32_bf16 v[8:11], v[234:237], v[226:229], v[8:11]
	v_mfma_f32_16x16x32_bf16 v[0:3], v[242:245], v[226:229], v[0:3]
	s_add_i32 s47, 0, 0x18000
	v_add_u32_e32 v148, s47, v155
	s_barrier
	ds_read_b128 v[128:131], v148
	ds_read_b128 v[132:135], v148 offset:1024
	ds_read_b128 v[150:153], v148 offset:2048
	ds_read_b128 v[174:177], v148 offset:3072
	s_add_u32 s24, s24, 0x80000
	s_addc_u32 s25, s25, 0
	s_mov_b32 m0, s36
	ds_read_b128 v[178:181], v167 offset:32768
	ds_read_b128 v[182:185], v167 offset:33792
	ds_read_b128 v[186:189], v167 offset:34816
	ds_read_b128 v[190:193], v167 offset:35840
	ds_read_b128 v[194:197], v167 offset:36864
	ds_read_b128 v[218:221], v167 offset:37888
	ds_read_b128 v[222:225], v167 offset:38912
	ds_read_b128 v[226:229], v167 offset:39936
	global_load_lds_dwordx4 v140, s[24:25]
	s_mov_b32 m0, s37
	s_nop 0
	global_load_lds_dwordx4 v138, s[24:25]
	s_waitcnt lgkmcnt(8)
	s_barrier
	s_waitcnt lgkmcnt(0)
	v_mfma_f32_16x16x32_bf16 v[124:127], v[128:131], v[178:181], v[124:127]
	v_mfma_f32_16x16x32_bf16 v[116:119], v[150:153], v[178:181], v[116:119]
	v_mfma_f32_16x16x32_bf16 v[108:111], v[128:131], v[186:189], v[108:111]
	v_mfma_f32_16x16x32_bf16 v[100:103], v[150:153], v[186:189], v[100:103]
	v_mfma_f32_16x16x32_bf16 v[92:95], v[128:131], v[194:197], v[92:95]
	v_mfma_f32_16x16x32_bf16 v[84:87], v[150:153], v[194:197], v[84:87]
	v_mfma_f32_16x16x32_bf16 v[76:79], v[128:131], v[222:225], v[76:79]
	v_mfma_f32_16x16x32_bf16 v[68:71], v[150:153], v[222:225], v[68:71]
	v_mfma_f32_16x16x32_bf16 v[124:127], v[132:135], v[182:185], v[124:127]
	v_mfma_f32_16x16x32_bf16 v[116:119], v[174:177], v[182:185], v[116:119]
	v_mfma_f32_16x16x32_bf16 v[108:111], v[132:135], v[190:193], v[108:111]
	v_mfma_f32_16x16x32_bf16 v[100:103], v[174:177], v[190:193], v[100:103]
	v_mfma_f32_16x16x32_bf16 v[92:95], v[132:135], v[218:221], v[92:95]
	v_mfma_f32_16x16x32_bf16 v[84:87], v[174:177], v[218:221], v[84:87]
	v_mfma_f32_16x16x32_bf16 v[76:79], v[132:135], v[226:229], v[76:79]
	v_mfma_f32_16x16x32_bf16 v[68:71], v[174:177], v[226:229], v[68:71]
	s_barrier
	s_add_i32 s24, 0, 0x1c000
	s_add_i32 s25, s47, s30
	v_add_u32_e32 v148, s24, v155
	s_add_u32 s100, s22, 0x80
	s_addc_u32 s101, s23, 0
	s_mov_b32 m0, s25
	ds_read_b128 v[230:233], v148
	ds_read_b128 v[234:237], v148 offset:1024
	ds_read_b128 v[238:241], v148 offset:2048
	ds_read_b128 v[242:245], v148 offset:3072
	global_load_lds_dwordx4 v160, s[100:101]
	s_add_i32 m0, s25, 0x2000
	s_nop 0
	global_load_lds_dwordx4 v136, s[100:101]
	s_barrier
	s_waitcnt lgkmcnt(0)
	v_mfma_f32_16x16x32_bf16 v[120:123], v[230:233], v[178:181], v[120:123]
	v_mfma_f32_16x16x32_bf16 v[112:115], v[238:241], v[178:181], v[112:115]
	v_mfma_f32_16x16x32_bf16 v[104:107], v[230:233], v[186:189], v[104:107]
	v_mfma_f32_16x16x32_bf16 v[96:99], v[238:241], v[186:189], v[96:99]
	v_mfma_f32_16x16x32_bf16 v[88:91], v[230:233], v[194:197], v[88:91]
	v_mfma_f32_16x16x32_bf16 v[80:83], v[238:241], v[194:197], v[80:83]
	v_mfma_f32_16x16x32_bf16 v[72:75], v[230:233], v[222:225], v[72:75]
	v_mfma_f32_16x16x32_bf16 v[64:67], v[238:241], v[222:225], v[64:67]
	v_mfma_f32_16x16x32_bf16 v[120:123], v[234:237], v[182:185], v[120:123]
	v_mfma_f32_16x16x32_bf16 v[112:115], v[242:245], v[182:185], v[112:115]
	v_mfma_f32_16x16x32_bf16 v[104:107], v[234:237], v[190:193], v[104:107]
	v_mfma_f32_16x16x32_bf16 v[96:99], v[242:245], v[190:193], v[96:99]
	v_mfma_f32_16x16x32_bf16 v[88:91], v[234:237], v[218:221], v[88:91]
	v_mfma_f32_16x16x32_bf16 v[80:83], v[242:245], v[218:221], v[80:83]
	v_mfma_f32_16x16x32_bf16 v[72:75], v[234:237], v[226:229], v[72:75]
	v_mfma_f32_16x16x32_bf16 v[64:67], v[242:245], v[226:229], v[64:67]
	s_mov_b32 m0, s38
	v_lshl_add_u64 v[146:147], v[214:215], 0, s[2:3]
	s_barrier
	ds_read_b128 v[178:181], v167 offset:49152
	ds_read_b128 v[182:185], v167 offset:50176
	ds_read_b128 v[186:189], v167 offset:51200
	ds_read_b128 v[190:193], v167 offset:52224
	ds_read_b128 v[194:197], v167 offset:53248
	ds_read_b128 v[218:221], v167 offset:54272
	ds_read_b128 v[222:225], v167 offset:55296
	ds_read_b128 v[226:229], v167 offset:56320
	global_load_lds_dwordx4 v[146:147], off
	v_lshl_add_u64 v[146:147], v[216:217], 0, s[2:3]
	s_mov_b32 m0, s39
	s_nop 0
	global_load_lds_dwordx4 v[146:147], off
	s_barrier
; #define PG8_STAGE(bufoff, gbase, voff) do { _Pragma("unroll") for (int _i = 0; _i < 2; ++_i) \
;         __builtin_amdgcn_global_load_lds((const unsigned*)((const char*)(gbase) + (voff)[_i]), (LAS unsigned*)(lds + (bufoff) + ldsw + _i * 8192), 16, 0, 0); } while (0)
; #define PG8_MMA(ai, bj, At, Bt) do { __builtin_amdgcn_s_setprio(1); _Pragma("unroll") for (int m = 0; m < 4; ++m) _Pragma("unroll") for (int n = 0; n < 2; ++n) _Pragma("unroll") for (int k = 0; k < 2; ++k) \
;         acc[ai][bj][m][n] = __builtin_amdgcn_mfma_f32_16x16x32_bf16(Bt[n][k], At[m][k], acc[ai][bj][m][n], 0, 0, 0); __builtin_amdgcn_s_setprio(0); } while (0)
; #define PG8_WAIT_V(n) asm volatile("s_waitcnt vmcnt(" #n ")" ::: "memory")
; #define PG8_WAIT_L(n) asm volatile("s_waitcnt lgkmcnt(" #n ")" ::: "memory")
; #define PG8_BAR __builtin_amdgcn_s_barrier()
; #define PG8_SCHED __builtin_amdgcn_sched_barrier(0)
;     DEV void operator()(AccRef acc, const pg8::Unit& u, int wr, int wc, int fr, int fq) const { store_bf16_tile<0, false>(acc, O, ld, u.pm * 256 + wr * 64 + fr, u.pn * 256 + wc * 32 + 4 * fq, ss); }
; template <class Epi>
; DEV void gemm_phase(LAS unsigned char* lds, const Gemm g, const StaticOrder& S, const Epi& E) {
;     ...
;             PG8_BAR; PG8_WAIT_L(0); PG8_MMA(1, 0, At, B0); PG8_BAR; PG8_SCHED;
;             PG8_STAGE(PG8_SB(1, 1), b3 + hstep, voffB);
;             PG8_WAIT_V(6); PG8_BAR; PG8_MMA(1, 1, At, B1); PG8_BAR;
;         }
; DEV float rowscale(const float* ss, int row) { const f32x4 a = *(const f32x4*)(ss + (size_t)row * 8), b = *(const f32x4*)(ss + (size_t)row * 8 + 4);
;     return rsqrtf(((a[0] + a[1]) + (a[2] + a[3]) + (b[0] + b[1]) + (b[2] + b[3])) * (1.0f / 2048.0f) + EPS); }
;     DEV void operator()(AccRef acc, const pg8::Unit& u, int wr, int wc, int fr, int fq) const {
;         const int row0 = u.pm * 256 + wr * 64 + fr, col0 = u.pn * 128 + wc * 32 + 8 * fq;
;         float rsv[2][4];
; #pragma unroll
;         for (int ai = 0; ai < 2; ++ai)
; #pragma unroll
;             for (int m = 0; m < 4; ++m) rsv[ai][m] = rowscale(ss, row0 + ai * 128 + m * 16);
	s_waitcnt lgkmcnt(0)
	v_mfma_f32_16x16x32_bf16 v[60:63], v[128:131], v[178:181], v[60:63]
	v_mfma_f32_16x16x32_bf16 v[52:55], v[150:153], v[178:181], v[52:55]
	v_mfma_f32_16x16x32_bf16 v[44:47], v[128:131], v[186:189], v[44:47]
	v_mfma_f32_16x16x32_bf16 v[36:39], v[150:153], v[186:189], v[36:39]
	v_mfma_f32_16x16x32_bf16 v[28:31], v[128:131], v[194:197], v[28:31]
	v_mfma_f32_16x16x32_bf16 v[20:23], v[150:153], v[194:197], v[20:23]
	v_mfma_f32_16x16x32_bf16 v[12:15], v[128:131], v[222:225], v[12:15]
	v_mfma_f32_16x16x32_bf16 v[4:7], v[150:153], v[222:225], v[4:7]
	v_mfma_f32_16x16x32_bf16 v[60:63], v[132:135], v[182:185], v[60:63]
	v_mfma_f32_16x16x32_bf16 v[52:55], v[174:177], v[182:185], v[52:55]
	v_mfma_f32_16x16x32_bf16 v[44:47], v[132:135], v[190:193], v[44:47]
	v_mfma_f32_16x16x32_bf16 v[36:39], v[174:177], v[190:193], v[36:39]
	v_mfma_f32_16x16x32_bf16 v[28:31], v[132:135], v[218:221], v[28:31]
	v_mfma_f32_16x16x32_bf16 v[20:23], v[174:177], v[218:221], v[20:23]
	v_mfma_f32_16x16x32_bf16 v[12:15], v[132:135], v[226:229], v[12:15]
	v_mfma_f32_16x16x32_bf16 v[4:7], v[174:177], v[226:229], v[4:7]
	s_barrier
	s_add_u32 s22, s22, 0x80080
	s_addc_u32 s23, s23, 0
	s_add_i32 s24, s24, s30
	s_mov_b32 m0, s24
	s_nop 0
	global_load_lds_dwordx4 v160, s[22:23]
	s_add_i32 m0, s24, 0x2000
	s_nop 0
	global_load_lds_dwordx4 v136, s[22:23]
	s_waitcnt vmcnt(6)
	s_barrier
	v_mfma_f32_16x16x32_bf16 v[56:59], v[230:233], v[178:181], v[56:59]
	v_mfma_f32_16x16x32_bf16 v[48:51], v[238:241], v[178:181], v[48:51]
	v_mfma_f32_16x16x32_bf16 v[40:43], v[230:233], v[186:189], v[40:43]
	v_mfma_f32_16x16x32_bf16 v[32:35], v[238:241], v[186:189], v[32:35]
	v_mfma_f32_16x16x32_bf16 v[24:27], v[230:233], v[194:197], v[24:27]
	v_mfma_f32_16x16x32_bf16 v[16:19], v[238:241], v[194:197], v[16:19]
	v_mfma_f32_16x16x32_bf16 v[8:11], v[230:233], v[222:225], v[8:11]
	v_mfma_f32_16x16x32_bf16 v[0:3], v[238:241], v[222:225], v[0:3]
	v_mfma_f32_16x16x32_bf16 v[56:59], v[234:237], v[182:185], v[56:59]
	v_mfma_f32_16x16x32_bf16 v[48:51], v[242:245], v[182:185], v[48:51]
	v_mfma_f32_16x16x32_bf16 v[40:43], v[234:237], v[190:193], v[40:43]
	v_mfma_f32_16x16x32_bf16 v[32:35], v[242:245], v[190:193], v[32:35]
	v_mfma_f32_16x16x32_bf16 v[24:27], v[234:237], v[218:221], v[24:27]
	v_mfma_f32_16x16x32_bf16 v[16:19], v[242:245], v[218:221], v[16:19]
	v_mfma_f32_16x16x32_bf16 v[8:11], v[234:237], v[226:229], v[8:11]
	v_mfma_f32_16x16x32_bf16 v[0:3], v[242:245], v[226:229], v[0:3]
	s_add_i32 s46, s46, 2
	s_add_u32 s20, s20, 0x100
	s_addc_u32 s21, s21, 0
	s_add_u32 s44, s44, 0x100
	s_addc_u32 s45, s45, 0
	s_cmp_gt_u32 s46, 29
	s_barrier
	s_cbranch_scc0 .LBB0_755
	v_lshl_add_u32 v186, s4, 8, v149
	v_ashrrev_i32_e32 v187, 31, v186
	v_lshlrev_b64 v[146:147], 5, v[186:187]
	v_lshl_add_u64 v[146:147], s[8:9], 0, v[146:147]
	v_add_co_u32_e32 v158, vcc, 0x1000, v146
	global_load_dwordx4 v[218:221], v[146:147], off
	global_load_dwordx4 v[222:225], v[146:147], off offset:16
	v_addc_co_u32_e32 v159, vcc, 0, v147, vcc
	global_load_dwordx4 v[174:177], v[146:147], off offset:512
	global_load_dwordx4 v[230:233], v[146:147], off offset:528
	global_load_dwordx4 v[234:237], v[146:147], off offset:1024
	global_load_dwordx4 v[238:241], v[146:147], off offset:1040
	global_load_dwordx4 v[242:245], v[146:147], off offset:1536
	global_load_dwordx4 v[246:249], v[146:147], off offset:1552
	global_load_dwordx4 v[190:193], v[158:159], off
	global_load_dwordx4 v[194:197], v[158:159], off offset:16
	global_load_dwordx4 v[214:217], v[158:159], off offset:512
	global_load_dwordx4 v[132:135], v[158:159], off offset:528
	global_load_dwordx4 v[150:153], v[158:159], off offset:1024
	global_load_dwordx4 v[128:131], v[158:159], off offset:1040
	global_load_dwordx4 v[226:229], v[158:159], off offset:1536
	global_load_dwordx4 v[180:183], v[158:159], off offset:1552
	s_mov_b32 s12, 0x3a000000
	s_mov_b64 s[22:23], s[18:19]
	s_mov_b64 s[20:21], s[16:17]
	s_movk_i32 s11, 0x2c00
	v_readlane_b32 s4, v250, 11
	v_readlane_b32 s5, v250, 12
	s_waitcnt vmcnt(14)
	v_add_f32_e32 v218, v218, v219
	v_add_f32_e32 v220, v220, v221
	v_add_f32_e32 v222, v222, v223
	v_add_f32_e32 v224, v224, v225
	v_add_f32_e32 v218, v218, v220
	v_add_f32_e32 v218, v218, v222
	v_add_f32_e32 v218, v218, v224
	v_fmamk_f32 v218, v218, 0x3a000000, v199
	v_rsq_f32_e32 v184, v218
	s_waitcnt vmcnt(12)
	v_add_f32_e32 v174, v174, v175
	v_add_f32_e32 v176, v176, v177
	v_add_f32_e32 v230, v230, v231
	v_add_f32_e32 v232, v232, v233
	v_add_f32_e32 v174, v174, v176
	v_add_f32_e32 v174, v174, v230
	v_add_f32_e32 v174, v174, v232
	v_fmamk_f32 v174, v174, 0x3a000000, v199
	v_rsq_f32_e32 v176, v174
	v_pk_mul_f32 v[124:125], v[124:125], v[184:185] op_sel_hi:[1,0]
	v_pk_mul_f32 v[120:121], v[120:121], v[184:185] op_sel_hi:[1,0]
	v_pk_mul_f32 v[122:123], v[122:123], v[184:185] op_sel_hi:[1,0]
	v_pk_mul_f32 v[116:117], v[116:117], v[184:185] op_sel_hi:[1,0]
	v_pk_mul_f32 v[112:113], v[112:113], v[184:185] op_sel_hi:[1,0]
	v_pk_mul_f32 v[114:115], v[114:115], v[184:185] op_sel_hi:[1,0]
	s_waitcnt vmcnt(10)
	v_add_f32_e32 v234, v234, v235
	v_add_f32_e32 v236, v236, v237
	v_add_f32_e32 v238, v238, v239
	v_add_f32_e32 v240, v240, v241
	v_add_f32_e32 v234, v234, v236
	v_add_f32_e32 v234, v234, v238
	v_add_f32_e32 v234, v234, v240
	v_fmamk_f32 v234, v234, 0x3a000000, v199
	v_rsq_f32_e32 v178, v234
	v_pk_mul_f32 v[108:109], v[108:109], v[176:177] op_sel_hi:[1,0]
	v_pk_mul_f32 v[104:105], v[104:105], v[176:177] op_sel_hi:[1,0]
	v_pk_mul_f32 v[106:107], v[106:107], v[176:177] op_sel_hi:[1,0]
	v_pk_mul_f32 v[100:101], v[100:101], v[176:177] op_sel_hi:[1,0]
	v_pk_mul_f32 v[96:97], v[96:97], v[176:177] op_sel_hi:[1,0]
	v_pk_mul_f32 v[98:99], v[98:99], v[176:177] op_sel_hi:[1,0]
	s_waitcnt vmcnt(8)
; DEV bf16x8 pack8(f32x4 a, f32x4 b) { u32x4 w; w.x = cvt_pk_bf16(a[0], a[1]); w.y = cvt_pk_bf16(a[2], a[3]); w.z = cvt_pk_bf16(b[0], b[1]); w.w = cvt_pk_bf16(b[2], b[3]); return __builtin_bit_cast(bf16x8, w); }
; DEV float siluf(float x) { return x * __builtin_amdgcn_rcpf(1.0f + __builtin_amdgcn_exp2f(x * -1.4426950408889634f)); }
;     DEV void operator()(AccRef acc, const pg8::Unit& u, int wr, int wc, int fr, int fq) const {
;         const int row0 = u.pm * 256 + wr * 64 + fr, col0 = u.pn * 128 + wc * 32 + 8 * fq;
;         float rsv[2][4];
; #pragma unroll
;         for (int ai = 0; ai < 2; ++ai)
; #pragma unroll
;             for (int m = 0; m < 4; ++m) rsv[ai][m] = rowscale(ss, row0 + ai * 128 + m * 16);
; #pragma unroll
;         for (int ai = 0; ai < 2; ++ai)
; #pragma unroll
;             for (int m = 0; m < 4; ++m) { u16* rowp = O + (size_t)(row0 + ai * 128 + m * 16) * 5632 + col0; const float rs = rsv[ai][m]; f32x4 r[2];
; #pragma unroll
;                 for (int n = 0; n < 2; ++n) { const f32x4 g = acc[ai][0][m][n] * rs, uu = acc[ai][1][m][n] * rs;
; #pragma unroll
;                     for (int e = 0; e < 4; ++e) r[n][e] = siluf(g[e]) * uu[e]; }
;                 *(u32x4*)rowp = __builtin_bit_cast(u32x4, pack8(r[0], r[1])); }
	v_add_f32_e32 v242, v242, v243
	v_add_f32_e32 v244, v244, v245
	v_add_f32_e32 v246, v246, v247
	v_add_f32_e32 v248, v248, v249
	v_add_f32_e32 v242, v242, v244
	v_add_f32_e32 v242, v242, v246
	v_add_f32_e32 v242, v242, v248
	v_fmamk_f32 v242, v242, 0x3a000000, v199
	v_rsq_f32_e32 v154, v242
	v_pk_mul_f32 v[92:93], v[92:93], v[178:179] op_sel_hi:[1,0]
	v_pk_mul_f32 v[88:89], v[88:89], v[178:179] op_sel_hi:[1,0]
	v_pk_mul_f32 v[90:91], v[90:91], v[178:179] op_sel_hi:[1,0]
	v_pk_mul_f32 v[84:85], v[84:85], v[178:179] op_sel_hi:[1,0]
	v_pk_mul_f32 v[80:81], v[80:81], v[178:179] op_sel_hi:[1,0]
	v_pk_mul_f32 v[82:83], v[82:83], v[178:179] op_sel_hi:[1,0]
	s_waitcnt vmcnt(6)
	v_add_f32_e32 v190, v190, v191
	v_add_f32_e32 v192, v192, v193
	v_add_f32_e32 v194, v194, v195
	v_add_f32_e32 v196, v196, v197
	v_add_f32_e32 v190, v190, v192
	v_add_f32_e32 v190, v190, v194
	v_add_f32_e32 v190, v190, v196
	v_fmamk_f32 v190, v190, 0x3a000000, v199
	v_rsq_f32_e32 v156, v190
	v_pk_mul_f32 v[76:77], v[76:77], v[154:155] op_sel_hi:[1,0]
	v_pk_mul_f32 v[72:73], v[72:73], v[154:155] op_sel_hi:[1,0]
	v_pk_mul_f32 v[74:75], v[74:75], v[154:155] op_sel_hi:[1,0]
	v_pk_mul_f32 v[68:69], v[68:69], v[154:155] op_sel_hi:[1,0]
	v_pk_mul_f32 v[64:65], v[64:65], v[154:155] op_sel_hi:[1,0]
	v_pk_mul_f32 v[66:67], v[66:67], v[154:155] op_sel_hi:[1,0]
	s_waitcnt vmcnt(4)
	v_add_f32_e32 v214, v214, v215
	v_add_f32_e32 v216, v216, v217
	v_add_f32_e32 v132, v132, v133
	v_add_f32_e32 v134, v134, v135
	v_add_f32_e32 v214, v214, v216
	v_add_f32_e32 v214, v214, v132
	v_add_f32_e32 v214, v214, v134
	v_fmamk_f32 v214, v214, 0x3a000000, v199
	v_rsq_f32_e32 v148, v214
	v_pk_mul_f32 v[60:61], v[60:61], v[156:157] op_sel_hi:[1,0]
	v_pk_mul_f32 v[56:57], v[56:57], v[156:157] op_sel_hi:[1,0]
	v_pk_mul_f32 v[58:59], v[58:59], v[156:157] op_sel_hi:[1,0]
	v_pk_mul_f32 v[52:53], v[52:53], v[156:157] op_sel_hi:[1,0]
	v_pk_mul_f32 v[48:49], v[48:49], v[156:157] op_sel_hi:[1,0]
	v_pk_mul_f32 v[50:51], v[50:51], v[156:157] op_sel_hi:[1,0]
	s_waitcnt vmcnt(2)
	v_add_f32_e32 v150, v150, v151
	v_add_f32_e32 v152, v152, v153
	v_add_f32_e32 v128, v128, v129
	v_add_f32_e32 v130, v130, v131
	v_add_f32_e32 v150, v150, v152
	v_add_f32_e32 v150, v150, v128
	v_add_f32_e32 v150, v150, v130
	v_fmamk_f32 v150, v150, 0x3a000000, v199
	v_rsq_f32_e32 v130, v150
	v_pk_mul_f32 v[44:45], v[44:45], v[148:149] op_sel_hi:[1,0]
	v_pk_mul_f32 v[40:41], v[40:41], v[148:149] op_sel_hi:[1,0]
	v_pk_mul_f32 v[42:43], v[42:43], v[148:149] op_sel_hi:[1,0]
	v_pk_mul_f32 v[36:37], v[36:37], v[148:149] op_sel_hi:[1,0]
	v_pk_mul_f32 v[32:33], v[32:33], v[148:149] op_sel_hi:[1,0]
	v_pk_mul_f32 v[34:35], v[34:35], v[148:149] op_sel_hi:[1,0]
	s_waitcnt vmcnt(0)
	v_add_f32_e32 v226, v226, v227
	v_add_f32_e32 v228, v228, v229
	v_add_f32_e32 v180, v180, v181
	v_add_f32_e32 v182, v182, v183
	v_add_f32_e32 v226, v226, v228
	v_add_f32_e32 v226, v226, v180
	v_add_f32_e32 v226, v226, v182
	v_fmamk_f32 v226, v226, 0x3a000000, v199
	v_rsq_f32_e32 v128, v226
	v_pk_mul_f32 v[28:29], v[28:29], v[130:131] op_sel_hi:[1,0]
	v_or_b32_e32 v182, 16, v186
	v_ashrrev_i32_e32 v183, 31, v182
	v_or_b32_e32 v180, 32, v186
	v_ashrrev_i32_e32 v181, 31, v180
	v_or_b32_e32 v174, 48, v186
	v_ashrrev_i32_e32 v175, 31, v174
	v_add_u32_e32 v158, 0x80, v186
	v_ashrrev_i32_e32 v159, 31, v158
	v_add_u32_e32 v152, 0x90, v186
	v_ashrrev_i32_e32 v153, 31, v152
	v_add_u32_e32 v150, 0xa0, v186
	v_ashrrev_i32_e32 v151, 31, v150
	v_add_u32_e32 v146, 0xb0, v186
	v_ashrrev_i32_e32 v147, 31, v146
	v_lshl_or_b32 v134, s42, 7, v157
	v_ashrrev_i32_e32 v135, 31, v134
	s_mov_b32 s42, s10
	v_mul_f32_e32 v129, 0xbfb8aa3b, v124
	v_exp_f32_e32 v129, v129
	v_mov_b64_e32 v[132:133], s[4:5]
	v_mad_i64_i32 v[186:187], s[4:5], v186, s11, v[132:133]
	v_add_f32_e32 v129, 1.0, v129
	v_rcp_f32_e32 v188, v129
	v_mul_f32_e32 v129, 0xbfb8aa3b, v125
	v_exp_f32_e32 v129, v129
	v_pk_mul_f32 v[24:25], v[24:25], v[130:131] op_sel_hi:[1,0]
	v_pk_mul_f32 v[26:27], v[26:27], v[130:131] op_sel_hi:[1,0]
	v_pk_mul_f32 v[20:21], v[20:21], v[130:131] op_sel_hi:[1,0]
	v_add_f32_e32 v129, 1.0, v129
	v_rcp_f32_e32 v189, v129
	v_pk_mul_f32 v[16:17], v[16:17], v[130:131] op_sel_hi:[1,0]
	v_pk_mul_f32 v[18:19], v[18:19], v[130:131] op_sel_hi:[1,0]
	v_pk_mul_f32 v[12:13], v[12:13], v[128:129] op_sel_hi:[1,0]
	v_pk_mul_f32 v[124:125], v[124:125], v[188:189]
	v_pk_mul_f32 v[8:9], v[8:9], v[128:129] op_sel_hi:[1,0]
	v_pk_mul_f32 v[120:121], v[120:121], v[124:125]
	v_pk_mul_f32 v[124:125], v[126:127], v[184:185] op_sel_hi:[1,0]
	v_pk_mul_f32 v[10:11], v[10:11], v[128:129] op_sel_hi:[1,0]
	v_mul_f32_e32 v126, 0xbfb8aa3b, v124
	v_mul_f32_e32 v127, 0xbfb8aa3b, v125
	v_exp_f32_e32 v126, v126
	v_exp_f32_e32 v127, v127
	v_pk_mul_f32 v[4:5], v[4:5], v[128:129] op_sel_hi:[1,0]
	v_pk_mul_f32 v[0:1], v[0:1], v[128:129] op_sel_hi:[1,0]
	v_add_f32_e32 v126, 1.0, v126
	v_add_f32_e32 v127, 1.0, v127
	v_rcp_f32_e32 v126, v126
	v_rcp_f32_e32 v127, v127
	v_pk_mul_f32 v[2:3], v[2:3], v[128:129] op_sel_hi:[1,0]
	s_and_b64 vcc, exec, s[0:1]
	v_pk_mul_f32 v[124:125], v[124:125], v[126:127]
	s_nop 0
	v_pk_mul_f32 v[122:123], v[122:123], v[124:125]
	v_mul_f32_e32 v124, 0xbfb8aa3b, v116
	v_mul_f32_e32 v125, 0xbfb8aa3b, v117
	v_exp_f32_e32 v124, v124
	v_exp_f32_e32 v125, v125
	v_add_f32_e32 v124, 1.0, v124
	v_add_f32_e32 v125, 1.0, v125
	v_rcp_f32_e32 v124, v124
	v_rcp_f32_e32 v125, v125
	s_nop 0
	v_pk_mul_f32 v[116:117], v[116:117], v[124:125]
	s_nop 0
	v_pk_mul_f32 v[116:117], v[112:113], v[116:117]
	v_pk_mul_f32 v[112:113], v[118:119], v[184:185] op_sel_hi:[1,0]
	v_cvt_pk_bf16_f32 v116, v116, v117
	v_mul_f32_e32 v118, 0xbfb8aa3b, v112
; DEV bf16x8 pack8(f32x4 a, f32x4 b) { u32x4 w; w.x = cvt_pk_bf16(a[0], a[1]); w.y = cvt_pk_bf16(a[2], a[3]); w.z = cvt_pk_bf16(b[0], b[1]); w.w = cvt_pk_bf16(b[2], b[3]); return __builtin_bit_cast(bf16x8, w); }
; DEV float siluf(float x) { return x * __builtin_amdgcn_rcpf(1.0f + __builtin_amdgcn_exp2f(x * -1.4426950408889634f)); }
;     DEV void operator()(AccRef acc, const pg8::Unit& u, int wr, int wc, int fr, int fq) const {
;     ...
;             for (int m = 0; m < 4; ++m) { u16* rowp = O + (size_t)(row0 + ai * 128 + m * 16) * 5632 + col0; const float rs = rsv[ai][m]; f32x4 r[2];
; #pragma unroll
;                 for (int n = 0; n < 2; ++n) { const f32x4 g = acc[ai][0][m][n] * rs, uu = acc[ai][1][m][n] * rs;
; #pragma unroll
;                     for (int e = 0; e < 4; ++e) r[n][e] = siluf(g[e]) * uu[e]; }
;                 *(u32x4*)rowp = __builtin_bit_cast(u32x4, pack8(r[0], r[1])); }
	v_mul_f32_e32 v119, 0xbfb8aa3b, v113
	v_exp_f32_e32 v118, v118
	v_exp_f32_e32 v119, v119
	v_add_f32_e32 v118, 1.0, v118
	v_add_f32_e32 v119, 1.0, v119
	v_rcp_f32_e32 v118, v118
	v_rcp_f32_e32 v119, v119
	s_nop 0
	v_pk_mul_f32 v[112:113], v[112:113], v[118:119]
	s_nop 0
	v_pk_mul_f32 v[118:119], v[114:115], v[112:113]
	v_lshlrev_b64 v[112:113], 1, v[134:135]
	v_lshl_add_u64 v[124:125], v[186:187], 0, v[112:113]
	v_cvt_pk_bf16_f32 v114, v120, v121
	v_cvt_pk_bf16_f32 v115, v122, v123
	v_cvt_pk_bf16_f32 v117, v118, v119
	global_store_dwordx4 v[124:125], v[114:117], off
	s_nop 1
	v_mul_f32_e32 v116, 0xbfb8aa3b, v108
	v_mul_f32_e32 v117, 0xbfb8aa3b, v109
	v_exp_f32_e32 v116, v116
	v_exp_f32_e32 v117, v117
	v_mad_i64_i32 v[114:115], s[4:5], v182, s11, v[132:133]
	v_add_f32_e32 v116, 1.0, v116
	v_add_f32_e32 v117, 1.0, v117
	v_rcp_f32_e32 v116, v116
	v_rcp_f32_e32 v117, v117
	s_nop 0
	v_pk_mul_f32 v[108:109], v[108:109], v[116:117]
	s_nop 0
	v_pk_mul_f32 v[104:105], v[104:105], v[108:109]
	v_pk_mul_f32 v[108:109], v[110:111], v[176:177] op_sel_hi:[1,0]
	s_nop 0
	v_mul_f32_e32 v110, 0xbfb8aa3b, v108
	v_mul_f32_e32 v111, 0xbfb8aa3b, v109
	v_exp_f32_e32 v110, v110
	v_exp_f32_e32 v111, v111
	v_add_f32_e32 v110, 1.0, v110
	v_add_f32_e32 v111, 1.0, v111
	v_rcp_f32_e32 v110, v110
	v_rcp_f32_e32 v111, v111
	s_nop 0
	v_pk_mul_f32 v[108:109], v[108:109], v[110:111]
	s_nop 0
	v_pk_mul_f32 v[106:107], v[106:107], v[108:109]
	v_mul_f32_e32 v108, 0xbfb8aa3b, v100
	v_mul_f32_e32 v109, 0xbfb8aa3b, v101
	v_exp_f32_e32 v108, v108
	v_exp_f32_e32 v109, v109
	v_add_f32_e32 v108, 1.0, v108
	v_add_f32_e32 v109, 1.0, v109
	v_rcp_f32_e32 v108, v108
	v_rcp_f32_e32 v109, v109
	s_nop 0
	v_pk_mul_f32 v[100:101], v[100:101], v[108:109]
	s_nop 0
	v_pk_mul_f32 v[100:101], v[96:97], v[100:101]
	v_pk_mul_f32 v[96:97], v[102:103], v[176:177] op_sel_hi:[1,0]
	v_lshl_add_u64 v[108:109], v[114:115], 0, v[112:113]
	v_mul_f32_e32 v102, 0xbfb8aa3b, v96
	v_mul_f32_e32 v103, 0xbfb8aa3b, v97
	v_exp_f32_e32 v102, v102
	v_exp_f32_e32 v103, v103
	v_add_f32_e32 v102, 1.0, v102
	v_add_f32_e32 v103, 1.0, v103
	v_rcp_f32_e32 v102, v102
	v_rcp_f32_e32 v103, v103
	s_nop 0
	v_pk_mul_f32 v[96:97], v[96:97], v[102:103]
	s_nop 0
	v_pk_mul_f32 v[102:103], v[98:99], v[96:97]
	v_cvt_pk_bf16_f32 v96, v104, v105
	v_cvt_pk_bf16_f32 v97, v106, v107
	v_cvt_pk_bf16_f32 v98, v100, v101
	v_cvt_pk_bf16_f32 v99, v102, v103
	global_store_dwordx4 v[108:109], v[96:99], off
	s_nop 1
	v_mul_f32_e32 v98, 0xbfb8aa3b, v92
	v_mul_f32_e32 v99, 0xbfb8aa3b, v93
	v_exp_f32_e32 v98, v98
	v_exp_f32_e32 v99, v99
	v_mad_i64_i32 v[96:97], s[4:5], v180, s11, v[132:133]
	v_add_f32_e32 v98, 1.0, v98
	v_add_f32_e32 v99, 1.0, v99
	v_rcp_f32_e32 v98, v98
	v_rcp_f32_e32 v99, v99
	s_nop 0
	v_pk_mul_f32 v[92:93], v[92:93], v[98:99]
	s_nop 0
	v_pk_mul_f32 v[88:89], v[88:89], v[92:93]
	v_pk_mul_f32 v[92:93], v[94:95], v[178:179] op_sel_hi:[1,0]
	s_nop 0
	v_mul_f32_e32 v94, 0xbfb8aa3b, v92
	v_mul_f32_e32 v95, 0xbfb8aa3b, v93
	v_exp_f32_e32 v94, v94
	v_exp_f32_e32 v95, v95
	v_add_f32_e32 v94, 1.0, v94
	v_add_f32_e32 v95, 1.0, v95
	v_rcp_f32_e32 v94, v94
	v_rcp_f32_e32 v95, v95
	s_nop 0
	v_pk_mul_f32 v[92:93], v[92:93], v[94:95]
	s_nop 0
	v_pk_mul_f32 v[90:91], v[90:91], v[92:93]
	v_mul_f32_e32 v92, 0xbfb8aa3b, v84
	v_mul_f32_e32 v93, 0xbfb8aa3b, v85
	v_exp_f32_e32 v92, v92
	v_exp_f32_e32 v93, v93
	v_add_f32_e32 v92, 1.0, v92
	v_add_f32_e32 v93, 1.0, v93
	v_rcp_f32_e32 v92, v92
	v_rcp_f32_e32 v93, v93
	s_nop 0
	v_pk_mul_f32 v[84:85], v[84:85], v[92:93]
	s_nop 0
	v_pk_mul_f32 v[84:85], v[80:81], v[84:85]
	v_pk_mul_f32 v[80:81], v[86:87], v[178:179] op_sel_hi:[1,0]
	v_lshl_add_u64 v[92:93], v[96:97], 0, v[112:113]
	v_mul_f32_e32 v86, 0xbfb8aa3b, v80
	v_mul_f32_e32 v87, 0xbfb8aa3b, v81
	v_exp_f32_e32 v86, v86
	v_exp_f32_e32 v87, v87
	v_add_f32_e32 v86, 1.0, v86
	v_add_f32_e32 v87, 1.0, v87
	v_rcp_f32_e32 v86, v86
	v_rcp_f32_e32 v87, v87
	s_nop 0
	v_pk_mul_f32 v[80:81], v[80:81], v[86:87]
	s_nop 0
	v_pk_mul_f32 v[86:87], v[82:83], v[80:81]
	v_cvt_pk_bf16_f32 v80, v88, v89
	v_cvt_pk_bf16_f32 v81, v90, v91
	v_cvt_pk_bf16_f32 v82, v84, v85
	v_cvt_pk_bf16_f32 v83, v86, v87
	global_store_dwordx4 v[92:93], v[80:83], off
	s_nop 1
	v_mul_f32_e32 v82, 0xbfb8aa3b, v76
	v_mul_f32_e32 v83, 0xbfb8aa3b, v77
	v_exp_f32_e32 v82, v82
	v_exp_f32_e32 v83, v83
	v_mad_i64_i32 v[80:81], s[4:5], v174, s11, v[132:133]
	v_add_f32_e32 v82, 1.0, v82
	v_add_f32_e32 v83, 1.0, v83
	v_rcp_f32_e32 v82, v82
	v_rcp_f32_e32 v83, v83
	s_nop 0
	v_pk_mul_f32 v[76:77], v[76:77], v[82:83]
	s_nop 0
	v_pk_mul_f32 v[72:73], v[72:73], v[76:77]
	v_pk_mul_f32 v[76:77], v[78:79], v[154:155] op_sel_hi:[1,0]
	s_nop 0
	v_mul_f32_e32 v78, 0xbfb8aa3b, v76
	v_mul_f32_e32 v79, 0xbfb8aa3b, v77
	v_exp_f32_e32 v78, v78
	v_exp_f32_e32 v79, v79
	v_add_f32_e32 v78, 1.0, v78
	v_add_f32_e32 v79, 1.0, v79
	v_rcp_f32_e32 v78, v78
	v_rcp_f32_e32 v79, v79
	s_nop 0
	v_pk_mul_f32 v[76:77], v[76:77], v[78:79]
	s_nop 0
	v_pk_mul_f32 v[74:75], v[74:75], v[76:77]
	v_mul_f32_e32 v76, 0xbfb8aa3b, v68
	v_mul_f32_e32 v77, 0xbfb8aa3b, v69
	v_exp_f32_e32 v76, v76
	v_exp_f32_e32 v77, v77
	v_add_f32_e32 v76, 1.0, v76
	v_add_f32_e32 v77, 1.0, v77
	v_rcp_f32_e32 v76, v76
	v_rcp_f32_e32 v77, v77
	s_nop 0
	v_pk_mul_f32 v[68:69], v[68:69], v[76:77]
	s_nop 0
	v_pk_mul_f32 v[68:69], v[64:65], v[68:69]
	v_pk_mul_f32 v[64:65], v[70:71], v[154:155] op_sel_hi:[1,0]
	v_lshl_add_u64 v[76:77], v[80:81], 0, v[112:113]
	v_mul_f32_e32 v70, 0xbfb8aa3b, v64
	v_mul_f32_e32 v71, 0xbfb8aa3b, v65
	v_exp_f32_e32 v70, v70
	v_exp_f32_e32 v71, v71
	v_add_f32_e32 v70, 1.0, v70
	v_add_f32_e32 v71, 1.0, v71
	v_rcp_f32_e32 v70, v70
	v_rcp_f32_e32 v71, v71
; DEV float siluf(float x) { return x * __builtin_amdgcn_rcpf(1.0f + __builtin_amdgcn_exp2f(x * -1.4426950408889634f)); }
; DEV bf16x8 pack8(f32x4 a, f32x4 b) { u32x4 w; w.x = cvt_pk_bf16(a[0], a[1]); w.y = cvt_pk_bf16(a[2], a[3]); w.z = cvt_pk_bf16(b[0], b[1]); w.w = cvt_pk_bf16(b[2], b[3]); return __builtin_bit_cast(bf16x8, w); }
;     DEV void operator()(AccRef acc, const pg8::Unit& u, int wr, int wc, int fr, int fq) const {
;     ...
;             for (int m = 0; m < 4; ++m) { u16* rowp = O + (size_t)(row0 + ai * 128 + m * 16) * 5632 + col0; const float rs = rsv[ai][m]; f32x4 r[2];
; #pragma unroll
;                 for (int n = 0; n < 2; ++n) { const f32x4 g = acc[ai][0][m][n] * rs, uu = acc[ai][1][m][n] * rs;
; #pragma unroll
;                     for (int e = 0; e < 4; ++e) r[n][e] = siluf(g[e]) * uu[e]; }
;                 *(u32x4*)rowp = __builtin_bit_cast(u32x4, pack8(r[0], r[1])); }
	s_nop 0
	v_pk_mul_f32 v[64:65], v[64:65], v[70:71]
	s_nop 0
	v_pk_mul_f32 v[70:71], v[66:67], v[64:65]
	v_cvt_pk_bf16_f32 v64, v72, v73
	v_cvt_pk_bf16_f32 v65, v74, v75
	v_cvt_pk_bf16_f32 v66, v68, v69
	v_cvt_pk_bf16_f32 v67, v70, v71
	global_store_dwordx4 v[76:77], v[64:67], off
	s_nop 1
	v_mul_f32_e32 v66, 0xbfb8aa3b, v60
	v_mul_f32_e32 v67, 0xbfb8aa3b, v61
	v_exp_f32_e32 v66, v66
	v_exp_f32_e32 v67, v67
	v_mad_i64_i32 v[64:65], s[4:5], v158, s11, v[132:133]
	v_add_f32_e32 v66, 1.0, v66
	v_add_f32_e32 v67, 1.0, v67
	v_rcp_f32_e32 v66, v66
	v_rcp_f32_e32 v67, v67
	s_nop 0
	v_pk_mul_f32 v[60:61], v[60:61], v[66:67]
	s_nop 0
	v_pk_mul_f32 v[56:57], v[56:57], v[60:61]
	v_pk_mul_f32 v[60:61], v[62:63], v[156:157] op_sel_hi:[1,0]
	s_nop 0
	v_mul_f32_e32 v62, 0xbfb8aa3b, v60
	v_mul_f32_e32 v63, 0xbfb8aa3b, v61
	v_exp_f32_e32 v62, v62
	v_exp_f32_e32 v63, v63
	v_add_f32_e32 v62, 1.0, v62
	v_add_f32_e32 v63, 1.0, v63
	v_rcp_f32_e32 v62, v62
	v_rcp_f32_e32 v63, v63
	s_nop 0
	v_pk_mul_f32 v[60:61], v[60:61], v[62:63]
	s_nop 0
	v_pk_mul_f32 v[58:59], v[58:59], v[60:61]
	v_mul_f32_e32 v60, 0xbfb8aa3b, v52
	v_mul_f32_e32 v61, 0xbfb8aa3b, v53
	v_exp_f32_e32 v60, v60
	v_exp_f32_e32 v61, v61
	v_add_f32_e32 v60, 1.0, v60
	v_add_f32_e32 v61, 1.0, v61
	v_rcp_f32_e32 v60, v60
	v_rcp_f32_e32 v61, v61
	s_nop 0
	v_pk_mul_f32 v[52:53], v[52:53], v[60:61]
	s_nop 0
	v_pk_mul_f32 v[52:53], v[48:49], v[52:53]
	v_pk_mul_f32 v[48:49], v[54:55], v[156:157] op_sel_hi:[1,0]
	v_lshl_add_u64 v[60:61], v[64:65], 0, v[112:113]
	v_mul_f32_e32 v54, 0xbfb8aa3b, v48
	v_mul_f32_e32 v55, 0xbfb8aa3b, v49
	v_exp_f32_e32 v54, v54
	v_exp_f32_e32 v55, v55
	v_add_f32_e32 v54, 1.0, v54
	v_add_f32_e32 v55, 1.0, v55
	v_rcp_f32_e32 v54, v54
	v_rcp_f32_e32 v55, v55
	s_nop 0
	v_pk_mul_f32 v[48:49], v[48:49], v[54:55]
	s_nop 0
	v_pk_mul_f32 v[54:55], v[50:51], v[48:49]
	v_cvt_pk_bf16_f32 v48, v56, v57
	v_cvt_pk_bf16_f32 v49, v58, v59
	v_cvt_pk_bf16_f32 v50, v52, v53
	v_cvt_pk_bf16_f32 v51, v54, v55
	global_store_dwordx4 v[60:61], v[48:51], off
	s_nop 1
	v_mul_f32_e32 v50, 0xbfb8aa3b, v44
	v_mul_f32_e32 v51, 0xbfb8aa3b, v45
	v_exp_f32_e32 v50, v50
	v_exp_f32_e32 v51, v51
	v_mad_i64_i32 v[48:49], s[4:5], v152, s11, v[132:133]
	v_add_f32_e32 v50, 1.0, v50
	v_add_f32_e32 v51, 1.0, v51
	v_rcp_f32_e32 v50, v50
	v_rcp_f32_e32 v51, v51
	s_nop 0
	v_pk_mul_f32 v[44:45], v[44:45], v[50:51]
	s_nop 0
	v_pk_mul_f32 v[40:41], v[40:41], v[44:45]
	v_pk_mul_f32 v[44:45], v[46:47], v[148:149] op_sel_hi:[1,0]
	s_nop 0
	v_mul_f32_e32 v46, 0xbfb8aa3b, v44
	v_mul_f32_e32 v47, 0xbfb8aa3b, v45
	v_exp_f32_e32 v46, v46
	v_exp_f32_e32 v47, v47
	v_add_f32_e32 v46, 1.0, v46
	v_add_f32_e32 v47, 1.0, v47
	v_rcp_f32_e32 v46, v46
	v_rcp_f32_e32 v47, v47
	s_nop 0
	v_pk_mul_f32 v[44:45], v[44:45], v[46:47]
	s_nop 0
	v_pk_mul_f32 v[42:43], v[42:43], v[44:45]
	v_mul_f32_e32 v44, 0xbfb8aa3b, v36
	v_mul_f32_e32 v45, 0xbfb8aa3b, v37
	v_exp_f32_e32 v44, v44
	v_exp_f32_e32 v45, v45
	v_add_f32_e32 v44, 1.0, v44
	v_add_f32_e32 v45, 1.0, v45
	v_rcp_f32_e32 v44, v44
	v_rcp_f32_e32 v45, v45
	s_nop 0
	v_pk_mul_f32 v[36:37], v[36:37], v[44:45]
	s_nop 0
	v_pk_mul_f32 v[36:37], v[32:33], v[36:37]
	v_pk_mul_f32 v[32:33], v[38:39], v[148:149] op_sel_hi:[1,0]
	v_lshl_add_u64 v[44:45], v[48:49], 0, v[112:113]
	v_mul_f32_e32 v38, 0xbfb8aa3b, v32
	v_mul_f32_e32 v39, 0xbfb8aa3b, v33
	v_exp_f32_e32 v38, v38
	v_exp_f32_e32 v39, v39
	v_add_f32_e32 v38, 1.0, v38
	v_add_f32_e32 v39, 1.0, v39
	v_rcp_f32_e32 v38, v38
	v_rcp_f32_e32 v39, v39
	s_nop 0
	v_pk_mul_f32 v[32:33], v[32:33], v[38:39]
	s_nop 0
	v_pk_mul_f32 v[38:39], v[34:35], v[32:33]
	v_cvt_pk_bf16_f32 v32, v40, v41
	v_cvt_pk_bf16_f32 v33, v42, v43
; DEV float siluf(float x) { return x * __builtin_amdgcn_rcpf(1.0f + __builtin_amdgcn_exp2f(x * -1.4426950408889634f)); }
; DEV bf16x8 pack8(f32x4 a, f32x4 b) { u32x4 w; w.x = cvt_pk_bf16(a[0], a[1]); w.y = cvt_pk_bf16(a[2], a[3]); w.z = cvt_pk_bf16(b[0], b[1]); w.w = cvt_pk_bf16(b[2], b[3]); return __builtin_bit_cast(bf16x8, w); }
; #define PG8_WAIT_V(n) asm volatile("s_waitcnt vmcnt(" #n ")" ::: "memory")
; #define PG8_BAR __builtin_amdgcn_s_barrier()
; template <class Epi>
; DEV void gemm_phase(LAS unsigned char* lds, const Gemm g, const StaticOrder& S, const Epi& E) {
;     ...
;     PG8_WAIT_V(0);
;     if (wr == 0) PG8_BAR;
;     PG8_BAR;
;     DEV void operator()(AccRef acc, const pg8::Unit& u, int wr, int wc, int fr, int fq) const {
;     ...
;             for (int m = 0; m < 4; ++m) { u16* rowp = O + (size_t)(row0 + ai * 128 + m * 16) * 5632 + col0; const float rs = rsv[ai][m]; f32x4 r[2];
; #pragma unroll
;                 for (int n = 0; n < 2; ++n) { const f32x4 g = acc[ai][0][m][n] * rs, uu = acc[ai][1][m][n] * rs;
; #pragma unroll
;                     for (int e = 0; e < 4; ++e) r[n][e] = siluf(g[e]) * uu[e]; }
;                 *(u32x4*)rowp = __builtin_bit_cast(u32x4, pack8(r[0], r[1])); }
	v_cvt_pk_bf16_f32 v34, v36, v37
	v_cvt_pk_bf16_f32 v35, v38, v39
	global_store_dwordx4 v[44:45], v[32:35], off
	s_nop 1
	v_mul_f32_e32 v34, 0xbfb8aa3b, v28
	v_mul_f32_e32 v35, 0xbfb8aa3b, v29
	v_exp_f32_e32 v34, v34
	v_exp_f32_e32 v35, v35
	v_mad_i64_i32 v[32:33], s[4:5], v150, s11, v[132:133]
	v_add_f32_e32 v34, 1.0, v34
	v_add_f32_e32 v35, 1.0, v35
	v_rcp_f32_e32 v34, v34
	v_rcp_f32_e32 v35, v35
	s_nop 0
	v_pk_mul_f32 v[28:29], v[28:29], v[34:35]
	s_nop 0
	v_pk_mul_f32 v[24:25], v[24:25], v[28:29]
	v_pk_mul_f32 v[28:29], v[30:31], v[130:131] op_sel_hi:[1,0]
	s_nop 0
	v_mul_f32_e32 v30, 0xbfb8aa3b, v28
	v_mul_f32_e32 v31, 0xbfb8aa3b, v29
	v_exp_f32_e32 v30, v30
	v_exp_f32_e32 v31, v31
	v_add_f32_e32 v30, 1.0, v30
	v_add_f32_e32 v31, 1.0, v31
	v_rcp_f32_e32 v30, v30
	v_rcp_f32_e32 v31, v31
	s_nop 0
	v_pk_mul_f32 v[28:29], v[28:29], v[30:31]
	s_nop 0
	v_pk_mul_f32 v[26:27], v[26:27], v[28:29]
	v_mul_f32_e32 v28, 0xbfb8aa3b, v20
	v_mul_f32_e32 v29, 0xbfb8aa3b, v21
	v_exp_f32_e32 v28, v28
	v_exp_f32_e32 v29, v29
	v_add_f32_e32 v28, 1.0, v28
	v_add_f32_e32 v29, 1.0, v29
	v_rcp_f32_e32 v28, v28
	v_rcp_f32_e32 v29, v29
	s_nop 0
	v_pk_mul_f32 v[20:21], v[20:21], v[28:29]
	s_nop 0
	v_pk_mul_f32 v[20:21], v[16:17], v[20:21]
	v_pk_mul_f32 v[16:17], v[22:23], v[130:131] op_sel_hi:[1,0]
	v_lshl_add_u64 v[28:29], v[32:33], 0, v[112:113]
	v_mul_f32_e32 v22, 0xbfb8aa3b, v16
	v_mul_f32_e32 v23, 0xbfb8aa3b, v17
	v_exp_f32_e32 v22, v22
	v_exp_f32_e32 v23, v23
	v_add_f32_e32 v22, 1.0, v22
	v_add_f32_e32 v23, 1.0, v23
	v_rcp_f32_e32 v22, v22
	v_rcp_f32_e32 v23, v23
	s_nop 0
	v_pk_mul_f32 v[16:17], v[16:17], v[22:23]
	s_nop 0
	v_pk_mul_f32 v[22:23], v[18:19], v[16:17]
	v_cvt_pk_bf16_f32 v16, v24, v25
	v_cvt_pk_bf16_f32 v17, v26, v27
	v_cvt_pk_bf16_f32 v18, v20, v21
	v_cvt_pk_bf16_f32 v19, v22, v23
	global_store_dwordx4 v[28:29], v[16:19], off
	s_nop 1
	v_mul_f32_e32 v18, 0xbfb8aa3b, v12
	v_mul_f32_e32 v19, 0xbfb8aa3b, v13
	v_exp_f32_e32 v18, v18
	v_exp_f32_e32 v19, v19
	v_mad_i64_i32 v[16:17], s[4:5], v146, s11, v[132:133]
	v_add_f32_e32 v18, 1.0, v18
	v_add_f32_e32 v19, 1.0, v19
	v_rcp_f32_e32 v18, v18
	v_rcp_f32_e32 v19, v19
	s_mov_b32 s4, s14
	v_pk_mul_f32 v[12:13], v[12:13], v[18:19]
	s_nop 0
	v_pk_mul_f32 v[8:9], v[8:9], v[12:13]
	v_pk_mul_f32 v[12:13], v[14:15], v[128:129] op_sel_hi:[1,0]
	s_nop 0
	v_mul_f32_e32 v14, 0xbfb8aa3b, v12
	v_mul_f32_e32 v15, 0xbfb8aa3b, v13
	v_exp_f32_e32 v14, v14
	v_exp_f32_e32 v15, v15
	v_add_f32_e32 v14, 1.0, v14
	v_add_f32_e32 v15, 1.0, v15
	v_rcp_f32_e32 v14, v14
	v_rcp_f32_e32 v15, v15
	s_nop 0
	v_pk_mul_f32 v[12:13], v[12:13], v[14:15]
	s_nop 0
	v_pk_mul_f32 v[10:11], v[10:11], v[12:13]
	v_mul_f32_e32 v12, 0xbfb8aa3b, v4
	v_mul_f32_e32 v13, 0xbfb8aa3b, v5
	v_exp_f32_e32 v12, v12
	v_exp_f32_e32 v13, v13
	v_add_f32_e32 v12, 1.0, v12
	v_add_f32_e32 v13, 1.0, v13
	v_rcp_f32_e32 v12, v12
	v_rcp_f32_e32 v13, v13
	s_nop 0
	v_pk_mul_f32 v[4:5], v[4:5], v[12:13]
	s_nop 0
	v_pk_mul_f32 v[4:5], v[0:1], v[4:5]
	v_pk_mul_f32 v[0:1], v[6:7], v[128:129] op_sel_hi:[1,0]
	v_lshl_add_u64 v[12:13], v[16:17], 0, v[112:113]
	v_mul_f32_e32 v6, 0xbfb8aa3b, v0
	v_mul_f32_e32 v7, 0xbfb8aa3b, v1
	v_exp_f32_e32 v6, v6
	v_exp_f32_e32 v7, v7
	v_add_f32_e32 v6, 1.0, v6
	v_add_f32_e32 v7, 1.0, v7
	v_rcp_f32_e32 v6, v6
	v_rcp_f32_e32 v7, v7
	s_nop 0
	v_pk_mul_f32 v[0:1], v[0:1], v[6:7]
	s_nop 0
	v_pk_mul_f32 v[6:7], v[2:3], v[0:1]
	v_cvt_pk_bf16_f32 v0, v8, v9
	v_cvt_pk_bf16_f32 v1, v10, v11
	v_cvt_pk_bf16_f32 v2, v4, v5
	v_cvt_pk_bf16_f32 v3, v6, v7
	global_store_dwordx4 v[12:13], v[0:3], off
	s_cbranch_vccz .LBB0_752
	s_waitcnt vmcnt(0)
	s_cmpk_gt_u32 s27, 0xff
	s_cbranch_scc1 .LBB0_759
	s_barrier
